# lever 4: one static s_setprio 1 for waves 4-7 over each GEMM phase, hipcc per-MFMA-block priority flips removed (5 main GEMM instances)
# speedup vs baseline: 1.0092x; 1.0040x over previous
;     __device__ bool next(int i, Unit& u) const { const int idx = i * G + c; if (idx >= 64) return false; u.kp = idx & 3; u.pn = (idx >> 2) & 7; u.pm = 192 + (idx >> 5); return true; }
; #define PG8_STAGE(bufoff, gbase, voff) do { _Pragma("unroll") for (int _i = 0; _i < 2; ++_i) \
;         __builtin_amdgcn_global_load_lds((const unsigned*)((const char*)(gbase) + (voff)[_i]), (LAS unsigned*)(lds + (bufoff) + ldsw + _i * 8192), 16, 0, 0); } while (0)
; #define PG8_WAIT_V(n) asm volatile("s_waitcnt vmcnt(" #n ")" ::: "memory")
; #define PG8_BAR __builtin_amdgcn_s_barrier()
; template <class Epi, class Sched = StaticOrder, bool ALIGN_EPI = true>
; __device__ __forceinline__ void gemm_phase(LAS unsigned char* lds, const Gemm g, const Sched& S, const Epi& E) {
;     ...
;     for (int i = 0; i < 2; ++i) { int R, C; stage_rc(tid * 16 + i * 8192, R, C); const int Rb = Epi::PERM ? ((R & ~31) + perm32(R & 31)) : R;
;         voffA[i] = (unsigned)(R * g.ld + C) * 2u; voffB[i] = (unsigned)(Rb * g.ld + C) * 2u; }
;     const size_t kstep = (size_t)(BK * 2);
;     const size_t hstep = (size_t)HALF * g.ld * 2;
;     const size_t tstep = 2 * hstep;
;     const unsigned ldsw = (unsigned)wid * 1024u;
;     const int aoff = lds_byte(wr * 64 + fr, fq * 8), boff = lds_byte(wc * 32 + fr, fq * 8);
;     ...
;     Unit cur, nxt; int ui = 0;
;     if (!S.next(0, cur)) return;
;     f32x4 acc[2][2][4][2];
; #pragma unroll
;     for (int a = 0; a < 2; ++a)
; #pragma unroll
;         for (int b = 0; b < 2; ++b)
; #pragma unroll
;             for (int m = 0; m < 4; ++m)
; #pragma unroll
;                 for (int n = 0; n < 2; ++n) acc[a][b][m][n] = (f32x4){0.f, 0.f, 0.f, 0.f};
;     bf16x8 At[4][2], B0[2][2], B1[2][2];
;     const char* cA = (const char*)g.A + (size_t)cur.pm * tstep + (size_t)cur.kp * K * 2; const char* cB = (const char*)g.Bt + (size_t)cur.pn * tstep + (size_t)cur.kp * K * 2;
;     PG8_STAGE(PG8_SB(0, 0), cB, voffB); PG8_STAGE(PG8_SB(0, 1), cB + hstep, voffB); PG8_STAGE(PG8_SA(0, 0), cA, voffA); PG8_STAGE(PG8_SA(0, 1), cA + hstep, voffA);
;     if (wr == 1) PG8_BAR;
;     PG8_WAIT_V(2); PG8_BAR;
;     PG8_STAGE(PG8_SB(1, 0), cB + kstep, voffB); PG8_STAGE(PG8_SA(1, 0), cA + kstep, voffA); PG8_STAGE(PG8_SB(1, 1), cB + hstep + kstep, voffB);
;     PG8_WAIT_V(6); PG8_BAR;
.LBB0_100:
	v_lshrrev_b32_e32 v18, 1, v16
	v_and_b32_e32 v18, 24, v18
	v_and_b32_e32 v17, 15, v16
	v_lshlrev_b32_e32 v19, 1, v18
	v_lshlrev_b32_e32 v16, 2, v16
	s_sext_i32_i8 s23, s0
	v_lshl_or_b32 v1, s12, 6, v17
	v_lshl_or_b32 v17, v17, 6, v19
	s_lshl_b32 s0, s12, 13
	v_and_b32_e32 v16, 32, v16
	v_bitop3_b32 v19, v17, s0, v16 bitop3:0xde
	s_lshl_b32 s0, s11, 5
	s_and_b32 s0, s0, 0x60
	s_lshl_b32 s11, s0, 7
	s_add_i32 m0, s7, 0x18000
	v_lshl_add_u64 v[8:9], v[8:9], 0, s[34:35]
	v_bitop3_b32 v144, v17, s11, v16 bitop3:0xde
	s_waitcnt vmcnt(2)
	s_barrier
	global_load_lds_dwordx4 v[8:9], off
	v_lshl_add_u64 v[6:7], v[6:7], 0, s[34:35]
	s_add_i32 m0, s7, 0x1a000
	s_add_i32 s11, s7, 0x8000
	s_add_i32 s18, s7, 0xa000
	global_load_lds_dwordx4 v[6:7], off
	v_lshl_add_u64 v[2:3], v[2:3], 0, s[34:35]
	s_mov_b32 m0, s11
	s_add_u32 s12, s46, 0x80080
	global_load_lds_dwordx4 v[2:3], off
	v_lshl_add_u64 v[2:3], v[4:5], 0, s[34:35]
	s_mov_b32 m0, s18
	s_addc_u32 s13, s47, 0
	global_load_lds_dwordx4 v[2:3], off
	s_add_i32 m0, s7, 0x1c000
	v_lshl_add_u64 v[2:3], s[12:13], 0, v[134:135]
	global_load_lds_dwordx4 v[2:3], off
	v_lshl_add_u64 v[2:3], s[12:13], 0, v[130:131]
	s_add_i32 m0, s7, 0x1e000
	s_cmpk_lt_u32 s1, 0x100
	global_load_lds_dwordx4 v[2:3], off
	v_lshlrev_b32_e32 v2, 15, v14
	v_and_b32_e32 v2, 0xffff0000, v2
	v_lshl_add_u32 v2, v13, 12, v2
	v_and_b32_e32 v3, 1, v14
	v_lshl_or_b32 v2, v3, 6, v2
	v_lshl_add_u32 v138, v15, 1, v2
	v_lshlrev_b32_e32 v2, 15, v10
	v_and_b32_e32 v2, 0xffff0000, v2
	s_waitcnt vmcnt(6)
	v_lshl_add_u32 v2, v11, 12, v2
	v_and_b32_e32 v3, 1, v10
	v_lshl_or_b32 v2, v3, 6, v2
	s_cselect_b64 s[12:13], -1, 0
	v_or_b32_e32 v145, s0, v18
	v_mov_b32_e32 v139, v0
	v_lshl_add_u32 v140, v12, 1, v2
	v_mov_b32_e32 v141, v0
	s_mov_b32 s22, 0
	v_add_u32_e32 v146, 0, v19
	s_barrier
	s_cmp_eq_u64 s[2:3], 0
	s_cbranch_scc1 .Lmy_pr_103
	s_setprio 1
.Lmy_pr_103:
	s_branch .LBB0_103
.LBB0_101:
	s_mov_b64 s[30:31], 0

; #define PG8_STAGE(bufoff, gbase, voff) do { _Pragma("unroll") for (int _i = 0; _i < 2; ++_i) \
;         __builtin_amdgcn_global_load_lds((const unsigned*)((const char*)(gbase) + (voff)[_i]), (LAS unsigned*)(lds + (bufoff) + ldsw + _i * 8192), 16, 0, 0); } while (0)
; #define PG8_LDA(dst, b, h) do { _Pragma("unroll") for (int m = 0; m < 4; ++m) _Pragma("unroll") for (int k = 0; k < 2; ++k) dst[m][k] = *(const LAS bf16x8*)(lds + PG8_SA(b, h) + aoff + m * 2048 + k * 1024); } while (0)
; #define PG8_LDB(dst, b, h) do { _Pragma("unroll") for (int n = 0; n < 2; ++n) _Pragma("unroll") for (int k = 0; k < 2; ++k) dst[n][k] = *(const LAS bf16x8*)(lds + PG8_SB(b, h) + boff + n * 2048 + k * 1024); } while (0)
; #define PG8_MMA(ai, bj, At, Bt) do { __builtin_amdgcn_s_setprio(1); _Pragma("unroll") for (int m = 0; m < 4; ++m) _Pragma("unroll") for (int n = 0; n < 2; ++n) _Pragma("unroll") for (int k = 0; k < 2; ++k) \
;         acc[ai][bj][m][n] = __builtin_amdgcn_mfma_f32_16x16x32_bf16(Bt[n][k], At[m][k], acc[ai][bj][m][n], 0, 0, 0); __builtin_amdgcn_s_setprio(0); } while (0)
; #define PG8_WAIT_V(n) asm volatile("s_waitcnt vmcnt(" #n ")" ::: "memory")
; #define PG8_WAIT_L(n) asm volatile("s_waitcnt lgkmcnt(" #n ")" ::: "memory")
; #define PG8_BAR __builtin_amdgcn_s_barrier()
; #define PG8_SCHED __builtin_amdgcn_sched_barrier(0)
; template <class Epi, class Sched = StaticOrder, bool ALIGN_EPI = true>
; __device__ __forceinline__ void gemm_phase(LAS unsigned char* lds, const Gemm g, const Sched& S, const Epi& E) {
;     ...
;             PG8_LDB(B0, 0, 0); PG8_LDB(B1, 0, 1); PG8_SCHED; PG8_LDA(At, 0, 0); PG8_STAGE(PG8_SA(1, 1), a1 + hstep, voffA);
;             PG8_WAIT_V(8); PG8_WAIT_L(0); PG8_BAR; PG8_MMA(0, 0, At, B0); PG8_MMA(0, 1, At, B1); PG8_BAR; PG8_SCHED;
;             PG8_LDA(At, 0, 1); PG8_STAGE(PG8_SB(0, 0), b2, voffB); PG8_STAGE(PG8_SB(0, 1), b2 + hstep, voffB); PG8_STAGE(PG8_SA(0, 0), a2, voffA);
.Lmy_nb_106:
	s_add_u32 s16, s80, 0xfff80080
	s_addc_u32 s17, s81, -1
	s_add_i32 s33, 0, 0x10000
	s_cmp_eq_u32 s49, 28
	s_cselect_b32 vcc_hi, s30, s17
	s_cselect_b32 vcc_lo, s31, s16
	v_add_u32_e32 v142, s33, v144
	s_cselect_b32 s47, s21, s43
	s_cselect_b32 s46, s36, s37
	s_add_i32 s70, 0, 0x14000
	ds_read_b128 v[148:151], v142
	ds_read_b128 v[160:163], v142 offset:1024
	ds_read_b128 v[164:167], v142 offset:2048
	ds_read_b128 v[168:171], v142 offset:3072
	v_add_u32_e32 v142, s70, v144
	ds_read_b128 v[172:175], v142
	ds_read_b128 v[176:179], v142 offset:1024
	ds_read_b128 v[180:183], v142 offset:2048
	ds_read_b128 v[184:187], v142 offset:3072
	v_lshl_add_u64 v[142:143], s[80:81], 0, v[138:139]
	s_add_i32 m0, s7, 0xc000
	ds_read_b128 v[188:191], v146
	ds_read_b128 v[192:195], v146 offset:1024
	ds_read_b128 v[210:213], v146 offset:2048
	ds_read_b128 v[214:217], v146 offset:3072
	ds_read_b128 v[218:221], v146 offset:4096
	ds_read_b128 v[222:225], v146 offset:5120
	ds_read_b128 v[226:229], v146 offset:6144
	ds_read_b128 v[230:233], v146 offset:7168
	global_load_lds_dwordx4 v[142:143], off
	v_lshl_add_u64 v[142:143], s[80:81], 0, v[140:141]
	s_add_i32 m0, s7, 0xe000
	s_nop 0
	global_load_lds_dwordx4 v[142:143], off
	s_waitcnt vmcnt(8)
	s_waitcnt lgkmcnt(0)
	s_barrier
	s_waitcnt lgkmcnt(0)
	v_mfma_f32_16x16x32_bf16 v[126:129], v[148:151], v[188:191], 0
	v_mfma_f32_16x16x32_bf16 v[122:125], v[164:167], v[188:191], 0
	v_mfma_f32_16x16x32_bf16 v[118:121], v[148:151], v[210:213], 0
	v_mfma_f32_16x16x32_bf16 v[110:113], v[164:167], v[210:213], 0
	v_mfma_f32_16x16x32_bf16 v[102:105], v[148:151], v[218:221], 0
	v_mfma_f32_16x16x32_bf16 v[94:97], v[164:167], v[218:221], 0
	v_mfma_f32_16x16x32_bf16 v[82:85], v[148:151], v[226:229], 0
	v_mfma_f32_16x16x32_bf16 v[74:77], v[164:167], v[226:229], 0
	v_mfma_f32_16x16x32_bf16 v[126:129], v[160:163], v[192:195], v[126:129]
	v_mfma_f32_16x16x32_bf16 v[122:125], v[168:171], v[192:195], v[122:125]
	v_mfma_f32_16x16x32_bf16 v[118:121], v[160:163], v[214:217], v[118:121]
	v_mfma_f32_16x16x32_bf16 v[110:113], v[168:171], v[214:217], v[110:113]
	v_mfma_f32_16x16x32_bf16 v[102:105], v[160:163], v[222:225], v[102:105]
	v_mfma_f32_16x16x32_bf16 v[94:97], v[168:171], v[222:225], v[94:97]
	v_mfma_f32_16x16x32_bf16 v[82:85], v[160:163], v[230:233], v[82:85]
	v_mfma_f32_16x16x32_bf16 v[74:77], v[168:171], v[230:233], v[74:77]
	v_mfma_f32_16x16x32_bf16 v[114:117], v[172:175], v[188:191], 0
	v_mfma_f32_16x16x32_bf16 v[106:109], v[180:183], v[188:191], 0
	v_mfma_f32_16x16x32_bf16 v[98:101], v[172:175], v[210:213], 0
	v_mfma_f32_16x16x32_bf16 v[90:93], v[180:183], v[210:213], 0
	v_mfma_f32_16x16x32_bf16 v[86:89], v[172:175], v[218:221], 0
	v_mfma_f32_16x16x32_bf16 v[78:81], v[180:183], v[218:221], 0
	v_mfma_f32_16x16x32_bf16 v[70:73], v[172:175], v[226:229], 0
	v_mfma_f32_16x16x32_bf16 v[66:69], v[180:183], v[226:229], 0
	v_mfma_f32_16x16x32_bf16 v[114:117], v[176:179], v[192:195], v[114:117]
	v_mfma_f32_16x16x32_bf16 v[106:109], v[184:187], v[192:195], v[106:109]
	v_mfma_f32_16x16x32_bf16 v[98:101], v[176:179], v[214:217], v[98:101]
	v_mfma_f32_16x16x32_bf16 v[90:93], v[184:187], v[214:217], v[90:93]
	v_mfma_f32_16x16x32_bf16 v[86:89], v[176:179], v[222:225], v[86:89]
	v_mfma_f32_16x16x32_bf16 v[78:81], v[184:187], v[222:225], v[78:81]
	v_mfma_f32_16x16x32_bf16 v[70:73], v[176:179], v[230:233], v[70:73]
	v_mfma_f32_16x16x32_bf16 v[66:69], v[184:187], v[230:233], v[66:69]
	s_barrier
	s_add_i32 s16, s33, s5
	v_lshl_add_u64 v[142:143], s[46:47], 0, v[134:135]
	s_mov_b32 m0, s16
	ds_read_b128 v[188:191], v146 offset:16384
	ds_read_b128 v[192:195], v146 offset:17408
	ds_read_b128 v[210:213], v146 offset:18432
	ds_read_b128 v[214:217], v146 offset:19456
	ds_read_b128 v[218:221], v146 offset:20480
	ds_read_b128 v[222:225], v146 offset:21504
	ds_read_b128 v[226:229], v146 offset:22528
	ds_read_b128 v[230:233], v146 offset:23552
	global_load_lds_dwordx4 v[142:143], off
	s_add_i32 m0, s16, 0x2000
	s_add_u32 s16, s46, 0x80000
	v_lshl_add_u64 v[152:153], s[46:47], 0, v[130:131]
	s_addc_u32 s17, s47, 0
	s_add_i32 s33, s70, s5
	global_load_lds_dwordx4 v[152:153], off
	v_lshl_add_u64 v[196:197], s[16:17], 0, v[134:135]
	s_mov_b32 m0, s33
	v_lshl_add_u64 v[234:235], vcc, 0, v[132:133]
	global_load_lds_dwordx4 v[196:197], off
	v_lshl_add_u64 v[196:197], s[16:17], 0, v[130:131]
	s_add_i32 m0, s33, 0x2000
	s_nop 0
	global_load_lds_dwordx4 v[196:197], off
	v_lshl_add_u64 v[196:197], vcc, 0, v[136:137]
	s_mov_b32 m0, s7
	s_nop 0
	global_load_lds_dwordx4 v[196:197], off
	s_mov_b32 m0, s8
	s_nop 0
	global_load_lds_dwordx4 v[234:235], off
	s_waitcnt vmcnt(8)
	s_waitcnt lgkmcnt(0)
	s_barrier
; #define PG8_STAGE(bufoff, gbase, voff) do { _Pragma("unroll") for (int _i = 0; _i < 2; ++_i) \
;         __builtin_amdgcn_global_load_lds((const unsigned*)((const char*)(gbase) + (voff)[_i]), (LAS unsigned*)(lds + (bufoff) + ldsw + _i * 8192), 16, 0, 0); } while (0)
; #define PG8_LDA(dst, b, h) do { _Pragma("unroll") for (int m = 0; m < 4; ++m) _Pragma("unroll") for (int k = 0; k < 2; ++k) dst[m][k] = *(const LAS bf16x8*)(lds + PG8_SA(b, h) + aoff + m * 2048 + k * 1024); } while (0)
; #define PG8_LDB(dst, b, h) do { _Pragma("unroll") for (int n = 0; n < 2; ++n) _Pragma("unroll") for (int k = 0; k < 2; ++k) dst[n][k] = *(const LAS bf16x8*)(lds + PG8_SB(b, h) + boff + n * 2048 + k * 1024); } while (0)
; #define PG8_MMA(ai, bj, At, Bt) do { __builtin_amdgcn_s_setprio(1); _Pragma("unroll") for (int m = 0; m < 4; ++m) _Pragma("unroll") for (int n = 0; n < 2; ++n) _Pragma("unroll") for (int k = 0; k < 2; ++k) \
;         acc[ai][bj][m][n] = __builtin_amdgcn_mfma_f32_16x16x32_bf16(Bt[n][k], At[m][k], acc[ai][bj][m][n], 0, 0, 0); __builtin_amdgcn_s_setprio(0); } while (0)
; #define PG8_WAIT_V(n) asm volatile("s_waitcnt vmcnt(" #n ")" ::: "memory")
; #define PG8_WAIT_L(n) asm volatile("s_waitcnt lgkmcnt(" #n ")" ::: "memory")
; #define PG8_BAR __builtin_amdgcn_s_barrier()
; #define PG8_SCHED __builtin_amdgcn_sched_barrier(0)
; template <class Epi, class Sched = StaticOrder, bool ALIGN_EPI = true>
; __device__ __forceinline__ void gemm_phase(LAS unsigned char* lds, const Gemm g, const Sched& S, const Epi& E) {
;     ...
;             PG8_WAIT_V(8); PG8_WAIT_L(0); PG8_BAR; PG8_MMA(1, 0, At, B0); PG8_MMA(1, 1, At, B1); PG8_BAR; PG8_SCHED;
;             PG8_LDB(B0, 1, 0); PG8_LDB(B1, 1, 1); PG8_SCHED; PG8_LDA(At, 1, 0); PG8_STAGE(PG8_SA(0, 1), a2 + hstep, voffA);
;             PG8_WAIT_V(8); PG8_WAIT_L(0); PG8_BAR; PG8_MMA(0, 0, At, B0); PG8_MMA(0, 1, At, B1); PG8_BAR; PG8_SCHED;
	s_waitcnt lgkmcnt(0)
	v_mfma_f32_16x16x32_bf16 v[62:65], v[148:151], v[188:191], 0
	v_mfma_f32_16x16x32_bf16 v[58:61], v[164:167], v[188:191], 0
	v_mfma_f32_16x16x32_bf16 v[54:57], v[148:151], v[210:213], 0
	v_mfma_f32_16x16x32_bf16 v[46:49], v[164:167], v[210:213], 0
	v_mfma_f32_16x16x32_bf16 v[38:41], v[148:151], v[218:221], 0
	v_mfma_f32_16x16x32_bf16 v[30:33], v[164:167], v[218:221], 0
	v_mfma_f32_16x16x32_bf16 v[22:25], v[148:151], v[226:229], 0
	v_mfma_f32_16x16x32_bf16 v[14:17], v[164:167], v[226:229], 0
	v_mfma_f32_16x16x32_bf16 v[62:65], v[160:163], v[192:195], v[62:65]
	v_mfma_f32_16x16x32_bf16 v[58:61], v[168:171], v[192:195], v[58:61]
	v_mfma_f32_16x16x32_bf16 v[54:57], v[160:163], v[214:217], v[54:57]
	v_mfma_f32_16x16x32_bf16 v[46:49], v[168:171], v[214:217], v[46:49]
	v_mfma_f32_16x16x32_bf16 v[38:41], v[160:163], v[222:225], v[38:41]
	v_mfma_f32_16x16x32_bf16 v[30:33], v[168:171], v[222:225], v[30:33]
	v_mfma_f32_16x16x32_bf16 v[22:25], v[160:163], v[230:233], v[22:25]
	v_mfma_f32_16x16x32_bf16 v[14:17], v[168:171], v[230:233], v[14:17]
	v_mfma_f32_16x16x32_bf16 v[50:53], v[172:175], v[188:191], 0
	v_mfma_f32_16x16x32_bf16 v[42:45], v[180:183], v[188:191], 0
	v_mfma_f32_16x16x32_bf16 v[34:37], v[172:175], v[210:213], 0
	v_mfma_f32_16x16x32_bf16 v[26:29], v[180:183], v[210:213], 0
	v_mfma_f32_16x16x32_bf16 v[18:21], v[172:175], v[218:221], 0
	v_mfma_f32_16x16x32_bf16 v[10:13], v[180:183], v[218:221], 0
	v_mfma_f32_16x16x32_bf16 v[6:9], v[172:175], v[226:229], 0
	v_mfma_f32_16x16x32_bf16 v[2:5], v[180:183], v[226:229], 0
	v_mfma_f32_16x16x32_bf16 v[50:53], v[176:179], v[192:195], v[50:53]
	v_mfma_f32_16x16x32_bf16 v[42:45], v[184:187], v[192:195], v[42:45]
	v_mfma_f32_16x16x32_bf16 v[34:37], v[176:179], v[214:217], v[34:37]
	v_mfma_f32_16x16x32_bf16 v[26:29], v[184:187], v[214:217], v[26:29]
	v_mfma_f32_16x16x32_bf16 v[18:21], v[176:179], v[222:225], v[18:21]
	v_mfma_f32_16x16x32_bf16 v[10:13], v[184:187], v[222:225], v[10:13]
	v_mfma_f32_16x16x32_bf16 v[6:9], v[176:179], v[230:233], v[6:9]
	v_mfma_f32_16x16x32_bf16 v[2:5], v[184:187], v[230:233], v[2:5]
	s_barrier
	s_add_i32 s33, 0, 0x18000
	v_add_u32_e32 v147, s33, v144
	s_add_i32 s70, 0, 0x1c000
	ds_read_b128 v[148:151], v147
	ds_read_b128 v[160:163], v147 offset:1024
	ds_read_b128 v[164:167], v147 offset:2048
	ds_read_b128 v[168:171], v147 offset:3072
	v_add_u32_e32 v147, s70, v144
	ds_read_b128 v[172:175], v147
	ds_read_b128 v[176:179], v147 offset:1024
	ds_read_b128 v[180:183], v147 offset:2048
	ds_read_b128 v[184:187], v147 offset:3072
	s_add_u32 s16, vcc_lo, 0x80000
	s_addc_u32 s17, vcc_hi, 0
	s_mov_b32 m0, s9
	v_lshl_add_u64 v[236:237], s[16:17], 0, v[136:137]
	ds_read_b128 v[188:191], v146 offset:32768
	ds_read_b128 v[192:195], v146 offset:33792
	ds_read_b128 v[210:213], v146 offset:34816
	ds_read_b128 v[214:217], v146 offset:35840
	ds_read_b128 v[218:221], v146 offset:36864
	ds_read_b128 v[222:225], v146 offset:37888
	ds_read_b128 v[226:229], v146 offset:38912
	ds_read_b128 v[230:233], v146 offset:39936
	global_load_lds_dwordx4 v[236:237], off
	v_lshl_add_u64 v[236:237], s[16:17], 0, v[132:133]
	s_mov_b32 m0, s10
	s_nop 0
	global_load_lds_dwordx4 v[236:237], off
	s_waitcnt vmcnt(8)
	s_waitcnt lgkmcnt(0)
	s_barrier
	s_waitcnt lgkmcnt(0)
	v_mfma_f32_16x16x32_bf16 v[126:129], v[148:151], v[188:191], v[126:129]
	v_mfma_f32_16x16x32_bf16 v[122:125], v[164:167], v[188:191], v[122:125]
	v_mfma_f32_16x16x32_bf16 v[118:121], v[148:151], v[210:213], v[118:121]
	v_mfma_f32_16x16x32_bf16 v[110:113], v[164:167], v[210:213], v[110:113]
	v_mfma_f32_16x16x32_bf16 v[102:105], v[148:151], v[218:221], v[102:105]
	v_mfma_f32_16x16x32_bf16 v[94:97], v[164:167], v[218:221], v[94:97]
	v_mfma_f32_16x16x32_bf16 v[82:85], v[148:151], v[226:229], v[82:85]
	v_mfma_f32_16x16x32_bf16 v[74:77], v[164:167], v[226:229], v[74:77]
	v_mfma_f32_16x16x32_bf16 v[126:129], v[160:163], v[192:195], v[126:129]
	v_mfma_f32_16x16x32_bf16 v[122:125], v[168:171], v[192:195], v[122:125]
	v_mfma_f32_16x16x32_bf16 v[118:121], v[160:163], v[214:217], v[118:121]
	v_mfma_f32_16x16x32_bf16 v[110:113], v[168:171], v[214:217], v[110:113]
	v_mfma_f32_16x16x32_bf16 v[102:105], v[160:163], v[222:225], v[102:105]
	v_mfma_f32_16x16x32_bf16 v[94:97], v[168:171], v[222:225], v[94:97]
	v_mfma_f32_16x16x32_bf16 v[82:85], v[160:163], v[230:233], v[82:85]
	v_mfma_f32_16x16x32_bf16 v[74:77], v[168:171], v[230:233], v[74:77]
	v_mfma_f32_16x16x32_bf16 v[114:117], v[172:175], v[188:191], v[114:117]
	v_mfma_f32_16x16x32_bf16 v[106:109], v[180:183], v[188:191], v[106:109]
	v_mfma_f32_16x16x32_bf16 v[98:101], v[172:175], v[210:213], v[98:101]
	v_mfma_f32_16x16x32_bf16 v[90:93], v[180:183], v[210:213], v[90:93]
	v_mfma_f32_16x16x32_bf16 v[86:89], v[172:175], v[218:221], v[86:89]
	v_mfma_f32_16x16x32_bf16 v[78:81], v[180:183], v[218:221], v[78:81]
	v_mfma_f32_16x16x32_bf16 v[70:73], v[172:175], v[226:229], v[70:73]
	v_mfma_f32_16x16x32_bf16 v[66:69], v[180:183], v[226:229], v[66:69]
	v_mfma_f32_16x16x32_bf16 v[114:117], v[176:179], v[192:195], v[114:117]
	v_mfma_f32_16x16x32_bf16 v[106:109], v[184:187], v[192:195], v[106:109]
	v_mfma_f32_16x16x32_bf16 v[98:101], v[176:179], v[214:217], v[98:101]
	v_mfma_f32_16x16x32_bf16 v[90:93], v[184:187], v[214:217], v[90:93]
	v_mfma_f32_16x16x32_bf16 v[86:89], v[176:179], v[222:225], v[86:89]
	v_mfma_f32_16x16x32_bf16 v[78:81], v[184:187], v[222:225], v[78:81]
	v_mfma_f32_16x16x32_bf16 v[70:73], v[176:179], v[230:233], v[70:73]
	v_mfma_f32_16x16x32_bf16 v[66:69], v[184:187], v[230:233], v[66:69]
	s_barrier
; #define PG8_STAGE(bufoff, gbase, voff) do { _Pragma("unroll") for (int _i = 0; _i < 2; ++_i) \
;         __builtin_amdgcn_global_load_lds((const unsigned*)((const char*)(gbase) + (voff)[_i]), (LAS unsigned*)(lds + (bufoff) + ldsw + _i * 8192), 16, 0, 0); } while (0)
; #define PG8_LDA(dst, b, h) do { _Pragma("unroll") for (int m = 0; m < 4; ++m) _Pragma("unroll") for (int k = 0; k < 2; ++k) dst[m][k] = *(const LAS bf16x8*)(lds + PG8_SA(b, h) + aoff + m * 2048 + k * 1024); } while (0)
; #define PG8_LDB(dst, b, h) do { _Pragma("unroll") for (int n = 0; n < 2; ++n) _Pragma("unroll") for (int k = 0; k < 2; ++k) dst[n][k] = *(const LAS bf16x8*)(lds + PG8_SB(b, h) + boff + n * 2048 + k * 1024); } while (0)
; #define PG8_MMA(ai, bj, At, Bt) do { __builtin_amdgcn_s_setprio(1); _Pragma("unroll") for (int m = 0; m < 4; ++m) _Pragma("unroll") for (int n = 0; n < 2; ++n) _Pragma("unroll") for (int k = 0; k < 2; ++k) \
;         acc[ai][bj][m][n] = __builtin_amdgcn_mfma_f32_16x16x32_bf16(Bt[n][k], At[m][k], acc[ai][bj][m][n], 0, 0, 0); __builtin_amdgcn_s_setprio(0); } while (0)
; #define PG8_WAIT_V(n) asm volatile("s_waitcnt vmcnt(" #n ")" ::: "memory")
; #define PG8_WAIT_L(n) asm volatile("s_waitcnt lgkmcnt(" #n ")" ::: "memory")
; #define PG8_BAR __builtin_amdgcn_s_barrier()
; #define PG8_SCHED __builtin_amdgcn_sched_barrier(0)
; template <class Epi, class Sched = StaticOrder, bool ALIGN_EPI = true>
; __device__ __forceinline__ void gemm_phase(LAS unsigned char* lds, const Gemm g, const Sched& S, const Epi& E) {
;     ...
;         for (int t = 0; t < nt; t += 2) {
;             const bool last = (t == nt - 2);
;             const char* a1 = cA + (size_t)(t + 1) * kstep;
;             const char* a2 = last ? nA : cA + (size_t)(t + 2) * kstep; const char* b2 = last ? nB : cB + (size_t)(t + 2) * kstep;
;             const char* a3 = a2 + kstep; const char* b3 = b2 + kstep;
;             PG8_LDB(B0, 0, 0); PG8_LDB(B1, 0, 1); PG8_SCHED; PG8_LDA(At, 0, 0); PG8_STAGE(PG8_SA(1, 1), a1 + hstep, voffA);
;             PG8_WAIT_V(8); PG8_WAIT_L(0); PG8_BAR; PG8_MMA(0, 0, At, B0); PG8_MMA(0, 1, At, B1); PG8_BAR; PG8_SCHED;
;     ...
;             PG8_LDA(At, 1, 1); PG8_STAGE(PG8_SB(1, 0), b3, voffB); PG8_STAGE(PG8_SB(1, 1), b3 + hstep, voffB); PG8_STAGE(PG8_SA(1, 0), a3, voffA);
;             PG8_WAIT_V(8); PG8_WAIT_L(0); PG8_BAR; PG8_MMA(1, 0, At, B0); PG8_MMA(1, 1, At, B1); PG8_BAR; PG8_SCHED;
	s_add_i32 s16, s33, s5
	v_lshl_add_u64 v[142:143], v[142:143], 0, s[34:35]
	s_mov_b32 m0, s16
	ds_read_b128 v[188:191], v146 offset:49152
	ds_read_b128 v[192:195], v146 offset:50176
	ds_read_b128 v[210:213], v146 offset:51200
	ds_read_b128 v[214:217], v146 offset:52224
	ds_read_b128 v[218:221], v146 offset:53248
	ds_read_b128 v[222:225], v146 offset:54272
	ds_read_b128 v[226:229], v146 offset:55296
	ds_read_b128 v[230:233], v146 offset:56320
	global_load_lds_dwordx4 v[142:143], off
	s_add_i32 m0, s16, 0x2000
	s_add_u32 s16, s46, 0x80080
	v_lshl_add_u64 v[142:143], v[152:153], 0, s[34:35]
	s_addc_u32 s17, s47, 0
	s_add_i32 s33, s70, s5
	global_load_lds_dwordx4 v[142:143], off
	v_lshl_add_u64 v[142:143], s[16:17], 0, v[134:135]
	s_mov_b32 m0, s33
	s_nop 0
	global_load_lds_dwordx4 v[142:143], off
	v_lshl_add_u64 v[142:143], s[16:17], 0, v[130:131]
	s_add_i32 m0, s33, 0x2000
	s_nop 0
	global_load_lds_dwordx4 v[142:143], off
	v_lshl_add_u64 v[142:143], v[196:197], 0, s[34:35]
	s_mov_b32 m0, s11
	s_nop 0
	global_load_lds_dwordx4 v[142:143], off
	v_lshl_add_u64 v[142:143], v[234:235], 0, s[34:35]
	s_mov_b32 m0, s18
	s_nop 0
	global_load_lds_dwordx4 v[142:143], off
	s_waitcnt vmcnt(8)
	s_waitcnt lgkmcnt(0)
	s_barrier
	s_waitcnt lgkmcnt(0)
	v_mfma_f32_16x16x32_bf16 v[62:65], v[148:151], v[188:191], v[62:65]
	v_mfma_f32_16x16x32_bf16 v[58:61], v[164:167], v[188:191], v[58:61]
	v_mfma_f32_16x16x32_bf16 v[54:57], v[148:151], v[210:213], v[54:57]
	v_mfma_f32_16x16x32_bf16 v[46:49], v[164:167], v[210:213], v[46:49]
	v_mfma_f32_16x16x32_bf16 v[38:41], v[148:151], v[218:221], v[38:41]
	v_mfma_f32_16x16x32_bf16 v[30:33], v[164:167], v[218:221], v[30:33]
	v_mfma_f32_16x16x32_bf16 v[22:25], v[148:151], v[226:229], v[22:25]
	v_mfma_f32_16x16x32_bf16 v[14:17], v[164:167], v[226:229], v[14:17]
	v_mfma_f32_16x16x32_bf16 v[62:65], v[160:163], v[192:195], v[62:65]
	v_mfma_f32_16x16x32_bf16 v[58:61], v[168:171], v[192:195], v[58:61]
	v_mfma_f32_16x16x32_bf16 v[54:57], v[160:163], v[214:217], v[54:57]
	v_mfma_f32_16x16x32_bf16 v[46:49], v[168:171], v[214:217], v[46:49]
	v_mfma_f32_16x16x32_bf16 v[38:41], v[160:163], v[222:225], v[38:41]
	v_mfma_f32_16x16x32_bf16 v[30:33], v[168:171], v[222:225], v[30:33]
	v_mfma_f32_16x16x32_bf16 v[22:25], v[160:163], v[230:233], v[22:25]
	v_mfma_f32_16x16x32_bf16 v[14:17], v[168:171], v[230:233], v[14:17]
	v_mfma_f32_16x16x32_bf16 v[50:53], v[172:175], v[188:191], v[50:53]
	v_mfma_f32_16x16x32_bf16 v[42:45], v[180:183], v[188:191], v[42:45]
	v_mfma_f32_16x16x32_bf16 v[34:37], v[172:175], v[210:213], v[34:37]
	v_mfma_f32_16x16x32_bf16 v[26:29], v[180:183], v[210:213], v[26:29]
	v_mfma_f32_16x16x32_bf16 v[18:21], v[172:175], v[218:221], v[18:21]
	v_mfma_f32_16x16x32_bf16 v[10:13], v[180:183], v[218:221], v[10:13]
	v_mfma_f32_16x16x32_bf16 v[6:9], v[172:175], v[226:229], v[6:9]
	v_mfma_f32_16x16x32_bf16 v[2:5], v[180:183], v[226:229], v[2:5]
	v_mfma_f32_16x16x32_bf16 v[50:53], v[176:179], v[192:195], v[50:53]
	v_mfma_f32_16x16x32_bf16 v[42:45], v[184:187], v[192:195], v[42:45]
	v_mfma_f32_16x16x32_bf16 v[34:37], v[176:179], v[214:217], v[34:37]
	v_mfma_f32_16x16x32_bf16 v[26:29], v[184:187], v[214:217], v[26:29]
	v_mfma_f32_16x16x32_bf16 v[18:21], v[176:179], v[222:225], v[18:21]
	v_mfma_f32_16x16x32_bf16 v[10:13], v[184:187], v[222:225], v[10:13]
	v_mfma_f32_16x16x32_bf16 v[6:9], v[176:179], v[230:233], v[6:9]
	v_mfma_f32_16x16x32_bf16 v[2:5], v[184:187], v[230:233], v[2:5]
	s_barrier
	s_add_i32 s49, s49, 2
	s_add_u32 s80, s80, 0x100
	s_addc_u32 s81, s81, 0
	s_add_u32 s37, s37, 0x100
	s_addc_u32 s43, s43, 0
	s_cmp_gt_u32 s49, 29
	s_cbranch_scc0 .LBB0_106
.LBB0_106:
	s_add_u32 s16, s80, 0xfff80080
	s_addc_u32 s17, s81, -1
	s_add_i32 s33, 0, 0x10000
	s_cmp_eq_u32 s49, 28
	s_cselect_b32 vcc_hi, s30, s17
	s_cselect_b32 vcc_lo, s31, s16
	v_add_u32_e32 v142, s33, v144
	s_cselect_b32 s47, s21, s43
	s_cselect_b32 s46, s36, s37
	s_add_i32 s70, 0, 0x14000
	ds_read_b128 v[148:151], v142
	ds_read_b128 v[160:163], v142 offset:1024
	ds_read_b128 v[164:167], v142 offset:2048
	ds_read_b128 v[168:171], v142 offset:3072
	v_add_u32_e32 v142, s70, v144
	ds_read_b128 v[172:175], v142
	ds_read_b128 v[176:179], v142 offset:1024
	ds_read_b128 v[180:183], v142 offset:2048
	ds_read_b128 v[184:187], v142 offset:3072
	v_lshl_add_u64 v[142:143], s[80:81], 0, v[138:139]
	s_add_i32 m0, s7, 0xc000
	ds_read_b128 v[188:191], v146
	ds_read_b128 v[192:195], v146 offset:1024
	ds_read_b128 v[210:213], v146 offset:2048
	ds_read_b128 v[214:217], v146 offset:3072
	ds_read_b128 v[218:221], v146 offset:4096
	ds_read_b128 v[222:225], v146 offset:5120
	ds_read_b128 v[226:229], v146 offset:6144
	ds_read_b128 v[230:233], v146 offset:7168
	global_load_lds_dwordx4 v[142:143], off
	v_lshl_add_u64 v[142:143], s[80:81], 0, v[140:141]
	s_add_i32 m0, s7, 0xe000
	s_nop 0
	global_load_lds_dwordx4 v[142:143], off
	s_waitcnt vmcnt(8)
	s_waitcnt lgkmcnt(0)
	s_barrier
; #define PG8_STAGE(bufoff, gbase, voff) do { _Pragma("unroll") for (int _i = 0; _i < 2; ++_i) \
;         __builtin_amdgcn_global_load_lds((const unsigned*)((const char*)(gbase) + (voff)[_i]), (LAS unsigned*)(lds + (bufoff) + ldsw + _i * 8192), 16, 0, 0); } while (0)
; #define PG8_LDA(dst, b, h) do { _Pragma("unroll") for (int m = 0; m < 4; ++m) _Pragma("unroll") for (int k = 0; k < 2; ++k) dst[m][k] = *(const LAS bf16x8*)(lds + PG8_SA(b, h) + aoff + m * 2048 + k * 1024); } while (0)
; #define PG8_MMA(ai, bj, At, Bt) do { __builtin_amdgcn_s_setprio(1); _Pragma("unroll") for (int m = 0; m < 4; ++m) _Pragma("unroll") for (int n = 0; n < 2; ++n) _Pragma("unroll") for (int k = 0; k < 2; ++k) \
;         acc[ai][bj][m][n] = __builtin_amdgcn_mfma_f32_16x16x32_bf16(Bt[n][k], At[m][k], acc[ai][bj][m][n], 0, 0, 0); __builtin_amdgcn_s_setprio(0); } while (0)
; #define PG8_WAIT_V(n) asm volatile("s_waitcnt vmcnt(" #n ")" ::: "memory")
; #define PG8_WAIT_L(n) asm volatile("s_waitcnt lgkmcnt(" #n ")" ::: "memory")
; #define PG8_BAR __builtin_amdgcn_s_barrier()
; #define PG8_SCHED __builtin_amdgcn_sched_barrier(0)
; template <class Epi, class Sched = StaticOrder, bool ALIGN_EPI = true>
; __device__ __forceinline__ void gemm_phase(LAS unsigned char* lds, const Gemm g, const Sched& S, const Epi& E) {
;     ...
;             PG8_WAIT_V(8); PG8_WAIT_L(0); PG8_BAR; PG8_MMA(0, 0, At, B0); PG8_MMA(0, 1, At, B1); PG8_BAR; PG8_SCHED;
;             PG8_LDA(At, 0, 1); PG8_STAGE(PG8_SB(0, 0), b2, voffB); PG8_STAGE(PG8_SB(0, 1), b2 + hstep, voffB); PG8_STAGE(PG8_SA(0, 0), a2, voffA);
;             PG8_WAIT_V(8); PG8_WAIT_L(0); PG8_BAR; PG8_MMA(1, 0, At, B0); PG8_MMA(1, 1, At, B1); PG8_BAR; PG8_SCHED;
	s_waitcnt lgkmcnt(0)
	v_mfma_f32_16x16x32_bf16 v[126:129], v[148:151], v[188:191], v[126:129]
	v_mfma_f32_16x16x32_bf16 v[122:125], v[164:167], v[188:191], v[122:125]
	v_mfma_f32_16x16x32_bf16 v[118:121], v[148:151], v[210:213], v[118:121]
	v_mfma_f32_16x16x32_bf16 v[110:113], v[164:167], v[210:213], v[110:113]
	v_mfma_f32_16x16x32_bf16 v[102:105], v[148:151], v[218:221], v[102:105]
	v_mfma_f32_16x16x32_bf16 v[94:97], v[164:167], v[218:221], v[94:97]
	v_mfma_f32_16x16x32_bf16 v[82:85], v[148:151], v[226:229], v[82:85]
	v_mfma_f32_16x16x32_bf16 v[74:77], v[164:167], v[226:229], v[74:77]
	v_mfma_f32_16x16x32_bf16 v[126:129], v[160:163], v[192:195], v[126:129]
	v_mfma_f32_16x16x32_bf16 v[122:125], v[168:171], v[192:195], v[122:125]
	v_mfma_f32_16x16x32_bf16 v[118:121], v[160:163], v[214:217], v[118:121]
	v_mfma_f32_16x16x32_bf16 v[110:113], v[168:171], v[214:217], v[110:113]
	v_mfma_f32_16x16x32_bf16 v[102:105], v[160:163], v[222:225], v[102:105]
	v_mfma_f32_16x16x32_bf16 v[94:97], v[168:171], v[222:225], v[94:97]
	v_mfma_f32_16x16x32_bf16 v[82:85], v[160:163], v[230:233], v[82:85]
	v_mfma_f32_16x16x32_bf16 v[74:77], v[168:171], v[230:233], v[74:77]
	v_mfma_f32_16x16x32_bf16 v[114:117], v[172:175], v[188:191], v[114:117]
	v_mfma_f32_16x16x32_bf16 v[106:109], v[180:183], v[188:191], v[106:109]
	v_mfma_f32_16x16x32_bf16 v[98:101], v[172:175], v[210:213], v[98:101]
	v_mfma_f32_16x16x32_bf16 v[90:93], v[180:183], v[210:213], v[90:93]
	v_mfma_f32_16x16x32_bf16 v[86:89], v[172:175], v[218:221], v[86:89]
	v_mfma_f32_16x16x32_bf16 v[78:81], v[180:183], v[218:221], v[78:81]
	v_mfma_f32_16x16x32_bf16 v[70:73], v[172:175], v[226:229], v[70:73]
	v_mfma_f32_16x16x32_bf16 v[66:69], v[180:183], v[226:229], v[66:69]
	v_mfma_f32_16x16x32_bf16 v[114:117], v[176:179], v[192:195], v[114:117]
	v_mfma_f32_16x16x32_bf16 v[106:109], v[184:187], v[192:195], v[106:109]
	v_mfma_f32_16x16x32_bf16 v[98:101], v[176:179], v[214:217], v[98:101]
	v_mfma_f32_16x16x32_bf16 v[90:93], v[184:187], v[214:217], v[90:93]
	v_mfma_f32_16x16x32_bf16 v[86:89], v[176:179], v[222:225], v[86:89]
	v_mfma_f32_16x16x32_bf16 v[78:81], v[184:187], v[222:225], v[78:81]
	v_mfma_f32_16x16x32_bf16 v[70:73], v[176:179], v[230:233], v[70:73]
	v_mfma_f32_16x16x32_bf16 v[66:69], v[184:187], v[230:233], v[66:69]
	s_barrier
	s_add_i32 s16, s33, s5
	v_lshl_add_u64 v[142:143], s[46:47], 0, v[134:135]
	s_mov_b32 m0, s16
	ds_read_b128 v[188:191], v146 offset:16384
	ds_read_b128 v[192:195], v146 offset:17408
	ds_read_b128 v[210:213], v146 offset:18432
	ds_read_b128 v[214:217], v146 offset:19456
	ds_read_b128 v[218:221], v146 offset:20480
	ds_read_b128 v[222:225], v146 offset:21504
	ds_read_b128 v[226:229], v146 offset:22528
	ds_read_b128 v[230:233], v146 offset:23552
	global_load_lds_dwordx4 v[142:143], off
	s_add_i32 m0, s16, 0x2000
	s_add_u32 s16, s46, 0x80000
	v_lshl_add_u64 v[152:153], s[46:47], 0, v[130:131]
	s_addc_u32 s17, s47, 0
	s_add_i32 s33, s70, s5
	global_load_lds_dwordx4 v[152:153], off
	v_lshl_add_u64 v[196:197], s[16:17], 0, v[134:135]
	s_mov_b32 m0, s33
	v_lshl_add_u64 v[234:235], vcc, 0, v[132:133]
	global_load_lds_dwordx4 v[196:197], off
	v_lshl_add_u64 v[196:197], s[16:17], 0, v[130:131]
	s_add_i32 m0, s33, 0x2000
	s_nop 0
	global_load_lds_dwordx4 v[196:197], off
	v_lshl_add_u64 v[196:197], vcc, 0, v[136:137]
	s_mov_b32 m0, s7
	s_nop 0
	global_load_lds_dwordx4 v[196:197], off
	s_mov_b32 m0, s8
	s_nop 0
	global_load_lds_dwordx4 v[234:235], off
	s_waitcnt vmcnt(8)
	s_waitcnt lgkmcnt(0)
	s_barrier
	s_waitcnt lgkmcnt(0)
	v_mfma_f32_16x16x32_bf16 v[62:65], v[148:151], v[188:191], v[62:65]
	v_mfma_f32_16x16x32_bf16 v[58:61], v[164:167], v[188:191], v[58:61]
	v_mfma_f32_16x16x32_bf16 v[54:57], v[148:151], v[210:213], v[54:57]
	v_mfma_f32_16x16x32_bf16 v[46:49], v[164:167], v[210:213], v[46:49]
	v_mfma_f32_16x16x32_bf16 v[38:41], v[148:151], v[218:221], v[38:41]
	v_mfma_f32_16x16x32_bf16 v[30:33], v[164:167], v[218:221], v[30:33]
	v_mfma_f32_16x16x32_bf16 v[22:25], v[148:151], v[226:229], v[22:25]
	v_mfma_f32_16x16x32_bf16 v[14:17], v[164:167], v[226:229], v[14:17]
	v_mfma_f32_16x16x32_bf16 v[62:65], v[160:163], v[192:195], v[62:65]
	v_mfma_f32_16x16x32_bf16 v[58:61], v[168:171], v[192:195], v[58:61]
	v_mfma_f32_16x16x32_bf16 v[54:57], v[160:163], v[214:217], v[54:57]
	v_mfma_f32_16x16x32_bf16 v[46:49], v[168:171], v[214:217], v[46:49]
	v_mfma_f32_16x16x32_bf16 v[38:41], v[160:163], v[222:225], v[38:41]
	v_mfma_f32_16x16x32_bf16 v[30:33], v[168:171], v[222:225], v[30:33]
	v_mfma_f32_16x16x32_bf16 v[22:25], v[160:163], v[230:233], v[22:25]
	v_mfma_f32_16x16x32_bf16 v[14:17], v[168:171], v[230:233], v[14:17]
	v_mfma_f32_16x16x32_bf16 v[50:53], v[172:175], v[188:191], v[50:53]
	v_mfma_f32_16x16x32_bf16 v[42:45], v[180:183], v[188:191], v[42:45]
	v_mfma_f32_16x16x32_bf16 v[34:37], v[172:175], v[210:213], v[34:37]
	v_mfma_f32_16x16x32_bf16 v[26:29], v[180:183], v[210:213], v[26:29]
	v_mfma_f32_16x16x32_bf16 v[18:21], v[172:175], v[218:221], v[18:21]
	v_mfma_f32_16x16x32_bf16 v[10:13], v[180:183], v[218:221], v[10:13]
	v_mfma_f32_16x16x32_bf16 v[6:9], v[172:175], v[226:229], v[6:9]
	v_mfma_f32_16x16x32_bf16 v[2:5], v[180:183], v[226:229], v[2:5]
	v_mfma_f32_16x16x32_bf16 v[50:53], v[176:179], v[192:195], v[50:53]
	v_mfma_f32_16x16x32_bf16 v[42:45], v[184:187], v[192:195], v[42:45]
	v_mfma_f32_16x16x32_bf16 v[34:37], v[176:179], v[214:217], v[34:37]
	v_mfma_f32_16x16x32_bf16 v[26:29], v[184:187], v[214:217], v[26:29]
	v_mfma_f32_16x16x32_bf16 v[18:21], v[176:179], v[222:225], v[18:21]
	v_mfma_f32_16x16x32_bf16 v[10:13], v[184:187], v[222:225], v[10:13]
	v_mfma_f32_16x16x32_bf16 v[6:9], v[176:179], v[230:233], v[6:9]
	v_mfma_f32_16x16x32_bf16 v[2:5], v[184:187], v[230:233], v[2:5]
	s_barrier
; #define PG8_STAGE(bufoff, gbase, voff) do { _Pragma("unroll") for (int _i = 0; _i < 2; ++_i) \
;         __builtin_amdgcn_global_load_lds((const unsigned*)((const char*)(gbase) + (voff)[_i]), (LAS unsigned*)(lds + (bufoff) + ldsw + _i * 8192), 16, 0, 0); } while (0)
; #define PG8_LDA(dst, b, h) do { _Pragma("unroll") for (int m = 0; m < 4; ++m) _Pragma("unroll") for (int k = 0; k < 2; ++k) dst[m][k] = *(const LAS bf16x8*)(lds + PG8_SA(b, h) + aoff + m * 2048 + k * 1024); } while (0)
; #define PG8_LDB(dst, b, h) do { _Pragma("unroll") for (int n = 0; n < 2; ++n) _Pragma("unroll") for (int k = 0; k < 2; ++k) dst[n][k] = *(const LAS bf16x8*)(lds + PG8_SB(b, h) + boff + n * 2048 + k * 1024); } while (0)
; #define PG8_MMA(ai, bj, At, Bt) do { __builtin_amdgcn_s_setprio(1); _Pragma("unroll") for (int m = 0; m < 4; ++m) _Pragma("unroll") for (int n = 0; n < 2; ++n) _Pragma("unroll") for (int k = 0; k < 2; ++k) \
;         acc[ai][bj][m][n] = __builtin_amdgcn_mfma_f32_16x16x32_bf16(Bt[n][k], At[m][k], acc[ai][bj][m][n], 0, 0, 0); __builtin_amdgcn_s_setprio(0); } while (0)
; #define PG8_WAIT_V(n) asm volatile("s_waitcnt vmcnt(" #n ")" ::: "memory")
; #define PG8_WAIT_L(n) asm volatile("s_waitcnt lgkmcnt(" #n ")" ::: "memory")
; #define PG8_BAR __builtin_amdgcn_s_barrier()
; #define PG8_SCHED __builtin_amdgcn_sched_barrier(0)
; template <class Epi, class Sched = StaticOrder, bool ALIGN_EPI = true>
; __device__ __forceinline__ void gemm_phase(LAS unsigned char* lds, const Gemm g, const Sched& S, const Epi& E) {
;     ...
;             PG8_LDB(B0, 1, 0); PG8_LDB(B1, 1, 1); PG8_SCHED; PG8_LDA(At, 1, 0); PG8_STAGE(PG8_SA(0, 1), a2 + hstep, voffA);
;             PG8_WAIT_V(8); PG8_WAIT_L(0); PG8_BAR; PG8_MMA(0, 0, At, B0); PG8_MMA(0, 1, At, B1); PG8_BAR; PG8_SCHED;
	s_add_i32 s33, 0, 0x18000
	v_add_u32_e32 v147, s33, v144
	s_add_i32 s70, 0, 0x1c000
	ds_read_b128 v[148:151], v147
	ds_read_b128 v[160:163], v147 offset:1024
	ds_read_b128 v[164:167], v147 offset:2048
	ds_read_b128 v[168:171], v147 offset:3072
	v_add_u32_e32 v147, s70, v144
	ds_read_b128 v[172:175], v147
	ds_read_b128 v[176:179], v147 offset:1024
	ds_read_b128 v[180:183], v147 offset:2048
	ds_read_b128 v[184:187], v147 offset:3072
	s_add_u32 s16, vcc_lo, 0x80000
	s_addc_u32 s17, vcc_hi, 0
	s_mov_b32 m0, s9
	v_lshl_add_u64 v[236:237], s[16:17], 0, v[136:137]
	ds_read_b128 v[188:191], v146 offset:32768
	ds_read_b128 v[192:195], v146 offset:33792
	ds_read_b128 v[210:213], v146 offset:34816
	ds_read_b128 v[214:217], v146 offset:35840
	ds_read_b128 v[218:221], v146 offset:36864
	ds_read_b128 v[222:225], v146 offset:37888
	ds_read_b128 v[226:229], v146 offset:38912
	ds_read_b128 v[230:233], v146 offset:39936
	global_load_lds_dwordx4 v[236:237], off
	v_lshl_add_u64 v[236:237], s[16:17], 0, v[132:133]
	s_mov_b32 m0, s10
	s_nop 0
	global_load_lds_dwordx4 v[236:237], off
	s_waitcnt vmcnt(8)
	s_waitcnt lgkmcnt(0)
	s_barrier
	s_waitcnt lgkmcnt(0)
	v_mfma_f32_16x16x32_bf16 v[126:129], v[148:151], v[188:191], v[126:129]
	v_mfma_f32_16x16x32_bf16 v[122:125], v[164:167], v[188:191], v[122:125]
	v_mfma_f32_16x16x32_bf16 v[118:121], v[148:151], v[210:213], v[118:121]
	v_mfma_f32_16x16x32_bf16 v[110:113], v[164:167], v[210:213], v[110:113]
	v_mfma_f32_16x16x32_bf16 v[102:105], v[148:151], v[218:221], v[102:105]
	v_mfma_f32_16x16x32_bf16 v[94:97], v[164:167], v[218:221], v[94:97]
	v_mfma_f32_16x16x32_bf16 v[82:85], v[148:151], v[226:229], v[82:85]
	v_mfma_f32_16x16x32_bf16 v[74:77], v[164:167], v[226:229], v[74:77]
	v_mfma_f32_16x16x32_bf16 v[126:129], v[160:163], v[192:195], v[126:129]
	v_mfma_f32_16x16x32_bf16 v[122:125], v[168:171], v[192:195], v[122:125]
	v_mfma_f32_16x16x32_bf16 v[118:121], v[160:163], v[214:217], v[118:121]
	v_mfma_f32_16x16x32_bf16 v[110:113], v[168:171], v[214:217], v[110:113]
	v_mfma_f32_16x16x32_bf16 v[102:105], v[160:163], v[222:225], v[102:105]
	v_mfma_f32_16x16x32_bf16 v[94:97], v[168:171], v[222:225], v[94:97]
	v_mfma_f32_16x16x32_bf16 v[82:85], v[160:163], v[230:233], v[82:85]
	v_mfma_f32_16x16x32_bf16 v[74:77], v[168:171], v[230:233], v[74:77]
	v_mfma_f32_16x16x32_bf16 v[114:117], v[172:175], v[188:191], v[114:117]
	v_mfma_f32_16x16x32_bf16 v[106:109], v[180:183], v[188:191], v[106:109]
	v_mfma_f32_16x16x32_bf16 v[98:101], v[172:175], v[210:213], v[98:101]
	v_mfma_f32_16x16x32_bf16 v[90:93], v[180:183], v[210:213], v[90:93]
	v_mfma_f32_16x16x32_bf16 v[86:89], v[172:175], v[218:221], v[86:89]
	v_mfma_f32_16x16x32_bf16 v[78:81], v[180:183], v[218:221], v[78:81]
	v_mfma_f32_16x16x32_bf16 v[70:73], v[172:175], v[226:229], v[70:73]
	v_mfma_f32_16x16x32_bf16 v[66:69], v[180:183], v[226:229], v[66:69]
	v_mfma_f32_16x16x32_bf16 v[114:117], v[176:179], v[192:195], v[114:117]
	v_mfma_f32_16x16x32_bf16 v[106:109], v[184:187], v[192:195], v[106:109]
	v_mfma_f32_16x16x32_bf16 v[98:101], v[176:179], v[214:217], v[98:101]
	v_mfma_f32_16x16x32_bf16 v[90:93], v[184:187], v[214:217], v[90:93]
	v_mfma_f32_16x16x32_bf16 v[86:89], v[176:179], v[222:225], v[86:89]
	v_mfma_f32_16x16x32_bf16 v[78:81], v[184:187], v[222:225], v[78:81]
	v_mfma_f32_16x16x32_bf16 v[70:73], v[176:179], v[230:233], v[70:73]
	v_mfma_f32_16x16x32_bf16 v[66:69], v[184:187], v[230:233], v[66:69]
	s_barrier
; #define PG8_STAGE(bufoff, gbase, voff) do { _Pragma("unroll") for (int _i = 0; _i < 2; ++_i) \
;         __builtin_amdgcn_global_load_lds((const unsigned*)((const char*)(gbase) + (voff)[_i]), (LAS unsigned*)(lds + (bufoff) + ldsw + _i * 8192), 16, 0, 0); } while (0)
; #define PG8_LDA(dst, b, h) do { _Pragma("unroll") for (int m = 0; m < 4; ++m) _Pragma("unroll") for (int k = 0; k < 2; ++k) dst[m][k] = *(const LAS bf16x8*)(lds + PG8_SA(b, h) + aoff + m * 2048 + k * 1024); } while (0)
; #define PG8_MMA(ai, bj, At, Bt) do { __builtin_amdgcn_s_setprio(1); _Pragma("unroll") for (int m = 0; m < 4; ++m) _Pragma("unroll") for (int n = 0; n < 2; ++n) _Pragma("unroll") for (int k = 0; k < 2; ++k) \
;         acc[ai][bj][m][n] = __builtin_amdgcn_mfma_f32_16x16x32_bf16(Bt[n][k], At[m][k], acc[ai][bj][m][n], 0, 0, 0); __builtin_amdgcn_s_setprio(0); } while (0)
; #define PG8_WAIT_V(n) asm volatile("s_waitcnt vmcnt(" #n ")" ::: "memory")
; #define PG8_WAIT_L(n) asm volatile("s_waitcnt lgkmcnt(" #n ")" ::: "memory")
; #define PG8_BAR __builtin_amdgcn_s_barrier()
; #define PG8_SCHED __builtin_amdgcn_sched_barrier(0)
; template <class Epi, class Sched = StaticOrder, bool ALIGN_EPI = true>
; __device__ __forceinline__ void gemm_phase(LAS unsigned char* lds, const Gemm g, const Sched& S, const Epi& E) {
;     ...
;             PG8_LDA(At, 1, 1); PG8_STAGE(PG8_SB(1, 0), b3, voffB); PG8_STAGE(PG8_SB(1, 1), b3 + hstep, voffB); PG8_STAGE(PG8_SA(1, 0), a3, voffA);
;             PG8_WAIT_V(8); PG8_WAIT_L(0); PG8_BAR; PG8_MMA(1, 0, At, B0); PG8_MMA(1, 1, At, B1); PG8_BAR; PG8_SCHED;
;         }
	s_add_i32 s16, s33, s5
	v_lshl_add_u64 v[142:143], v[142:143], 0, s[34:35]
	s_mov_b32 m0, s16
	ds_read_b128 v[188:191], v146 offset:49152
	ds_read_b128 v[192:195], v146 offset:50176
	ds_read_b128 v[210:213], v146 offset:51200
	ds_read_b128 v[214:217], v146 offset:52224
	ds_read_b128 v[218:221], v146 offset:53248
	ds_read_b128 v[222:225], v146 offset:54272
	ds_read_b128 v[226:229], v146 offset:55296
	ds_read_b128 v[230:233], v146 offset:56320
	global_load_lds_dwordx4 v[142:143], off
	s_add_i32 m0, s16, 0x2000
	s_add_u32 s16, s46, 0x80080
	v_lshl_add_u64 v[142:143], v[152:153], 0, s[34:35]
	s_addc_u32 s17, s47, 0
	s_add_i32 s33, s70, s5
	global_load_lds_dwordx4 v[142:143], off
	v_lshl_add_u64 v[142:143], s[16:17], 0, v[134:135]
	s_mov_b32 m0, s33
	s_nop 0
	global_load_lds_dwordx4 v[142:143], off
	v_lshl_add_u64 v[142:143], s[16:17], 0, v[130:131]
	s_add_i32 m0, s33, 0x2000
	s_nop 0
	global_load_lds_dwordx4 v[142:143], off
	v_lshl_add_u64 v[142:143], v[196:197], 0, s[34:35]
	s_mov_b32 m0, s11
	s_nop 0
	global_load_lds_dwordx4 v[142:143], off
	v_lshl_add_u64 v[142:143], v[234:235], 0, s[34:35]
	s_mov_b32 m0, s18
	s_nop 0
	global_load_lds_dwordx4 v[142:143], off
	s_waitcnt vmcnt(8)
	s_waitcnt lgkmcnt(0)
	s_barrier
	s_waitcnt lgkmcnt(0)
	v_mfma_f32_16x16x32_bf16 v[62:65], v[148:151], v[188:191], v[62:65]
	v_mfma_f32_16x16x32_bf16 v[58:61], v[164:167], v[188:191], v[58:61]
	v_mfma_f32_16x16x32_bf16 v[54:57], v[148:151], v[210:213], v[54:57]
	v_mfma_f32_16x16x32_bf16 v[46:49], v[164:167], v[210:213], v[46:49]
	v_mfma_f32_16x16x32_bf16 v[38:41], v[148:151], v[218:221], v[38:41]
	v_mfma_f32_16x16x32_bf16 v[30:33], v[164:167], v[218:221], v[30:33]
	v_mfma_f32_16x16x32_bf16 v[22:25], v[148:151], v[226:229], v[22:25]
	v_mfma_f32_16x16x32_bf16 v[14:17], v[164:167], v[226:229], v[14:17]
	v_mfma_f32_16x16x32_bf16 v[62:65], v[160:163], v[192:195], v[62:65]
	v_mfma_f32_16x16x32_bf16 v[58:61], v[168:171], v[192:195], v[58:61]
	v_mfma_f32_16x16x32_bf16 v[54:57], v[160:163], v[214:217], v[54:57]
	v_mfma_f32_16x16x32_bf16 v[46:49], v[168:171], v[214:217], v[46:49]
	v_mfma_f32_16x16x32_bf16 v[38:41], v[160:163], v[222:225], v[38:41]
	v_mfma_f32_16x16x32_bf16 v[30:33], v[168:171], v[222:225], v[30:33]
	v_mfma_f32_16x16x32_bf16 v[22:25], v[160:163], v[230:233], v[22:25]
	v_mfma_f32_16x16x32_bf16 v[14:17], v[168:171], v[230:233], v[14:17]
	v_mfma_f32_16x16x32_bf16 v[50:53], v[172:175], v[188:191], v[50:53]
	v_mfma_f32_16x16x32_bf16 v[42:45], v[180:183], v[188:191], v[42:45]
	v_mfma_f32_16x16x32_bf16 v[34:37], v[172:175], v[210:213], v[34:37]
	v_mfma_f32_16x16x32_bf16 v[26:29], v[180:183], v[210:213], v[26:29]
	v_mfma_f32_16x16x32_bf16 v[18:21], v[172:175], v[218:221], v[18:21]
	v_mfma_f32_16x16x32_bf16 v[10:13], v[180:183], v[218:221], v[10:13]
	v_mfma_f32_16x16x32_bf16 v[6:9], v[172:175], v[226:229], v[6:9]
	v_mfma_f32_16x16x32_bf16 v[2:5], v[180:183], v[226:229], v[2:5]
	v_mfma_f32_16x16x32_bf16 v[50:53], v[176:179], v[192:195], v[50:53]
	v_mfma_f32_16x16x32_bf16 v[42:45], v[184:187], v[192:195], v[42:45]
	v_mfma_f32_16x16x32_bf16 v[34:37], v[176:179], v[214:217], v[34:37]
	v_mfma_f32_16x16x32_bf16 v[26:29], v[184:187], v[214:217], v[26:29]
	v_mfma_f32_16x16x32_bf16 v[18:21], v[176:179], v[222:225], v[18:21]
	v_mfma_f32_16x16x32_bf16 v[10:13], v[184:187], v[222:225], v[10:13]
	v_mfma_f32_16x16x32_bf16 v[6:9], v[176:179], v[230:233], v[6:9]
	v_mfma_f32_16x16x32_bf16 v[2:5], v[184:187], v[230:233], v[2:5]
	s_barrier
	s_add_i32 s49, s49, 2
	s_add_u32 s80, s80, 0x100
	s_addc_u32 s81, s81, 0
	s_add_u32 s37, s37, 0x100
	s_addc_u32 s43, s43, 0
	s_cmp_gt_u32 s49, 29
	s_cbranch_scc0 .LBB0_106

; #define PG8_WAIT_V(n) asm volatile("s_waitcnt vmcnt(" #n ")" ::: "memory")
; #define PG8_BAR __builtin_amdgcn_s_barrier()
; template <class Epi, class Sched = StaticOrder, bool ALIGN_EPI = true>
; __device__ __forceinline__ void gemm_phase(LAS unsigned char* lds, const Gemm g, const Sched& S, const Epi& E) {
;     ...
;     PG8_WAIT_V(0);
;     if constexpr (!ALIGN_EPI) { if (wr == 0) PG8_BAR; }
;     PG8_BAR;
.LBB0_112:
	s_setprio 0
	s_waitcnt vmcnt(0)
	v_readlane_b32 s22, v254, 39
	v_readlane_b32 s23, v254, 45
	s_barrier

;     __device__ bool next(int i, Unit& u) const { const int idx = i * G + c; if (idx >= 64) return false; u.kp = idx & 3; u.pn = (idx >> 2) & 7; u.pm = 192 + (idx >> 5); return true; }
; #define PG8_STAGE(bufoff, gbase, voff) do { _Pragma("unroll") for (int _i = 0; _i < 2; ++_i) \
;         __builtin_amdgcn_global_load_lds((const unsigned*)((const char*)(gbase) + (voff)[_i]), (LAS unsigned*)(lds + (bufoff) + ldsw + _i * 8192), 16, 0, 0); } while (0)
; #define PG8_WAIT_V(n) asm volatile("s_waitcnt vmcnt(" #n ")" ::: "memory")
; #define PG8_BAR __builtin_amdgcn_s_barrier()
; template <class Epi, class Sched = StaticOrder, bool ALIGN_EPI = true>
; __device__ __forceinline__ void gemm_phase(LAS unsigned char* lds, const Gemm g, const Sched& S, const Epi& E) {
;     ...
;     for (int i = 0; i < 2; ++i) { int R, C; stage_rc(tid * 16 + i * 8192, R, C); const int Rb = Epi::PERM ? ((R & ~31) + perm32(R & 31)) : R;
;         voffA[i] = (unsigned)(R * g.ld + C) * 2u; voffB[i] = (unsigned)(Rb * g.ld + C) * 2u; }
;     const size_t kstep = (size_t)(BK * 2);
;     const size_t hstep = (size_t)HALF * g.ld * 2;
;     const size_t tstep = 2 * hstep;
;     const unsigned ldsw = (unsigned)wid * 1024u;
;     const int aoff = lds_byte(wr * 64 + fr, fq * 8), boff = lds_byte(wc * 32 + fr, fq * 8);
;     ...
;     Unit cur, nxt; int ui = 0;
;     if (!S.next(0, cur)) return;
;     f32x4 acc[2][2][4][2];
; #pragma unroll
;     for (int a = 0; a < 2; ++a)
; #pragma unroll
;         for (int b = 0; b < 2; ++b)
; #pragma unroll
;             for (int m = 0; m < 4; ++m)
; #pragma unroll
;                 for (int n = 0; n < 2; ++n) acc[a][b][m][n] = (f32x4){0.f, 0.f, 0.f, 0.f};
;     bf16x8 At[4][2], B0[2][2], B1[2][2];
;     const char* cA = (const char*)g.A + (size_t)cur.pm * tstep + (size_t)cur.kp * K * 2; const char* cB = (const char*)g.Bt + (size_t)cur.pn * tstep + (size_t)cur.kp * K * 2;
;     PG8_STAGE(PG8_SB(0, 0), cB, voffB); PG8_STAGE(PG8_SB(0, 1), cB + hstep, voffB); PG8_STAGE(PG8_SA(0, 0), cA, voffA); PG8_STAGE(PG8_SA(0, 1), cA + hstep, voffA);
;     if (wr == 1) PG8_BAR;
;     PG8_WAIT_V(2); PG8_BAR;
;     PG8_STAGE(PG8_SB(1, 0), cB + kstep, voffB); PG8_STAGE(PG8_SA(1, 0), cA + kstep, voffA); PG8_STAGE(PG8_SB(1, 1), cB + hstep + kstep, voffB);
;     PG8_WAIT_V(6); PG8_BAR;
.LBB0_330:
	v_lshrrev_b32_e32 v18, 1, v16
	v_and_b32_e32 v18, 24, v18
	s_lshl_b32 s11, s11, 5
	v_and_b32_e32 v17, 15, v16
	v_lshlrev_b32_e32 v19, 1, v18
	v_lshlrev_b32_e32 v16, 2, v16
	s_and_b32 s20, s11, 0x60
	v_lshl_or_b32 v1, s18, 6, v17
	v_lshl_or_b32 v17, v17, 6, v19
	v_and_b32_e32 v16, 32, v16
	s_lshl_b32 s11, s20, 7
	s_add_i32 m0, s7, 0x18000
	v_lshl_add_u64 v[8:9], v[8:9], 0, s[34:35]
	s_sext_i32_i8 s23, s12
	s_lshl_b32 s12, s18, 13
	v_bitop3_b32 v144, v17, s11, v16 bitop3:0xde
	s_waitcnt vmcnt(2)
	s_barrier
	global_load_lds_dwordx4 v[8:9], off
	v_lshl_add_u64 v[6:7], v[6:7], 0, s[34:35]
	s_add_i32 m0, s7, 0x1a000
	s_add_i32 s11, s7, 0x8000
	s_add_i32 s18, s7, 0xa000
	global_load_lds_dwordx4 v[6:7], off
	v_lshl_add_u64 v[2:3], v[2:3], 0, s[34:35]
	s_mov_b32 m0, s11
	s_add_u32 s16, s92, 0x80080
	global_load_lds_dwordx4 v[2:3], off
	v_lshl_add_u64 v[2:3], v[4:5], 0, s[34:35]
	s_mov_b32 m0, s18
	s_addc_u32 s17, s93, 0
	global_load_lds_dwordx4 v[2:3], off
	s_add_i32 m0, s7, 0x1c000
	v_lshl_add_u64 v[2:3], s[16:17], 0, v[134:135]
	global_load_lds_dwordx4 v[2:3], off
	v_lshl_add_u64 v[2:3], s[16:17], 0, v[130:131]
	s_add_i32 m0, s7, 0x1e000
	v_bitop3_b32 v19, v17, s12, v16 bitop3:0xde
	global_load_lds_dwordx4 v[2:3], off
	v_lshlrev_b32_e32 v2, 15, v14
	v_and_b32_e32 v2, 0xffff0000, v2
	v_lshl_add_u32 v2, v13, 12, v2
	v_and_b32_e32 v3, 1, v14
	v_lshl_or_b32 v2, v3, 6, v2
	v_lshl_add_u32 v138, v15, 1, v2
	v_lshlrev_b32_e32 v2, 15, v10
	v_and_b32_e32 v2, 0xffff0000, v2
	s_waitcnt vmcnt(6)
	v_lshl_add_u32 v2, v11, 12, v2
	v_and_b32_e32 v3, 1, v10
	s_cmpk_lt_u32 s13, 0x100
	v_lshl_or_b32 v2, v3, 6, v2
	s_cselect_b64 s[12:13], -1, 0
	v_or_b32_e32 v145, s20, v18
	v_mov_b32_e32 v139, v0
	v_lshl_add_u32 v140, v12, 1, v2
	v_mov_b32_e32 v141, v0
	s_mov_b32 s22, 0
	v_add_u32_e32 v146, 0, v19
	s_barrier
	s_waitcnt vmcnt(0)
	s_cmp_eq_u64 s[2:3], 0
	s_cbranch_scc1 .Lmy_pr_333
	s_setprio 1
.Lmy_pr_333:
	s_branch .LBB0_333
.LBB0_331:
	s_mov_b64 s[0:1], 0

; #define PG8_STAGE(bufoff, gbase, voff) do { _Pragma("unroll") for (int _i = 0; _i < 2; ++_i) \
;         __builtin_amdgcn_global_load_lds((const unsigned*)((const char*)(gbase) + (voff)[_i]), (LAS unsigned*)(lds + (bufoff) + ldsw + _i * 8192), 16, 0, 0); } while (0)
; #define PG8_LDA(dst, b, h) do { _Pragma("unroll") for (int m = 0; m < 4; ++m) _Pragma("unroll") for (int k = 0; k < 2; ++k) dst[m][k] = *(const LAS bf16x8*)(lds + PG8_SA(b, h) + aoff + m * 2048 + k * 1024); } while (0)
; #define PG8_LDB(dst, b, h) do { _Pragma("unroll") for (int n = 0; n < 2; ++n) _Pragma("unroll") for (int k = 0; k < 2; ++k) dst[n][k] = *(const LAS bf16x8*)(lds + PG8_SB(b, h) + boff + n * 2048 + k * 1024); } while (0)
; #define PG8_MMA(ai, bj, At, Bt) do { __builtin_amdgcn_s_setprio(1); _Pragma("unroll") for (int m = 0; m < 4; ++m) _Pragma("unroll") for (int n = 0; n < 2; ++n) _Pragma("unroll") for (int k = 0; k < 2; ++k) \
;         acc[ai][bj][m][n] = __builtin_amdgcn_mfma_f32_16x16x32_bf16(Bt[n][k], At[m][k], acc[ai][bj][m][n], 0, 0, 0); __builtin_amdgcn_s_setprio(0); } while (0)
; #define PG8_WAIT_V(n) asm volatile("s_waitcnt vmcnt(" #n ")" ::: "memory")
; #define PG8_WAIT_L(n) asm volatile("s_waitcnt lgkmcnt(" #n ")" ::: "memory")
; #define PG8_BAR __builtin_amdgcn_s_barrier()
; #define PG8_SCHED __builtin_amdgcn_sched_barrier(0)
; template <class Epi, class Sched = StaticOrder, bool ALIGN_EPI = true>
; __device__ __forceinline__ void gemm_phase(LAS unsigned char* lds, const Gemm g, const Sched& S, const Epi& E) {
;     ...
;             PG8_LDB(B0, 0, 0); PG8_LDB(B1, 0, 1); PG8_SCHED; PG8_LDA(At, 0, 0); PG8_STAGE(PG8_SA(1, 1), a1 + hstep, voffA);
;             PG8_WAIT_V(8); PG8_WAIT_L(0); PG8_BAR; PG8_MMA(0, 0, At, B0); PG8_MMA(0, 1, At, B1); PG8_BAR; PG8_SCHED;
;             PG8_LDA(At, 0, 1); PG8_STAGE(PG8_SB(0, 0), b2, voffB); PG8_STAGE(PG8_SB(0, 1), b2 + hstep, voffB); PG8_STAGE(PG8_SA(0, 0), a2, voffA);
.Lmy_nb_336:
	s_add_u32 s0, s80, 0xfff80080
	s_addc_u32 s1, s81, -1
	s_add_i32 s16, 0, 0x10000
	s_cmp_eq_u32 s79, 28
	s_cselect_b32 s31, s36, s1
	s_cselect_b32 s30, s37, s0
	v_add_u32_e32 v142, s16, v144
	s_cselect_b32 s1, s21, s70
	s_cselect_b32 s0, s43, s49
	s_add_i32 s33, 0, 0x14000
	ds_read_b128 v[148:151], v142
	ds_read_b128 v[160:163], v142 offset:1024
	ds_read_b128 v[164:167], v142 offset:2048
	ds_read_b128 v[168:171], v142 offset:3072
	v_add_u32_e32 v142, s33, v144
	ds_read_b128 v[172:175], v142
	ds_read_b128 v[176:179], v142 offset:1024
	ds_read_b128 v[180:183], v142 offset:2048
	ds_read_b128 v[184:187], v142 offset:3072
	v_lshl_add_u64 v[142:143], s[80:81], 0, v[138:139]
	s_add_i32 m0, s7, 0xc000
	ds_read_b128 v[188:191], v146
	ds_read_b128 v[192:195], v146 offset:1024
	ds_read_b128 v[210:213], v146 offset:2048
	ds_read_b128 v[214:217], v146 offset:3072
	ds_read_b128 v[218:221], v146 offset:4096
	ds_read_b128 v[222:225], v146 offset:5120
	ds_read_b128 v[226:229], v146 offset:6144
	ds_read_b128 v[230:233], v146 offset:7168
	global_load_lds_dwordx4 v[142:143], off
	v_lshl_add_u64 v[142:143], s[80:81], 0, v[140:141]
	s_add_i32 m0, s7, 0xe000
	s_nop 0
	global_load_lds_dwordx4 v[142:143], off
	s_waitcnt vmcnt(8)
	s_waitcnt lgkmcnt(0)
	s_barrier
	s_waitcnt lgkmcnt(0)
	v_mfma_f32_16x16x32_bf16 v[126:129], v[148:151], v[188:191], 0
	v_mfma_f32_16x16x32_bf16 v[122:125], v[164:167], v[188:191], 0
	v_mfma_f32_16x16x32_bf16 v[118:121], v[148:151], v[210:213], 0
	v_mfma_f32_16x16x32_bf16 v[110:113], v[164:167], v[210:213], 0
	v_mfma_f32_16x16x32_bf16 v[102:105], v[148:151], v[218:221], 0
	v_mfma_f32_16x16x32_bf16 v[94:97], v[164:167], v[218:221], 0
	v_mfma_f32_16x16x32_bf16 v[86:89], v[148:151], v[226:229], 0
	v_mfma_f32_16x16x32_bf16 v[78:81], v[164:167], v[226:229], 0
	v_mfma_f32_16x16x32_bf16 v[126:129], v[160:163], v[192:195], v[126:129]
	v_mfma_f32_16x16x32_bf16 v[122:125], v[168:171], v[192:195], v[122:125]
	v_mfma_f32_16x16x32_bf16 v[118:121], v[160:163], v[214:217], v[118:121]
	v_mfma_f32_16x16x32_bf16 v[110:113], v[168:171], v[214:217], v[110:113]
	v_mfma_f32_16x16x32_bf16 v[102:105], v[160:163], v[222:225], v[102:105]
	v_mfma_f32_16x16x32_bf16 v[94:97], v[168:171], v[222:225], v[94:97]
	v_mfma_f32_16x16x32_bf16 v[86:89], v[160:163], v[230:233], v[86:89]
	v_mfma_f32_16x16x32_bf16 v[78:81], v[168:171], v[230:233], v[78:81]
	v_mfma_f32_16x16x32_bf16 v[114:117], v[172:175], v[188:191], 0
	v_mfma_f32_16x16x32_bf16 v[106:109], v[180:183], v[188:191], 0
	v_mfma_f32_16x16x32_bf16 v[98:101], v[172:175], v[210:213], 0
	v_mfma_f32_16x16x32_bf16 v[90:93], v[180:183], v[210:213], 0
	v_mfma_f32_16x16x32_bf16 v[82:85], v[172:175], v[218:221], 0
	v_mfma_f32_16x16x32_bf16 v[74:77], v[180:183], v[218:221], 0
	v_mfma_f32_16x16x32_bf16 v[70:73], v[172:175], v[226:229], 0
	v_mfma_f32_16x16x32_bf16 v[66:69], v[180:183], v[226:229], 0
	v_mfma_f32_16x16x32_bf16 v[114:117], v[176:179], v[192:195], v[114:117]
	v_mfma_f32_16x16x32_bf16 v[106:109], v[184:187], v[192:195], v[106:109]
	v_mfma_f32_16x16x32_bf16 v[98:101], v[176:179], v[214:217], v[98:101]
	v_mfma_f32_16x16x32_bf16 v[90:93], v[184:187], v[214:217], v[90:93]
	v_mfma_f32_16x16x32_bf16 v[82:85], v[176:179], v[222:225], v[82:85]
	v_mfma_f32_16x16x32_bf16 v[74:77], v[184:187], v[222:225], v[74:77]
	v_mfma_f32_16x16x32_bf16 v[70:73], v[176:179], v[230:233], v[70:73]
	v_mfma_f32_16x16x32_bf16 v[66:69], v[184:187], v[230:233], v[66:69]
	s_barrier
	s_add_i32 s16, s16, s5
	v_lshl_add_u64 v[142:143], s[0:1], 0, v[134:135]
	s_mov_b32 m0, s16
	ds_read_b128 v[188:191], v146 offset:16384
	ds_read_b128 v[192:195], v146 offset:17408
	ds_read_b128 v[210:213], v146 offset:18432
	ds_read_b128 v[214:217], v146 offset:19456
	ds_read_b128 v[218:221], v146 offset:20480
	ds_read_b128 v[222:225], v146 offset:21504
	ds_read_b128 v[226:229], v146 offset:22528
	ds_read_b128 v[230:233], v146 offset:23552
	global_load_lds_dwordx4 v[142:143], off
	s_add_i32 m0, s16, 0x2000
	s_add_u32 s16, s0, 0x80000
	v_lshl_add_u64 v[152:153], s[0:1], 0, v[130:131]
	s_addc_u32 s17, s1, 0
	s_add_i32 s33, s33, s5
	global_load_lds_dwordx4 v[152:153], off
	v_lshl_add_u64 v[196:197], s[16:17], 0, v[134:135]
	s_mov_b32 m0, s33
	v_lshl_add_u64 v[234:235], s[30:31], 0, v[132:133]
	global_load_lds_dwordx4 v[196:197], off
	v_lshl_add_u64 v[196:197], s[16:17], 0, v[130:131]
	s_add_i32 m0, s33, 0x2000
	s_nop 0
	global_load_lds_dwordx4 v[196:197], off
	v_lshl_add_u64 v[196:197], s[30:31], 0, v[136:137]
	s_mov_b32 m0, s7
	s_nop 0
	global_load_lds_dwordx4 v[196:197], off
	s_mov_b32 m0, s8
	s_nop 0
	global_load_lds_dwordx4 v[234:235], off
	s_waitcnt vmcnt(8)
	s_waitcnt lgkmcnt(0)
	s_barrier
; #define PG8_STAGE(bufoff, gbase, voff) do { _Pragma("unroll") for (int _i = 0; _i < 2; ++_i) \
;         __builtin_amdgcn_global_load_lds((const unsigned*)((const char*)(gbase) + (voff)[_i]), (LAS unsigned*)(lds + (bufoff) + ldsw + _i * 8192), 16, 0, 0); } while (0)
; #define PG8_LDA(dst, b, h) do { _Pragma("unroll") for (int m = 0; m < 4; ++m) _Pragma("unroll") for (int k = 0; k < 2; ++k) dst[m][k] = *(const LAS bf16x8*)(lds + PG8_SA(b, h) + aoff + m * 2048 + k * 1024); } while (0)
; #define PG8_LDB(dst, b, h) do { _Pragma("unroll") for (int n = 0; n < 2; ++n) _Pragma("unroll") for (int k = 0; k < 2; ++k) dst[n][k] = *(const LAS bf16x8*)(lds + PG8_SB(b, h) + boff + n * 2048 + k * 1024); } while (0)
; #define PG8_MMA(ai, bj, At, Bt) do { __builtin_amdgcn_s_setprio(1); _Pragma("unroll") for (int m = 0; m < 4; ++m) _Pragma("unroll") for (int n = 0; n < 2; ++n) _Pragma("unroll") for (int k = 0; k < 2; ++k) \
;         acc[ai][bj][m][n] = __builtin_amdgcn_mfma_f32_16x16x32_bf16(Bt[n][k], At[m][k], acc[ai][bj][m][n], 0, 0, 0); __builtin_amdgcn_s_setprio(0); } while (0)
; #define PG8_WAIT_V(n) asm volatile("s_waitcnt vmcnt(" #n ")" ::: "memory")
; #define PG8_WAIT_L(n) asm volatile("s_waitcnt lgkmcnt(" #n ")" ::: "memory")
; #define PG8_BAR __builtin_amdgcn_s_barrier()
; #define PG8_SCHED __builtin_amdgcn_sched_barrier(0)
; template <class Epi, class Sched = StaticOrder, bool ALIGN_EPI = true>
; __device__ __forceinline__ void gemm_phase(LAS unsigned char* lds, const Gemm g, const Sched& S, const Epi& E) {
;     ...
;             PG8_WAIT_V(8); PG8_WAIT_L(0); PG8_BAR; PG8_MMA(1, 0, At, B0); PG8_MMA(1, 1, At, B1); PG8_BAR; PG8_SCHED;
;             PG8_LDB(B0, 1, 0); PG8_LDB(B1, 1, 1); PG8_SCHED; PG8_LDA(At, 1, 0); PG8_STAGE(PG8_SA(0, 1), a2 + hstep, voffA);
;             PG8_WAIT_V(8); PG8_WAIT_L(0); PG8_BAR; PG8_MMA(0, 0, At, B0); PG8_MMA(0, 1, At, B1); PG8_BAR; PG8_SCHED;
	s_waitcnt lgkmcnt(0)
	v_mfma_f32_16x16x32_bf16 v[62:65], v[148:151], v[188:191], 0
	v_mfma_f32_16x16x32_bf16 v[58:61], v[164:167], v[188:191], 0
	v_mfma_f32_16x16x32_bf16 v[54:57], v[148:151], v[210:213], 0
	v_mfma_f32_16x16x32_bf16 v[46:49], v[164:167], v[210:213], 0
	v_mfma_f32_16x16x32_bf16 v[38:41], v[148:151], v[218:221], 0
	v_mfma_f32_16x16x32_bf16 v[30:33], v[164:167], v[218:221], 0
	v_mfma_f32_16x16x32_bf16 v[22:25], v[148:151], v[226:229], 0
	v_mfma_f32_16x16x32_bf16 v[14:17], v[164:167], v[226:229], 0
	v_mfma_f32_16x16x32_bf16 v[62:65], v[160:163], v[192:195], v[62:65]
	v_mfma_f32_16x16x32_bf16 v[58:61], v[168:171], v[192:195], v[58:61]
	v_mfma_f32_16x16x32_bf16 v[54:57], v[160:163], v[214:217], v[54:57]
	v_mfma_f32_16x16x32_bf16 v[46:49], v[168:171], v[214:217], v[46:49]
	v_mfma_f32_16x16x32_bf16 v[38:41], v[160:163], v[222:225], v[38:41]
	v_mfma_f32_16x16x32_bf16 v[30:33], v[168:171], v[222:225], v[30:33]
	v_mfma_f32_16x16x32_bf16 v[22:25], v[160:163], v[230:233], v[22:25]
	v_mfma_f32_16x16x32_bf16 v[14:17], v[168:171], v[230:233], v[14:17]
	v_mfma_f32_16x16x32_bf16 v[50:53], v[172:175], v[188:191], 0
	v_mfma_f32_16x16x32_bf16 v[42:45], v[180:183], v[188:191], 0
	v_mfma_f32_16x16x32_bf16 v[34:37], v[172:175], v[210:213], 0
	v_mfma_f32_16x16x32_bf16 v[26:29], v[180:183], v[210:213], 0
	v_mfma_f32_16x16x32_bf16 v[18:21], v[172:175], v[218:221], 0
	v_mfma_f32_16x16x32_bf16 v[10:13], v[180:183], v[218:221], 0
	v_mfma_f32_16x16x32_bf16 v[6:9], v[172:175], v[226:229], 0
	v_mfma_f32_16x16x32_bf16 v[2:5], v[180:183], v[226:229], 0
	v_mfma_f32_16x16x32_bf16 v[50:53], v[176:179], v[192:195], v[50:53]
	v_mfma_f32_16x16x32_bf16 v[42:45], v[184:187], v[192:195], v[42:45]
	v_mfma_f32_16x16x32_bf16 v[34:37], v[176:179], v[214:217], v[34:37]
	v_mfma_f32_16x16x32_bf16 v[26:29], v[184:187], v[214:217], v[26:29]
	v_mfma_f32_16x16x32_bf16 v[18:21], v[176:179], v[222:225], v[18:21]
	v_mfma_f32_16x16x32_bf16 v[10:13], v[184:187], v[222:225], v[10:13]
	v_mfma_f32_16x16x32_bf16 v[6:9], v[176:179], v[230:233], v[6:9]
	v_mfma_f32_16x16x32_bf16 v[2:5], v[184:187], v[230:233], v[2:5]
	s_barrier
	s_add_i32 s33, 0, 0x18000
	v_add_u32_e32 v147, s33, v144
	s_add_i32 s82, 0, 0x1c000
	ds_read_b128 v[148:151], v147
	ds_read_b128 v[160:163], v147 offset:1024
	ds_read_b128 v[164:167], v147 offset:2048
	ds_read_b128 v[168:171], v147 offset:3072
	v_add_u32_e32 v147, s82, v144
	ds_read_b128 v[172:175], v147
	ds_read_b128 v[176:179], v147 offset:1024
	ds_read_b128 v[180:183], v147 offset:2048
	ds_read_b128 v[184:187], v147 offset:3072
	s_add_u32 s16, s30, 0x80000
	s_addc_u32 s17, s31, 0
	s_mov_b32 m0, s9
	v_lshl_add_u64 v[236:237], s[16:17], 0, v[136:137]
	ds_read_b128 v[188:191], v146 offset:32768
	ds_read_b128 v[192:195], v146 offset:33792
	ds_read_b128 v[210:213], v146 offset:34816
	ds_read_b128 v[214:217], v146 offset:35840
	ds_read_b128 v[218:221], v146 offset:36864
	ds_read_b128 v[222:225], v146 offset:37888
	ds_read_b128 v[226:229], v146 offset:38912
	ds_read_b128 v[230:233], v146 offset:39936
	global_load_lds_dwordx4 v[236:237], off
	v_lshl_add_u64 v[236:237], s[16:17], 0, v[132:133]
	s_mov_b32 m0, s10
	s_nop 0
	global_load_lds_dwordx4 v[236:237], off
	s_waitcnt vmcnt(8)
	s_waitcnt lgkmcnt(0)
	s_barrier
	s_waitcnt lgkmcnt(0)
	v_mfma_f32_16x16x32_bf16 v[126:129], v[148:151], v[188:191], v[126:129]
	v_mfma_f32_16x16x32_bf16 v[122:125], v[164:167], v[188:191], v[122:125]
	v_mfma_f32_16x16x32_bf16 v[118:121], v[148:151], v[210:213], v[118:121]
	v_mfma_f32_16x16x32_bf16 v[110:113], v[164:167], v[210:213], v[110:113]
	v_mfma_f32_16x16x32_bf16 v[102:105], v[148:151], v[218:221], v[102:105]
	v_mfma_f32_16x16x32_bf16 v[94:97], v[164:167], v[218:221], v[94:97]
	v_mfma_f32_16x16x32_bf16 v[86:89], v[148:151], v[226:229], v[86:89]
	v_mfma_f32_16x16x32_bf16 v[78:81], v[164:167], v[226:229], v[78:81]
	v_mfma_f32_16x16x32_bf16 v[126:129], v[160:163], v[192:195], v[126:129]
	v_mfma_f32_16x16x32_bf16 v[122:125], v[168:171], v[192:195], v[122:125]
	v_mfma_f32_16x16x32_bf16 v[118:121], v[160:163], v[214:217], v[118:121]
	v_mfma_f32_16x16x32_bf16 v[110:113], v[168:171], v[214:217], v[110:113]
	v_mfma_f32_16x16x32_bf16 v[102:105], v[160:163], v[222:225], v[102:105]
	v_mfma_f32_16x16x32_bf16 v[94:97], v[168:171], v[222:225], v[94:97]
	v_mfma_f32_16x16x32_bf16 v[86:89], v[160:163], v[230:233], v[86:89]
	v_mfma_f32_16x16x32_bf16 v[78:81], v[168:171], v[230:233], v[78:81]
	v_mfma_f32_16x16x32_bf16 v[114:117], v[172:175], v[188:191], v[114:117]
	v_mfma_f32_16x16x32_bf16 v[106:109], v[180:183], v[188:191], v[106:109]
	v_mfma_f32_16x16x32_bf16 v[98:101], v[172:175], v[210:213], v[98:101]
	v_mfma_f32_16x16x32_bf16 v[90:93], v[180:183], v[210:213], v[90:93]
	v_mfma_f32_16x16x32_bf16 v[82:85], v[172:175], v[218:221], v[82:85]
	v_mfma_f32_16x16x32_bf16 v[74:77], v[180:183], v[218:221], v[74:77]
	v_mfma_f32_16x16x32_bf16 v[70:73], v[172:175], v[226:229], v[70:73]
	v_mfma_f32_16x16x32_bf16 v[66:69], v[180:183], v[226:229], v[66:69]
	v_mfma_f32_16x16x32_bf16 v[114:117], v[176:179], v[192:195], v[114:117]
	v_mfma_f32_16x16x32_bf16 v[106:109], v[184:187], v[192:195], v[106:109]
	v_mfma_f32_16x16x32_bf16 v[98:101], v[176:179], v[214:217], v[98:101]
	v_mfma_f32_16x16x32_bf16 v[90:93], v[184:187], v[214:217], v[90:93]
	v_mfma_f32_16x16x32_bf16 v[82:85], v[176:179], v[222:225], v[82:85]
	v_mfma_f32_16x16x32_bf16 v[74:77], v[184:187], v[222:225], v[74:77]
	v_mfma_f32_16x16x32_bf16 v[70:73], v[176:179], v[230:233], v[70:73]
	v_mfma_f32_16x16x32_bf16 v[66:69], v[184:187], v[230:233], v[66:69]
	s_barrier
; #define PG8_STAGE(bufoff, gbase, voff) do { _Pragma("unroll") for (int _i = 0; _i < 2; ++_i) \
;         __builtin_amdgcn_global_load_lds((const unsigned*)((const char*)(gbase) + (voff)[_i]), (LAS unsigned*)(lds + (bufoff) + ldsw + _i * 8192), 16, 0, 0); } while (0)
; #define PG8_LDA(dst, b, h) do { _Pragma("unroll") for (int m = 0; m < 4; ++m) _Pragma("unroll") for (int k = 0; k < 2; ++k) dst[m][k] = *(const LAS bf16x8*)(lds + PG8_SA(b, h) + aoff + m * 2048 + k * 1024); } while (0)
; #define PG8_LDB(dst, b, h) do { _Pragma("unroll") for (int n = 0; n < 2; ++n) _Pragma("unroll") for (int k = 0; k < 2; ++k) dst[n][k] = *(const LAS bf16x8*)(lds + PG8_SB(b, h) + boff + n * 2048 + k * 1024); } while (0)
; #define PG8_MMA(ai, bj, At, Bt) do { __builtin_amdgcn_s_setprio(1); _Pragma("unroll") for (int m = 0; m < 4; ++m) _Pragma("unroll") for (int n = 0; n < 2; ++n) _Pragma("unroll") for (int k = 0; k < 2; ++k) \
;         acc[ai][bj][m][n] = __builtin_amdgcn_mfma_f32_16x16x32_bf16(Bt[n][k], At[m][k], acc[ai][bj][m][n], 0, 0, 0); __builtin_amdgcn_s_setprio(0); } while (0)
; #define PG8_WAIT_V(n) asm volatile("s_waitcnt vmcnt(" #n ")" ::: "memory")
; #define PG8_WAIT_L(n) asm volatile("s_waitcnt lgkmcnt(" #n ")" ::: "memory")
; #define PG8_BAR __builtin_amdgcn_s_barrier()
; #define PG8_SCHED __builtin_amdgcn_sched_barrier(0)
; template <class Epi, class Sched = StaticOrder, bool ALIGN_EPI = true>
; __device__ __forceinline__ void gemm_phase(LAS unsigned char* lds, const Gemm g, const Sched& S, const Epi& E) {
;     ...
;         for (int t = 0; t < nt; t += 2) {
;             const bool last = (t == nt - 2);
;             const char* a1 = cA + (size_t)(t + 1) * kstep;
;             const char* a2 = last ? nA : cA + (size_t)(t + 2) * kstep; const char* b2 = last ? nB : cB + (size_t)(t + 2) * kstep;
;             const char* a3 = a2 + kstep; const char* b3 = b2 + kstep;
;             PG8_LDB(B0, 0, 0); PG8_LDB(B1, 0, 1); PG8_SCHED; PG8_LDA(At, 0, 0); PG8_STAGE(PG8_SA(1, 1), a1 + hstep, voffA);
;             PG8_WAIT_V(8); PG8_WAIT_L(0); PG8_BAR; PG8_MMA(0, 0, At, B0); PG8_MMA(0, 1, At, B1); PG8_BAR; PG8_SCHED;
;     ...
;             PG8_LDA(At, 1, 1); PG8_STAGE(PG8_SB(1, 0), b3, voffB); PG8_STAGE(PG8_SB(1, 1), b3 + hstep, voffB); PG8_STAGE(PG8_SA(1, 0), a3, voffA);
;             PG8_WAIT_V(8); PG8_WAIT_L(0); PG8_BAR; PG8_MMA(1, 0, At, B0); PG8_MMA(1, 1, At, B1); PG8_BAR; PG8_SCHED;
	s_add_i32 s16, s33, s5
	v_lshl_add_u64 v[142:143], v[142:143], 0, s[34:35]
	s_mov_b32 m0, s16
	ds_read_b128 v[188:191], v146 offset:49152
	ds_read_b128 v[192:195], v146 offset:50176
	ds_read_b128 v[210:213], v146 offset:51200
	ds_read_b128 v[214:217], v146 offset:52224
	ds_read_b128 v[218:221], v146 offset:53248
	ds_read_b128 v[222:225], v146 offset:54272
	ds_read_b128 v[226:229], v146 offset:55296
	ds_read_b128 v[230:233], v146 offset:56320
	global_load_lds_dwordx4 v[142:143], off
	s_add_i32 m0, s16, 0x2000
	s_add_u32 s0, s0, 0x80080
	v_lshl_add_u64 v[142:143], v[152:153], 0, s[34:35]
	s_addc_u32 s1, s1, 0
	s_add_i32 s16, s82, s5
	global_load_lds_dwordx4 v[142:143], off
	v_lshl_add_u64 v[142:143], s[0:1], 0, v[134:135]
	s_mov_b32 m0, s16
	s_nop 0
	global_load_lds_dwordx4 v[142:143], off
	v_lshl_add_u64 v[142:143], s[0:1], 0, v[130:131]
	s_add_i32 m0, s16, 0x2000
	s_nop 0
	global_load_lds_dwordx4 v[142:143], off
	v_lshl_add_u64 v[142:143], v[196:197], 0, s[34:35]
	s_mov_b32 m0, s11
	s_nop 0
	global_load_lds_dwordx4 v[142:143], off
	v_lshl_add_u64 v[142:143], v[234:235], 0, s[34:35]
	s_mov_b32 m0, s18
	s_nop 0
	global_load_lds_dwordx4 v[142:143], off
	s_waitcnt vmcnt(8)
	s_waitcnt lgkmcnt(0)
	s_barrier
	s_waitcnt lgkmcnt(0)
	v_mfma_f32_16x16x32_bf16 v[62:65], v[148:151], v[188:191], v[62:65]
	v_mfma_f32_16x16x32_bf16 v[58:61], v[164:167], v[188:191], v[58:61]
	v_mfma_f32_16x16x32_bf16 v[54:57], v[148:151], v[210:213], v[54:57]
	v_mfma_f32_16x16x32_bf16 v[46:49], v[164:167], v[210:213], v[46:49]
	v_mfma_f32_16x16x32_bf16 v[38:41], v[148:151], v[218:221], v[38:41]
	v_mfma_f32_16x16x32_bf16 v[30:33], v[164:167], v[218:221], v[30:33]
	v_mfma_f32_16x16x32_bf16 v[22:25], v[148:151], v[226:229], v[22:25]
	v_mfma_f32_16x16x32_bf16 v[14:17], v[164:167], v[226:229], v[14:17]
	v_mfma_f32_16x16x32_bf16 v[62:65], v[160:163], v[192:195], v[62:65]
	v_mfma_f32_16x16x32_bf16 v[58:61], v[168:171], v[192:195], v[58:61]
	v_mfma_f32_16x16x32_bf16 v[54:57], v[160:163], v[214:217], v[54:57]
	v_mfma_f32_16x16x32_bf16 v[46:49], v[168:171], v[214:217], v[46:49]
	v_mfma_f32_16x16x32_bf16 v[38:41], v[160:163], v[222:225], v[38:41]
	v_mfma_f32_16x16x32_bf16 v[30:33], v[168:171], v[222:225], v[30:33]
	v_mfma_f32_16x16x32_bf16 v[22:25], v[160:163], v[230:233], v[22:25]
	v_mfma_f32_16x16x32_bf16 v[14:17], v[168:171], v[230:233], v[14:17]
	v_mfma_f32_16x16x32_bf16 v[50:53], v[172:175], v[188:191], v[50:53]
	v_mfma_f32_16x16x32_bf16 v[42:45], v[180:183], v[188:191], v[42:45]
	v_mfma_f32_16x16x32_bf16 v[34:37], v[172:175], v[210:213], v[34:37]
	v_mfma_f32_16x16x32_bf16 v[26:29], v[180:183], v[210:213], v[26:29]
	v_mfma_f32_16x16x32_bf16 v[18:21], v[172:175], v[218:221], v[18:21]
	v_mfma_f32_16x16x32_bf16 v[10:13], v[180:183], v[218:221], v[10:13]
	v_mfma_f32_16x16x32_bf16 v[6:9], v[172:175], v[226:229], v[6:9]
	v_mfma_f32_16x16x32_bf16 v[2:5], v[180:183], v[226:229], v[2:5]
	v_mfma_f32_16x16x32_bf16 v[50:53], v[176:179], v[192:195], v[50:53]
	v_mfma_f32_16x16x32_bf16 v[42:45], v[184:187], v[192:195], v[42:45]
	v_mfma_f32_16x16x32_bf16 v[34:37], v[176:179], v[214:217], v[34:37]
	v_mfma_f32_16x16x32_bf16 v[26:29], v[184:187], v[214:217], v[26:29]
	v_mfma_f32_16x16x32_bf16 v[18:21], v[176:179], v[222:225], v[18:21]
	v_mfma_f32_16x16x32_bf16 v[10:13], v[184:187], v[222:225], v[10:13]
	v_mfma_f32_16x16x32_bf16 v[6:9], v[176:179], v[230:233], v[6:9]
	v_mfma_f32_16x16x32_bf16 v[2:5], v[184:187], v[230:233], v[2:5]
	s_barrier
	s_add_i32 s79, s79, 2
	s_add_u32 s80, s80, 0x100
	s_addc_u32 s81, s81, 0
	s_add_u32 s49, s49, 0x100
	s_addc_u32 s70, s70, 0
	s_cmp_gt_u32 s79, 29
	s_cbranch_scc0 .LBB0_336
.LBB0_336:
	s_add_u32 s0, s80, 0xfff80080
	s_addc_u32 s1, s81, -1
	s_add_i32 s16, 0, 0x10000
	s_cmp_eq_u32 s79, 28
	s_cselect_b32 s31, s36, s1
	s_cselect_b32 s30, s37, s0
	v_add_u32_e32 v142, s16, v144
	s_cselect_b32 s1, s21, s70
	s_cselect_b32 s0, s43, s49
	s_add_i32 s33, 0, 0x14000
	ds_read_b128 v[148:151], v142
	ds_read_b128 v[160:163], v142 offset:1024
	ds_read_b128 v[164:167], v142 offset:2048
	ds_read_b128 v[168:171], v142 offset:3072
	v_add_u32_e32 v142, s33, v144
	ds_read_b128 v[172:175], v142
	ds_read_b128 v[176:179], v142 offset:1024
	ds_read_b128 v[180:183], v142 offset:2048
	ds_read_b128 v[184:187], v142 offset:3072
	v_lshl_add_u64 v[142:143], s[80:81], 0, v[138:139]
	s_add_i32 m0, s7, 0xc000
	ds_read_b128 v[188:191], v146
	ds_read_b128 v[192:195], v146 offset:1024
	ds_read_b128 v[210:213], v146 offset:2048
	ds_read_b128 v[214:217], v146 offset:3072
	ds_read_b128 v[218:221], v146 offset:4096
	ds_read_b128 v[222:225], v146 offset:5120
	ds_read_b128 v[226:229], v146 offset:6144
	ds_read_b128 v[230:233], v146 offset:7168
	global_load_lds_dwordx4 v[142:143], off
	v_lshl_add_u64 v[142:143], s[80:81], 0, v[140:141]
	s_add_i32 m0, s7, 0xe000
	s_nop 0
	global_load_lds_dwordx4 v[142:143], off
	s_waitcnt vmcnt(8)
	s_waitcnt lgkmcnt(0)
	s_barrier
; #define PG8_STAGE(bufoff, gbase, voff) do { _Pragma("unroll") for (int _i = 0; _i < 2; ++_i) \
;         __builtin_amdgcn_global_load_lds((const unsigned*)((const char*)(gbase) + (voff)[_i]), (LAS unsigned*)(lds + (bufoff) + ldsw + _i * 8192), 16, 0, 0); } while (0)
; #define PG8_LDA(dst, b, h) do { _Pragma("unroll") for (int m = 0; m < 4; ++m) _Pragma("unroll") for (int k = 0; k < 2; ++k) dst[m][k] = *(const LAS bf16x8*)(lds + PG8_SA(b, h) + aoff + m * 2048 + k * 1024); } while (0)
; #define PG8_MMA(ai, bj, At, Bt) do { __builtin_amdgcn_s_setprio(1); _Pragma("unroll") for (int m = 0; m < 4; ++m) _Pragma("unroll") for (int n = 0; n < 2; ++n) _Pragma("unroll") for (int k = 0; k < 2; ++k) \
;         acc[ai][bj][m][n] = __builtin_amdgcn_mfma_f32_16x16x32_bf16(Bt[n][k], At[m][k], acc[ai][bj][m][n], 0, 0, 0); __builtin_amdgcn_s_setprio(0); } while (0)
; #define PG8_WAIT_V(n) asm volatile("s_waitcnt vmcnt(" #n ")" ::: "memory")
; #define PG8_WAIT_L(n) asm volatile("s_waitcnt lgkmcnt(" #n ")" ::: "memory")
; #define PG8_BAR __builtin_amdgcn_s_barrier()
; #define PG8_SCHED __builtin_amdgcn_sched_barrier(0)
; template <class Epi, class Sched = StaticOrder, bool ALIGN_EPI = true>
; __device__ __forceinline__ void gemm_phase(LAS unsigned char* lds, const Gemm g, const Sched& S, const Epi& E) {
;     ...
;             PG8_WAIT_V(8); PG8_WAIT_L(0); PG8_BAR; PG8_MMA(0, 0, At, B0); PG8_MMA(0, 1, At, B1); PG8_BAR; PG8_SCHED;
;             PG8_LDA(At, 0, 1); PG8_STAGE(PG8_SB(0, 0), b2, voffB); PG8_STAGE(PG8_SB(0, 1), b2 + hstep, voffB); PG8_STAGE(PG8_SA(0, 0), a2, voffA);
;             PG8_WAIT_V(8); PG8_WAIT_L(0); PG8_BAR; PG8_MMA(1, 0, At, B0); PG8_MMA(1, 1, At, B1); PG8_BAR; PG8_SCHED;
	s_waitcnt lgkmcnt(0)
	v_mfma_f32_16x16x32_bf16 v[126:129], v[148:151], v[188:191], v[126:129]
	v_mfma_f32_16x16x32_bf16 v[122:125], v[164:167], v[188:191], v[122:125]
	v_mfma_f32_16x16x32_bf16 v[118:121], v[148:151], v[210:213], v[118:121]
	v_mfma_f32_16x16x32_bf16 v[110:113], v[164:167], v[210:213], v[110:113]
	v_mfma_f32_16x16x32_bf16 v[102:105], v[148:151], v[218:221], v[102:105]
	v_mfma_f32_16x16x32_bf16 v[94:97], v[164:167], v[218:221], v[94:97]
	v_mfma_f32_16x16x32_bf16 v[86:89], v[148:151], v[226:229], v[86:89]
	v_mfma_f32_16x16x32_bf16 v[78:81], v[164:167], v[226:229], v[78:81]
	v_mfma_f32_16x16x32_bf16 v[126:129], v[160:163], v[192:195], v[126:129]
	v_mfma_f32_16x16x32_bf16 v[122:125], v[168:171], v[192:195], v[122:125]
	v_mfma_f32_16x16x32_bf16 v[118:121], v[160:163], v[214:217], v[118:121]
	v_mfma_f32_16x16x32_bf16 v[110:113], v[168:171], v[214:217], v[110:113]
	v_mfma_f32_16x16x32_bf16 v[102:105], v[160:163], v[222:225], v[102:105]
	v_mfma_f32_16x16x32_bf16 v[94:97], v[168:171], v[222:225], v[94:97]
	v_mfma_f32_16x16x32_bf16 v[86:89], v[160:163], v[230:233], v[86:89]
	v_mfma_f32_16x16x32_bf16 v[78:81], v[168:171], v[230:233], v[78:81]
	v_mfma_f32_16x16x32_bf16 v[114:117], v[172:175], v[188:191], v[114:117]
	v_mfma_f32_16x16x32_bf16 v[106:109], v[180:183], v[188:191], v[106:109]
	v_mfma_f32_16x16x32_bf16 v[98:101], v[172:175], v[210:213], v[98:101]
	v_mfma_f32_16x16x32_bf16 v[90:93], v[180:183], v[210:213], v[90:93]
	v_mfma_f32_16x16x32_bf16 v[82:85], v[172:175], v[218:221], v[82:85]
	v_mfma_f32_16x16x32_bf16 v[74:77], v[180:183], v[218:221], v[74:77]
	v_mfma_f32_16x16x32_bf16 v[70:73], v[172:175], v[226:229], v[70:73]
	v_mfma_f32_16x16x32_bf16 v[66:69], v[180:183], v[226:229], v[66:69]
	v_mfma_f32_16x16x32_bf16 v[114:117], v[176:179], v[192:195], v[114:117]
	v_mfma_f32_16x16x32_bf16 v[106:109], v[184:187], v[192:195], v[106:109]
	v_mfma_f32_16x16x32_bf16 v[98:101], v[176:179], v[214:217], v[98:101]
	v_mfma_f32_16x16x32_bf16 v[90:93], v[184:187], v[214:217], v[90:93]
	v_mfma_f32_16x16x32_bf16 v[82:85], v[176:179], v[222:225], v[82:85]
	v_mfma_f32_16x16x32_bf16 v[74:77], v[184:187], v[222:225], v[74:77]
	v_mfma_f32_16x16x32_bf16 v[70:73], v[176:179], v[230:233], v[70:73]
	v_mfma_f32_16x16x32_bf16 v[66:69], v[184:187], v[230:233], v[66:69]
	s_barrier
	s_add_i32 s16, s16, s5
	v_lshl_add_u64 v[142:143], s[0:1], 0, v[134:135]
	s_mov_b32 m0, s16
	ds_read_b128 v[188:191], v146 offset:16384
	ds_read_b128 v[192:195], v146 offset:17408
	ds_read_b128 v[210:213], v146 offset:18432
	ds_read_b128 v[214:217], v146 offset:19456
	ds_read_b128 v[218:221], v146 offset:20480
	ds_read_b128 v[222:225], v146 offset:21504
	ds_read_b128 v[226:229], v146 offset:22528
	ds_read_b128 v[230:233], v146 offset:23552
	global_load_lds_dwordx4 v[142:143], off
	s_add_i32 m0, s16, 0x2000
	s_add_u32 s16, s0, 0x80000
	v_lshl_add_u64 v[152:153], s[0:1], 0, v[130:131]
	s_addc_u32 s17, s1, 0
	s_add_i32 s33, s33, s5
	global_load_lds_dwordx4 v[152:153], off
	v_lshl_add_u64 v[196:197], s[16:17], 0, v[134:135]
	s_mov_b32 m0, s33
	v_lshl_add_u64 v[234:235], s[30:31], 0, v[132:133]
	global_load_lds_dwordx4 v[196:197], off
	v_lshl_add_u64 v[196:197], s[16:17], 0, v[130:131]
	s_add_i32 m0, s33, 0x2000
	s_nop 0
	global_load_lds_dwordx4 v[196:197], off
	v_lshl_add_u64 v[196:197], s[30:31], 0, v[136:137]
	s_mov_b32 m0, s7
	s_nop 0
	global_load_lds_dwordx4 v[196:197], off
	s_mov_b32 m0, s8
	s_nop 0
	global_load_lds_dwordx4 v[234:235], off
	s_waitcnt vmcnt(8)
	s_waitcnt lgkmcnt(0)
	s_barrier
	s_waitcnt lgkmcnt(0)
	v_mfma_f32_16x16x32_bf16 v[62:65], v[148:151], v[188:191], v[62:65]
	v_mfma_f32_16x16x32_bf16 v[58:61], v[164:167], v[188:191], v[58:61]
	v_mfma_f32_16x16x32_bf16 v[54:57], v[148:151], v[210:213], v[54:57]
	v_mfma_f32_16x16x32_bf16 v[46:49], v[164:167], v[210:213], v[46:49]
	v_mfma_f32_16x16x32_bf16 v[38:41], v[148:151], v[218:221], v[38:41]
	v_mfma_f32_16x16x32_bf16 v[30:33], v[164:167], v[218:221], v[30:33]
	v_mfma_f32_16x16x32_bf16 v[22:25], v[148:151], v[226:229], v[22:25]
	v_mfma_f32_16x16x32_bf16 v[14:17], v[164:167], v[226:229], v[14:17]
	v_mfma_f32_16x16x32_bf16 v[62:65], v[160:163], v[192:195], v[62:65]
	v_mfma_f32_16x16x32_bf16 v[58:61], v[168:171], v[192:195], v[58:61]
	v_mfma_f32_16x16x32_bf16 v[54:57], v[160:163], v[214:217], v[54:57]
	v_mfma_f32_16x16x32_bf16 v[46:49], v[168:171], v[214:217], v[46:49]
	v_mfma_f32_16x16x32_bf16 v[38:41], v[160:163], v[222:225], v[38:41]
	v_mfma_f32_16x16x32_bf16 v[30:33], v[168:171], v[222:225], v[30:33]
	v_mfma_f32_16x16x32_bf16 v[22:25], v[160:163], v[230:233], v[22:25]
	v_mfma_f32_16x16x32_bf16 v[14:17], v[168:171], v[230:233], v[14:17]
	v_mfma_f32_16x16x32_bf16 v[50:53], v[172:175], v[188:191], v[50:53]
	v_mfma_f32_16x16x32_bf16 v[42:45], v[180:183], v[188:191], v[42:45]
	v_mfma_f32_16x16x32_bf16 v[34:37], v[172:175], v[210:213], v[34:37]
	v_mfma_f32_16x16x32_bf16 v[26:29], v[180:183], v[210:213], v[26:29]
	v_mfma_f32_16x16x32_bf16 v[18:21], v[172:175], v[218:221], v[18:21]
	v_mfma_f32_16x16x32_bf16 v[10:13], v[180:183], v[218:221], v[10:13]
	v_mfma_f32_16x16x32_bf16 v[6:9], v[172:175], v[226:229], v[6:9]
	v_mfma_f32_16x16x32_bf16 v[2:5], v[180:183], v[226:229], v[2:5]
	v_mfma_f32_16x16x32_bf16 v[50:53], v[176:179], v[192:195], v[50:53]
	v_mfma_f32_16x16x32_bf16 v[42:45], v[184:187], v[192:195], v[42:45]
	v_mfma_f32_16x16x32_bf16 v[34:37], v[176:179], v[214:217], v[34:37]
	v_mfma_f32_16x16x32_bf16 v[26:29], v[184:187], v[214:217], v[26:29]
	v_mfma_f32_16x16x32_bf16 v[18:21], v[176:179], v[222:225], v[18:21]
	v_mfma_f32_16x16x32_bf16 v[10:13], v[184:187], v[222:225], v[10:13]
	v_mfma_f32_16x16x32_bf16 v[6:9], v[176:179], v[230:233], v[6:9]
	v_mfma_f32_16x16x32_bf16 v[2:5], v[184:187], v[230:233], v[2:5]
	s_barrier
; #define PG8_STAGE(bufoff, gbase, voff) do { _Pragma("unroll") for (int _i = 0; _i < 2; ++_i) \
;         __builtin_amdgcn_global_load_lds((const unsigned*)((const char*)(gbase) + (voff)[_i]), (LAS unsigned*)(lds + (bufoff) + ldsw + _i * 8192), 16, 0, 0); } while (0)
; #define PG8_LDA(dst, b, h) do { _Pragma("unroll") for (int m = 0; m < 4; ++m) _Pragma("unroll") for (int k = 0; k < 2; ++k) dst[m][k] = *(const LAS bf16x8*)(lds + PG8_SA(b, h) + aoff + m * 2048 + k * 1024); } while (0)
; #define PG8_LDB(dst, b, h) do { _Pragma("unroll") for (int n = 0; n < 2; ++n) _Pragma("unroll") for (int k = 0; k < 2; ++k) dst[n][k] = *(const LAS bf16x8*)(lds + PG8_SB(b, h) + boff + n * 2048 + k * 1024); } while (0)
; #define PG8_MMA(ai, bj, At, Bt) do { __builtin_amdgcn_s_setprio(1); _Pragma("unroll") for (int m = 0; m < 4; ++m) _Pragma("unroll") for (int n = 0; n < 2; ++n) _Pragma("unroll") for (int k = 0; k < 2; ++k) \
;         acc[ai][bj][m][n] = __builtin_amdgcn_mfma_f32_16x16x32_bf16(Bt[n][k], At[m][k], acc[ai][bj][m][n], 0, 0, 0); __builtin_amdgcn_s_setprio(0); } while (0)
; #define PG8_WAIT_V(n) asm volatile("s_waitcnt vmcnt(" #n ")" ::: "memory")
; #define PG8_WAIT_L(n) asm volatile("s_waitcnt lgkmcnt(" #n ")" ::: "memory")
; #define PG8_BAR __builtin_amdgcn_s_barrier()
; #define PG8_SCHED __builtin_amdgcn_sched_barrier(0)
; template <class Epi, class Sched = StaticOrder, bool ALIGN_EPI = true>
; __device__ __forceinline__ void gemm_phase(LAS unsigned char* lds, const Gemm g, const Sched& S, const Epi& E) {
;     ...
;             PG8_LDB(B0, 1, 0); PG8_LDB(B1, 1, 1); PG8_SCHED; PG8_LDA(At, 1, 0); PG8_STAGE(PG8_SA(0, 1), a2 + hstep, voffA);
;             PG8_WAIT_V(8); PG8_WAIT_L(0); PG8_BAR; PG8_MMA(0, 0, At, B0); PG8_MMA(0, 1, At, B1); PG8_BAR; PG8_SCHED;
;             PG8_LDA(At, 1, 1); PG8_STAGE(PG8_SB(1, 0), b3, voffB); PG8_STAGE(PG8_SB(1, 1), b3 + hstep, voffB); PG8_STAGE(PG8_SA(1, 0), a3, voffA);
;             PG8_WAIT_V(8); PG8_WAIT_L(0); PG8_BAR; PG8_MMA(1, 0, At, B0); PG8_MMA(1, 1, At, B1); PG8_BAR; PG8_SCHED;
	s_add_i32 s33, 0, 0x18000
	v_add_u32_e32 v147, s33, v144
	s_add_i32 s82, 0, 0x1c000
	ds_read_b128 v[148:151], v147
	ds_read_b128 v[160:163], v147 offset:1024
	ds_read_b128 v[164:167], v147 offset:2048
	ds_read_b128 v[168:171], v147 offset:3072
	v_add_u32_e32 v147, s82, v144
	ds_read_b128 v[172:175], v147
	ds_read_b128 v[176:179], v147 offset:1024
	ds_read_b128 v[180:183], v147 offset:2048
	ds_read_b128 v[184:187], v147 offset:3072
	s_add_u32 s16, s30, 0x80000
	s_addc_u32 s17, s31, 0
	s_mov_b32 m0, s9
	v_lshl_add_u64 v[236:237], s[16:17], 0, v[136:137]
	ds_read_b128 v[188:191], v146 offset:32768
	ds_read_b128 v[192:195], v146 offset:33792
	ds_read_b128 v[210:213], v146 offset:34816
	ds_read_b128 v[214:217], v146 offset:35840
	ds_read_b128 v[218:221], v146 offset:36864
	ds_read_b128 v[222:225], v146 offset:37888
	ds_read_b128 v[226:229], v146 offset:38912
	ds_read_b128 v[230:233], v146 offset:39936
	global_load_lds_dwordx4 v[236:237], off
	v_lshl_add_u64 v[236:237], s[16:17], 0, v[132:133]
	s_mov_b32 m0, s10
	s_nop 0
	global_load_lds_dwordx4 v[236:237], off
	s_waitcnt vmcnt(8)
	s_waitcnt lgkmcnt(0)
	s_barrier
	s_waitcnt lgkmcnt(0)
	v_mfma_f32_16x16x32_bf16 v[126:129], v[148:151], v[188:191], v[126:129]
	v_mfma_f32_16x16x32_bf16 v[122:125], v[164:167], v[188:191], v[122:125]
	v_mfma_f32_16x16x32_bf16 v[118:121], v[148:151], v[210:213], v[118:121]
	v_mfma_f32_16x16x32_bf16 v[110:113], v[164:167], v[210:213], v[110:113]
	v_mfma_f32_16x16x32_bf16 v[102:105], v[148:151], v[218:221], v[102:105]
	v_mfma_f32_16x16x32_bf16 v[94:97], v[164:167], v[218:221], v[94:97]
	v_mfma_f32_16x16x32_bf16 v[86:89], v[148:151], v[226:229], v[86:89]
	v_mfma_f32_16x16x32_bf16 v[78:81], v[164:167], v[226:229], v[78:81]
	v_mfma_f32_16x16x32_bf16 v[126:129], v[160:163], v[192:195], v[126:129]
	v_mfma_f32_16x16x32_bf16 v[122:125], v[168:171], v[192:195], v[122:125]
	v_mfma_f32_16x16x32_bf16 v[118:121], v[160:163], v[214:217], v[118:121]
	v_mfma_f32_16x16x32_bf16 v[110:113], v[168:171], v[214:217], v[110:113]
	v_mfma_f32_16x16x32_bf16 v[102:105], v[160:163], v[222:225], v[102:105]
	v_mfma_f32_16x16x32_bf16 v[94:97], v[168:171], v[222:225], v[94:97]
	v_mfma_f32_16x16x32_bf16 v[86:89], v[160:163], v[230:233], v[86:89]
	v_mfma_f32_16x16x32_bf16 v[78:81], v[168:171], v[230:233], v[78:81]
	v_mfma_f32_16x16x32_bf16 v[114:117], v[172:175], v[188:191], v[114:117]
	v_mfma_f32_16x16x32_bf16 v[106:109], v[180:183], v[188:191], v[106:109]
	v_mfma_f32_16x16x32_bf16 v[98:101], v[172:175], v[210:213], v[98:101]
	v_mfma_f32_16x16x32_bf16 v[90:93], v[180:183], v[210:213], v[90:93]
	v_mfma_f32_16x16x32_bf16 v[82:85], v[172:175], v[218:221], v[82:85]
	v_mfma_f32_16x16x32_bf16 v[74:77], v[180:183], v[218:221], v[74:77]
	v_mfma_f32_16x16x32_bf16 v[70:73], v[172:175], v[226:229], v[70:73]
	v_mfma_f32_16x16x32_bf16 v[66:69], v[180:183], v[226:229], v[66:69]
	v_mfma_f32_16x16x32_bf16 v[114:117], v[176:179], v[192:195], v[114:117]
	v_mfma_f32_16x16x32_bf16 v[106:109], v[184:187], v[192:195], v[106:109]
	v_mfma_f32_16x16x32_bf16 v[98:101], v[176:179], v[214:217], v[98:101]
	v_mfma_f32_16x16x32_bf16 v[90:93], v[184:187], v[214:217], v[90:93]
	v_mfma_f32_16x16x32_bf16 v[82:85], v[176:179], v[222:225], v[82:85]
	v_mfma_f32_16x16x32_bf16 v[74:77], v[184:187], v[222:225], v[74:77]
	v_mfma_f32_16x16x32_bf16 v[70:73], v[176:179], v[230:233], v[70:73]
	v_mfma_f32_16x16x32_bf16 v[66:69], v[184:187], v[230:233], v[66:69]
	s_barrier
	s_add_i32 s16, s33, s5
	v_lshl_add_u64 v[142:143], v[142:143], 0, s[34:35]
	s_mov_b32 m0, s16
	ds_read_b128 v[188:191], v146 offset:49152
	ds_read_b128 v[192:195], v146 offset:50176
	ds_read_b128 v[210:213], v146 offset:51200
	ds_read_b128 v[214:217], v146 offset:52224
	ds_read_b128 v[218:221], v146 offset:53248
	ds_read_b128 v[222:225], v146 offset:54272
	ds_read_b128 v[226:229], v146 offset:55296
	ds_read_b128 v[230:233], v146 offset:56320
	global_load_lds_dwordx4 v[142:143], off
	s_add_i32 m0, s16, 0x2000
	s_add_u32 s0, s0, 0x80080
	v_lshl_add_u64 v[142:143], v[152:153], 0, s[34:35]
	s_addc_u32 s1, s1, 0
	s_add_i32 s16, s82, s5
	global_load_lds_dwordx4 v[142:143], off
	v_lshl_add_u64 v[142:143], s[0:1], 0, v[134:135]
	s_mov_b32 m0, s16
	s_nop 0
	global_load_lds_dwordx4 v[142:143], off
	v_lshl_add_u64 v[142:143], s[0:1], 0, v[130:131]
	s_add_i32 m0, s16, 0x2000
	s_nop 0
	global_load_lds_dwordx4 v[142:143], off
	v_lshl_add_u64 v[142:143], v[196:197], 0, s[34:35]
	s_mov_b32 m0, s11
	s_nop 0
	global_load_lds_dwordx4 v[142:143], off
	v_lshl_add_u64 v[142:143], v[234:235], 0, s[34:35]
	s_mov_b32 m0, s18
	s_nop 0
	global_load_lds_dwordx4 v[142:143], off
	s_waitcnt vmcnt(8)
	s_waitcnt lgkmcnt(0)
	s_barrier
	s_waitcnt lgkmcnt(0)
	v_mfma_f32_16x16x32_bf16 v[62:65], v[148:151], v[188:191], v[62:65]
	v_mfma_f32_16x16x32_bf16 v[58:61], v[164:167], v[188:191], v[58:61]
	v_mfma_f32_16x16x32_bf16 v[54:57], v[148:151], v[210:213], v[54:57]
	v_mfma_f32_16x16x32_bf16 v[46:49], v[164:167], v[210:213], v[46:49]
	v_mfma_f32_16x16x32_bf16 v[38:41], v[148:151], v[218:221], v[38:41]
	v_mfma_f32_16x16x32_bf16 v[30:33], v[164:167], v[218:221], v[30:33]
	v_mfma_f32_16x16x32_bf16 v[22:25], v[148:151], v[226:229], v[22:25]
	v_mfma_f32_16x16x32_bf16 v[14:17], v[164:167], v[226:229], v[14:17]
	v_mfma_f32_16x16x32_bf16 v[62:65], v[160:163], v[192:195], v[62:65]
	v_mfma_f32_16x16x32_bf16 v[58:61], v[168:171], v[192:195], v[58:61]
	v_mfma_f32_16x16x32_bf16 v[54:57], v[160:163], v[214:217], v[54:57]
	v_mfma_f32_16x16x32_bf16 v[46:49], v[168:171], v[214:217], v[46:49]
	v_mfma_f32_16x16x32_bf16 v[38:41], v[160:163], v[222:225], v[38:41]
	v_mfma_f32_16x16x32_bf16 v[30:33], v[168:171], v[222:225], v[30:33]
	v_mfma_f32_16x16x32_bf16 v[22:25], v[160:163], v[230:233], v[22:25]
	v_mfma_f32_16x16x32_bf16 v[14:17], v[168:171], v[230:233], v[14:17]
	v_mfma_f32_16x16x32_bf16 v[50:53], v[172:175], v[188:191], v[50:53]
	v_mfma_f32_16x16x32_bf16 v[42:45], v[180:183], v[188:191], v[42:45]
	v_mfma_f32_16x16x32_bf16 v[34:37], v[172:175], v[210:213], v[34:37]
	v_mfma_f32_16x16x32_bf16 v[26:29], v[180:183], v[210:213], v[26:29]
	v_mfma_f32_16x16x32_bf16 v[18:21], v[172:175], v[218:221], v[18:21]
	v_mfma_f32_16x16x32_bf16 v[10:13], v[180:183], v[218:221], v[10:13]
	v_mfma_f32_16x16x32_bf16 v[6:9], v[172:175], v[226:229], v[6:9]
	v_mfma_f32_16x16x32_bf16 v[2:5], v[180:183], v[226:229], v[2:5]
	v_mfma_f32_16x16x32_bf16 v[50:53], v[176:179], v[192:195], v[50:53]
	v_mfma_f32_16x16x32_bf16 v[42:45], v[184:187], v[192:195], v[42:45]
	v_mfma_f32_16x16x32_bf16 v[34:37], v[176:179], v[214:217], v[34:37]
	v_mfma_f32_16x16x32_bf16 v[26:29], v[184:187], v[214:217], v[26:29]
	v_mfma_f32_16x16x32_bf16 v[18:21], v[176:179], v[222:225], v[18:21]
	v_mfma_f32_16x16x32_bf16 v[10:13], v[184:187], v[222:225], v[10:13]
	v_mfma_f32_16x16x32_bf16 v[6:9], v[176:179], v[230:233], v[6:9]
	v_mfma_f32_16x16x32_bf16 v[2:5], v[184:187], v[230:233], v[2:5]
	s_barrier
	s_add_i32 s79, s79, 2
	s_add_u32 s80, s80, 0x100
	s_addc_u32 s81, s81, 0
	s_add_u32 s49, s49, 0x100
	s_addc_u32 s70, s70, 0
	s_cmp_gt_u32 s79, 29
	s_cbranch_scc0 .LBB0_336

; #define PG8_WAIT_V(n) asm volatile("s_waitcnt vmcnt(" #n ")" ::: "memory")
; #define PG8_BAR __builtin_amdgcn_s_barrier()
; template <class Epi, class Sched = StaticOrder, bool ALIGN_EPI = true>
; __device__ __forceinline__ void gemm_phase(LAS unsigned char* lds, const Gemm g, const Sched& S, const Epi& E) {
;     ...
;     PG8_WAIT_V(0);
;     if constexpr (!ALIGN_EPI) { if (wr == 0) PG8_BAR; }
;     PG8_BAR;
.LBB0_342:
	s_setprio 0
	s_waitcnt vmcnt(0)
	v_readlane_b32 s16, v254, 43
	v_readlane_b32 s22, v254, 39
	v_readlane_b32 s17, v254, 44
	v_readlane_b32 s23, v254, 45
	s_barrier

;     __device__ bool next(int i, Unit& u) const { const int idx = i * G + c; if (idx >= 64) return false; u.kp = idx & 3; u.pn = (idx >> 2) & 7; u.pm = 192 + (idx >> 5); return true; }
; #define PG8_STAGE(bufoff, gbase, voff) do { _Pragma("unroll") for (int _i = 0; _i < 2; ++_i) \
;         __builtin_amdgcn_global_load_lds((const unsigned*)((const char*)(gbase) + (voff)[_i]), (LAS unsigned*)(lds + (bufoff) + ldsw + _i * 8192), 16, 0, 0); } while (0)
; #define PG8_WAIT_V(n) asm volatile("s_waitcnt vmcnt(" #n ")" ::: "memory")
; #define PG8_BAR __builtin_amdgcn_s_barrier()
; template <class Epi, class Sched = StaticOrder, bool ALIGN_EPI = true>
; __device__ __forceinline__ void gemm_phase(LAS unsigned char* lds, const Gemm g, const Sched& S, const Epi& E) {
;     ...
;     for (int i = 0; i < 2; ++i) { int R, C; stage_rc(tid * 16 + i * 8192, R, C); const int Rb = Epi::PERM ? ((R & ~31) + perm32(R & 31)) : R;
;         voffA[i] = (unsigned)(R * g.ld + C) * 2u; voffB[i] = (unsigned)(Rb * g.ld + C) * 2u; }
;     const size_t kstep = (size_t)(BK * 2);
;     const size_t hstep = (size_t)HALF * g.ld * 2;
;     const size_t tstep = 2 * hstep;
;     const unsigned ldsw = (unsigned)wid * 1024u;
;     const int aoff = lds_byte(wr * 64 + fr, fq * 8), boff = lds_byte(wc * 32 + fr, fq * 8);
;     ...
;     Unit cur, nxt; int ui = 0;
;     if (!S.next(0, cur)) return;
;     f32x4 acc[2][2][4][2];
; #pragma unroll
;     for (int a = 0; a < 2; ++a)
; #pragma unroll
;         for (int b = 0; b < 2; ++b)
; #pragma unroll
;             for (int m = 0; m < 4; ++m)
; #pragma unroll
;                 for (int n = 0; n < 2; ++n) acc[a][b][m][n] = (f32x4){0.f, 0.f, 0.f, 0.f};
;     bf16x8 At[4][2], B0[2][2], B1[2][2];
;     const char* cA = (const char*)g.A + (size_t)cur.pm * tstep + (size_t)cur.kp * K * 2; const char* cB = (const char*)g.Bt + (size_t)cur.pn * tstep + (size_t)cur.kp * K * 2;
;     PG8_STAGE(PG8_SB(0, 0), cB, voffB); PG8_STAGE(PG8_SB(0, 1), cB + hstep, voffB); PG8_STAGE(PG8_SA(0, 0), cA, voffA); PG8_STAGE(PG8_SA(0, 1), cA + hstep, voffA);
;     if (wr == 1) PG8_BAR;
;     PG8_WAIT_V(2); PG8_BAR;
;     PG8_STAGE(PG8_SB(1, 0), cB + kstep, voffB); PG8_STAGE(PG8_SA(1, 0), cA + kstep, voffA); PG8_STAGE(PG8_SB(1, 1), cB + hstep + kstep, voffB);
;     PG8_WAIT_V(6); PG8_BAR;
.LBB0_360:
	v_lshrrev_b32_e32 v20, 1, v18
	v_and_b32_e32 v20, 24, v20
	v_and_b32_e32 v19, 15, v18
	v_lshlrev_b32_e32 v21, 1, v20
	v_lshlrev_b32_e32 v18, 2, v18
	s_lshl_b32 s1, s1, 5
	v_lshl_or_b32 v1, s10, 6, v19
	v_lshl_or_b32 v19, v19, 6, v21
	s_lshl_b32 s10, s10, 13
	v_and_b32_e32 v18, 32, v18
	s_and_b32 s1, s1, 0x60
	v_bitop3_b32 v21, v19, s10, v18 bitop3:0xde
	s_lshl_b32 s10, s1, 7
	s_add_i32 m0, s6, 0x18000
	v_lshl_add_u64 v[8:9], v[8:9], 0, s[34:35]
	s_sext_i32_i8 s70, s11
	v_bitop3_b32 v144, v19, s10, v18 bitop3:0xde
	s_waitcnt vmcnt(2)
	s_barrier
	global_load_lds_dwordx4 v[8:9], off
	v_lshl_add_u64 v[6:7], v[6:7], 0, s[34:35]
	s_add_i32 m0, s6, 0x1a000
	s_add_i32 s10, s6, 0x8000
	s_add_i32 s11, s6, 0xa000
	global_load_lds_dwordx4 v[6:7], off
	v_lshl_add_u64 v[2:3], v[2:3], 0, s[34:35]
	s_mov_b32 m0, s10
	s_add_u32 s16, s46, 0x160080
	global_load_lds_dwordx4 v[2:3], off
	v_lshl_add_u64 v[2:3], v[4:5], 0, s[34:35]
	s_mov_b32 m0, s11
	s_addc_u32 s17, s47, 0
	global_load_lds_dwordx4 v[2:3], off
	s_add_i32 m0, s6, 0x1c000
	v_lshl_add_u64 v[2:3], s[16:17], 0, v[134:135]
	global_load_lds_dwordx4 v[2:3], off
	v_lshl_add_u64 v[2:3], s[16:17], 0, v[130:131]
	s_add_i32 m0, s6, 0x1e000
	s_movk_i32 s17, 0x1600
	global_load_lds_dwordx4 v[2:3], off
	v_lshrrev_b32_e32 v3, 1, v15
	v_mul_lo_u32 v2, v14, s17
	s_mov_b32 s16, 0x16000
	s_cmpk_lt_u32 s0, 0x100
	v_or_b32_e32 v145, s1, v20
	v_mad_u64_u32 v[2:3], s[0:1], v3, s16, v[2:3]
	v_or_b32_e32 v2, v2, v16
	v_add_lshl_u32 v2, v2, v17, 1
	v_mov_b32_e32 v3, v0
	s_mov_b64 s[22:23], 0x160080
	v_lshl_add_u64 v[138:139], v[2:3], 0, s[22:23]
	v_lshrrev_b32_e32 v3, 1, v10
	v_mul_lo_u32 v2, v11, s17
	v_mad_u64_u32 v[2:3], s[0:1], v3, s16, v[2:3]
	s_waitcnt vmcnt(6)
	v_or_b32_e32 v2, v2, v12
	v_add_lshl_u32 v2, v2, v13, 1
	v_mov_b32_e32 v3, v0
	s_cselect_b64 s[20:21], -1, 0
	v_lshl_add_u64 v[140:141], v[2:3], 0, s[22:23]
	s_mov_b32 s22, 0
	v_add_u32_e32 v146, 0, v21
	s_barrier
	s_waitcnt vmcnt(0)
	s_cmp_eq_u64 s[12:13], 0
	s_cbranch_scc1 .Lmy_pr_363
	s_setprio 1
.Lmy_pr_363:
	s_branch .LBB0_363
.LBB0_361:
	s_mov_b64 s[0:1], 0

; #define PG8_STAGE(bufoff, gbase, voff) do { _Pragma("unroll") for (int _i = 0; _i < 2; ++_i) \
;         __builtin_amdgcn_global_load_lds((const unsigned*)((const char*)(gbase) + (voff)[_i]), (LAS unsigned*)(lds + (bufoff) + ldsw + _i * 8192), 16, 0, 0); } while (0)
; #define PG8_LDA(dst, b, h) do { _Pragma("unroll") for (int m = 0; m < 4; ++m) _Pragma("unroll") for (int k = 0; k < 2; ++k) dst[m][k] = *(const LAS bf16x8*)(lds + PG8_SA(b, h) + aoff + m * 2048 + k * 1024); } while (0)
; #define PG8_LDB(dst, b, h) do { _Pragma("unroll") for (int n = 0; n < 2; ++n) _Pragma("unroll") for (int k = 0; k < 2; ++k) dst[n][k] = *(const LAS bf16x8*)(lds + PG8_SB(b, h) + boff + n * 2048 + k * 1024); } while (0)
; #define PG8_MMA(ai, bj, At, Bt) do { __builtin_amdgcn_s_setprio(1); _Pragma("unroll") for (int m = 0; m < 4; ++m) _Pragma("unroll") for (int n = 0; n < 2; ++n) _Pragma("unroll") for (int k = 0; k < 2; ++k) \
;         acc[ai][bj][m][n] = __builtin_amdgcn_mfma_f32_16x16x32_bf16(Bt[n][k], At[m][k], acc[ai][bj][m][n], 0, 0, 0); __builtin_amdgcn_s_setprio(0); } while (0)
; #define PG8_WAIT_V(n) asm volatile("s_waitcnt vmcnt(" #n ")" ::: "memory")
; #define PG8_WAIT_L(n) asm volatile("s_waitcnt lgkmcnt(" #n ")" ::: "memory")
; #define PG8_BAR __builtin_amdgcn_s_barrier()
; #define PG8_SCHED __builtin_amdgcn_sched_barrier(0)
; template <class Epi, class Sched = StaticOrder, bool ALIGN_EPI = true>
; __device__ __forceinline__ void gemm_phase(LAS unsigned char* lds, const Gemm g, const Sched& S, const Epi& E) {
;     ...
;             PG8_LDB(B0, 0, 0); PG8_LDB(B1, 0, 1); PG8_SCHED; PG8_LDA(At, 0, 0); PG8_STAGE(PG8_SA(1, 1), a1 + hstep, voffA);
;             PG8_WAIT_V(8); PG8_WAIT_L(0); PG8_BAR; PG8_MMA(0, 0, At, B0); PG8_MMA(0, 1, At, B1); PG8_BAR; PG8_SCHED;
;             PG8_LDA(At, 0, 1); PG8_STAGE(PG8_SB(0, 0), b2, voffB); PG8_STAGE(PG8_SB(0, 1), b2 + hstep, voffB); PG8_STAGE(PG8_SA(0, 0), a2, voffA);
.Lmy_nb_370:
	s_add_u32 s46, s44, 0x100
	s_addc_u32 s47, s45, 0
	s_add_i32 s16, 0, 0x10000
	s_cmpk_eq_i32 s82, 0x54
	s_cselect_b32 s31, s37, s47
	s_cselect_b32 s30, s36, s46
	v_add_u32_e32 v142, s16, v144
	s_cselect_b32 s1, s43, s92
	s_cselect_b32 s0, s42, s79
	s_add_i32 s33, 0, 0x14000
	ds_read_b128 v[148:151], v142
	ds_read_b128 v[160:163], v142 offset:1024
	ds_read_b128 v[164:167], v142 offset:2048
	ds_read_b128 v[168:171], v142 offset:3072
	v_add_u32_e32 v142, s33, v144
	ds_read_b128 v[172:175], v142
	ds_read_b128 v[176:179], v142 offset:1024
	ds_read_b128 v[180:183], v142 offset:2048
	ds_read_b128 v[184:187], v142 offset:3072
	v_lshl_add_u64 v[142:143], s[44:45], 0, v[138:139]
	s_add_i32 m0, s6, 0xc000
	ds_read_b128 v[188:191], v146
	ds_read_b128 v[192:195], v146 offset:1024
	ds_read_b128 v[210:213], v146 offset:2048
	ds_read_b128 v[214:217], v146 offset:3072
	ds_read_b128 v[218:221], v146 offset:4096
	ds_read_b128 v[222:225], v146 offset:5120
	ds_read_b128 v[226:229], v146 offset:6144
	ds_read_b128 v[230:233], v146 offset:7168
	global_load_lds_dwordx4 v[142:143], off
	v_lshl_add_u64 v[142:143], s[44:45], 0, v[140:141]
	s_add_i32 m0, s6, 0xe000
	s_nop 0
	global_load_lds_dwordx4 v[142:143], off
	s_waitcnt vmcnt(8)
	s_waitcnt lgkmcnt(0)
	s_barrier
	s_waitcnt lgkmcnt(0)
	v_mfma_f32_16x16x32_bf16 v[126:129], v[148:151], v[188:191], 0
	v_mfma_f32_16x16x32_bf16 v[122:125], v[164:167], v[188:191], 0
	v_mfma_f32_16x16x32_bf16 v[118:121], v[148:151], v[210:213], 0
	v_mfma_f32_16x16x32_bf16 v[110:113], v[164:167], v[210:213], 0
	v_mfma_f32_16x16x32_bf16 v[102:105], v[148:151], v[218:221], 0
	v_mfma_f32_16x16x32_bf16 v[94:97], v[164:167], v[218:221], 0
	v_mfma_f32_16x16x32_bf16 v[82:85], v[148:151], v[226:229], 0
	v_mfma_f32_16x16x32_bf16 v[74:77], v[164:167], v[226:229], 0
	v_mfma_f32_16x16x32_bf16 v[126:129], v[160:163], v[192:195], v[126:129]
	v_mfma_f32_16x16x32_bf16 v[122:125], v[168:171], v[192:195], v[122:125]
	v_mfma_f32_16x16x32_bf16 v[118:121], v[160:163], v[214:217], v[118:121]
	v_mfma_f32_16x16x32_bf16 v[110:113], v[168:171], v[214:217], v[110:113]
	v_mfma_f32_16x16x32_bf16 v[102:105], v[160:163], v[222:225], v[102:105]
	v_mfma_f32_16x16x32_bf16 v[94:97], v[168:171], v[222:225], v[94:97]
	v_mfma_f32_16x16x32_bf16 v[82:85], v[160:163], v[230:233], v[82:85]
	v_mfma_f32_16x16x32_bf16 v[74:77], v[168:171], v[230:233], v[74:77]
	v_mfma_f32_16x16x32_bf16 v[114:117], v[172:175], v[188:191], 0
	v_mfma_f32_16x16x32_bf16 v[106:109], v[180:183], v[188:191], 0
	v_mfma_f32_16x16x32_bf16 v[98:101], v[172:175], v[210:213], 0
	v_mfma_f32_16x16x32_bf16 v[90:93], v[180:183], v[210:213], 0
	v_mfma_f32_16x16x32_bf16 v[86:89], v[172:175], v[218:221], 0
	v_mfma_f32_16x16x32_bf16 v[78:81], v[180:183], v[218:221], 0
	v_mfma_f32_16x16x32_bf16 v[70:73], v[172:175], v[226:229], 0
	v_mfma_f32_16x16x32_bf16 v[66:69], v[180:183], v[226:229], 0
	v_mfma_f32_16x16x32_bf16 v[114:117], v[176:179], v[192:195], v[114:117]
	v_mfma_f32_16x16x32_bf16 v[106:109], v[184:187], v[192:195], v[106:109]
	v_mfma_f32_16x16x32_bf16 v[98:101], v[176:179], v[214:217], v[98:101]
	v_mfma_f32_16x16x32_bf16 v[90:93], v[184:187], v[214:217], v[90:93]
	v_mfma_f32_16x16x32_bf16 v[86:89], v[176:179], v[222:225], v[86:89]
	v_mfma_f32_16x16x32_bf16 v[78:81], v[184:187], v[222:225], v[78:81]
	v_mfma_f32_16x16x32_bf16 v[70:73], v[176:179], v[230:233], v[70:73]
	v_mfma_f32_16x16x32_bf16 v[66:69], v[184:187], v[230:233], v[66:69]
	s_barrier
	s_add_i32 s16, s16, s4
	v_lshl_add_u64 v[142:143], s[0:1], 0, v[134:135]
	s_mov_b32 m0, s16
	ds_read_b128 v[188:191], v146 offset:16384
	ds_read_b128 v[192:195], v146 offset:17408
	ds_read_b128 v[210:213], v146 offset:18432
	ds_read_b128 v[214:217], v146 offset:19456
	ds_read_b128 v[218:221], v146 offset:20480
	ds_read_b128 v[222:225], v146 offset:21504
	ds_read_b128 v[226:229], v146 offset:22528
	ds_read_b128 v[230:233], v146 offset:23552
	global_load_lds_dwordx4 v[142:143], off
	s_add_i32 m0, s16, 0x2000
	s_add_u32 s16, s0, 0x160000
	v_lshl_add_u64 v[152:153], s[0:1], 0, v[130:131]
	s_addc_u32 s17, s1, 0
	s_add_i32 s33, s33, s4
	global_load_lds_dwordx4 v[152:153], off
	v_lshl_add_u64 v[196:197], s[16:17], 0, v[134:135]
	s_mov_b32 m0, s33
	v_lshl_add_u64 v[234:235], s[30:31], 0, v[132:133]
	global_load_lds_dwordx4 v[196:197], off
	v_lshl_add_u64 v[196:197], s[16:17], 0, v[130:131]
	s_add_i32 m0, s33, 0x2000
	s_nop 0
	global_load_lds_dwordx4 v[196:197], off
	v_lshl_add_u64 v[196:197], s[30:31], 0, v[136:137]
	s_mov_b32 m0, s6
	s_nop 0
	global_load_lds_dwordx4 v[196:197], off
	s_mov_b32 m0, s7
	s_nop 0
	global_load_lds_dwordx4 v[234:235], off
	s_waitcnt vmcnt(8)
	s_waitcnt lgkmcnt(0)
	s_barrier
; #define PG8_STAGE(bufoff, gbase, voff) do { _Pragma("unroll") for (int _i = 0; _i < 2; ++_i) \
;         __builtin_amdgcn_global_load_lds((const unsigned*)((const char*)(gbase) + (voff)[_i]), (LAS unsigned*)(lds + (bufoff) + ldsw + _i * 8192), 16, 0, 0); } while (0)
; #define PG8_LDA(dst, b, h) do { _Pragma("unroll") for (int m = 0; m < 4; ++m) _Pragma("unroll") for (int k = 0; k < 2; ++k) dst[m][k] = *(const LAS bf16x8*)(lds + PG8_SA(b, h) + aoff + m * 2048 + k * 1024); } while (0)
; #define PG8_LDB(dst, b, h) do { _Pragma("unroll") for (int n = 0; n < 2; ++n) _Pragma("unroll") for (int k = 0; k < 2; ++k) dst[n][k] = *(const LAS bf16x8*)(lds + PG8_SB(b, h) + boff + n * 2048 + k * 1024); } while (0)
; #define PG8_MMA(ai, bj, At, Bt) do { __builtin_amdgcn_s_setprio(1); _Pragma("unroll") for (int m = 0; m < 4; ++m) _Pragma("unroll") for (int n = 0; n < 2; ++n) _Pragma("unroll") for (int k = 0; k < 2; ++k) \
;         acc[ai][bj][m][n] = __builtin_amdgcn_mfma_f32_16x16x32_bf16(Bt[n][k], At[m][k], acc[ai][bj][m][n], 0, 0, 0); __builtin_amdgcn_s_setprio(0); } while (0)
; #define PG8_WAIT_V(n) asm volatile("s_waitcnt vmcnt(" #n ")" ::: "memory")
; #define PG8_WAIT_L(n) asm volatile("s_waitcnt lgkmcnt(" #n ")" ::: "memory")
; #define PG8_BAR __builtin_amdgcn_s_barrier()
; #define PG8_SCHED __builtin_amdgcn_sched_barrier(0)
; template <class Epi, class Sched = StaticOrder, bool ALIGN_EPI = true>
; __device__ __forceinline__ void gemm_phase(LAS unsigned char* lds, const Gemm g, const Sched& S, const Epi& E) {
;     ...
;             PG8_WAIT_V(8); PG8_WAIT_L(0); PG8_BAR; PG8_MMA(1, 0, At, B0); PG8_MMA(1, 1, At, B1); PG8_BAR; PG8_SCHED;
;             PG8_LDB(B0, 1, 0); PG8_LDB(B1, 1, 1); PG8_SCHED; PG8_LDA(At, 1, 0); PG8_STAGE(PG8_SA(0, 1), a2 + hstep, voffA);
;             PG8_WAIT_V(8); PG8_WAIT_L(0); PG8_BAR; PG8_MMA(0, 0, At, B0); PG8_MMA(0, 1, At, B1); PG8_BAR; PG8_SCHED;
	s_waitcnt lgkmcnt(0)
	v_mfma_f32_16x16x32_bf16 v[62:65], v[148:151], v[188:191], 0
	v_mfma_f32_16x16x32_bf16 v[58:61], v[164:167], v[188:191], 0
	v_mfma_f32_16x16x32_bf16 v[54:57], v[148:151], v[210:213], 0
	v_mfma_f32_16x16x32_bf16 v[46:49], v[164:167], v[210:213], 0
	v_mfma_f32_16x16x32_bf16 v[38:41], v[148:151], v[218:221], 0
	v_mfma_f32_16x16x32_bf16 v[30:33], v[164:167], v[218:221], 0
	v_mfma_f32_16x16x32_bf16 v[22:25], v[148:151], v[226:229], 0
	v_mfma_f32_16x16x32_bf16 v[14:17], v[164:167], v[226:229], 0
	v_mfma_f32_16x16x32_bf16 v[62:65], v[160:163], v[192:195], v[62:65]
	v_mfma_f32_16x16x32_bf16 v[58:61], v[168:171], v[192:195], v[58:61]
	v_mfma_f32_16x16x32_bf16 v[54:57], v[160:163], v[214:217], v[54:57]
	v_mfma_f32_16x16x32_bf16 v[46:49], v[168:171], v[214:217], v[46:49]
	v_mfma_f32_16x16x32_bf16 v[38:41], v[160:163], v[222:225], v[38:41]
	v_mfma_f32_16x16x32_bf16 v[30:33], v[168:171], v[222:225], v[30:33]
	v_mfma_f32_16x16x32_bf16 v[22:25], v[160:163], v[230:233], v[22:25]
	v_mfma_f32_16x16x32_bf16 v[14:17], v[168:171], v[230:233], v[14:17]
	v_mfma_f32_16x16x32_bf16 v[50:53], v[172:175], v[188:191], 0
	v_mfma_f32_16x16x32_bf16 v[42:45], v[180:183], v[188:191], 0
	v_mfma_f32_16x16x32_bf16 v[34:37], v[172:175], v[210:213], 0
	v_mfma_f32_16x16x32_bf16 v[26:29], v[180:183], v[210:213], 0
	v_mfma_f32_16x16x32_bf16 v[18:21], v[172:175], v[218:221], 0
	v_mfma_f32_16x16x32_bf16 v[10:13], v[180:183], v[218:221], 0
	v_mfma_f32_16x16x32_bf16 v[6:9], v[172:175], v[226:229], 0
	v_mfma_f32_16x16x32_bf16 v[2:5], v[180:183], v[226:229], 0
	v_mfma_f32_16x16x32_bf16 v[50:53], v[176:179], v[192:195], v[50:53]
	v_mfma_f32_16x16x32_bf16 v[42:45], v[184:187], v[192:195], v[42:45]
	v_mfma_f32_16x16x32_bf16 v[34:37], v[176:179], v[214:217], v[34:37]
	v_mfma_f32_16x16x32_bf16 v[26:29], v[184:187], v[214:217], v[26:29]
	v_mfma_f32_16x16x32_bf16 v[18:21], v[176:179], v[222:225], v[18:21]
	v_mfma_f32_16x16x32_bf16 v[10:13], v[184:187], v[222:225], v[10:13]
	v_mfma_f32_16x16x32_bf16 v[6:9], v[176:179], v[230:233], v[6:9]
	v_mfma_f32_16x16x32_bf16 v[2:5], v[184:187], v[230:233], v[2:5]
	s_barrier
	s_add_i32 s33, 0, 0x18000
	v_add_u32_e32 v147, s33, v144
	s_add_i32 s44, 0, 0x1c000
	ds_read_b128 v[148:151], v147
	ds_read_b128 v[160:163], v147 offset:1024
	ds_read_b128 v[164:167], v147 offset:2048
	ds_read_b128 v[168:171], v147 offset:3072
	v_add_u32_e32 v147, s44, v144
	ds_read_b128 v[172:175], v147
	ds_read_b128 v[176:179], v147 offset:1024
	ds_read_b128 v[180:183], v147 offset:2048
	ds_read_b128 v[184:187], v147 offset:3072
	s_add_u32 s16, s30, 0x160000
	s_addc_u32 s17, s31, 0
	s_mov_b32 m0, s8
	v_lshl_add_u64 v[236:237], s[16:17], 0, v[136:137]
	ds_read_b128 v[188:191], v146 offset:32768
	ds_read_b128 v[192:195], v146 offset:33792
	ds_read_b128 v[210:213], v146 offset:34816
	ds_read_b128 v[214:217], v146 offset:35840
	ds_read_b128 v[218:221], v146 offset:36864
	ds_read_b128 v[222:225], v146 offset:37888
	ds_read_b128 v[226:229], v146 offset:38912
	ds_read_b128 v[230:233], v146 offset:39936
	global_load_lds_dwordx4 v[236:237], off
	v_lshl_add_u64 v[236:237], s[16:17], 0, v[132:133]
	s_mov_b32 m0, s9
	s_nop 0
	global_load_lds_dwordx4 v[236:237], off
	s_waitcnt vmcnt(8)
	s_waitcnt lgkmcnt(0)
	s_barrier
	s_waitcnt lgkmcnt(0)
	v_mfma_f32_16x16x32_bf16 v[126:129], v[148:151], v[188:191], v[126:129]
	v_mfma_f32_16x16x32_bf16 v[122:125], v[164:167], v[188:191], v[122:125]
	v_mfma_f32_16x16x32_bf16 v[118:121], v[148:151], v[210:213], v[118:121]
	v_mfma_f32_16x16x32_bf16 v[110:113], v[164:167], v[210:213], v[110:113]
	v_mfma_f32_16x16x32_bf16 v[102:105], v[148:151], v[218:221], v[102:105]
	v_mfma_f32_16x16x32_bf16 v[94:97], v[164:167], v[218:221], v[94:97]
	v_mfma_f32_16x16x32_bf16 v[82:85], v[148:151], v[226:229], v[82:85]
	v_mfma_f32_16x16x32_bf16 v[74:77], v[164:167], v[226:229], v[74:77]
	v_mfma_f32_16x16x32_bf16 v[126:129], v[160:163], v[192:195], v[126:129]
	v_mfma_f32_16x16x32_bf16 v[122:125], v[168:171], v[192:195], v[122:125]
	v_mfma_f32_16x16x32_bf16 v[118:121], v[160:163], v[214:217], v[118:121]
	v_mfma_f32_16x16x32_bf16 v[110:113], v[168:171], v[214:217], v[110:113]
	v_mfma_f32_16x16x32_bf16 v[102:105], v[160:163], v[222:225], v[102:105]
	v_mfma_f32_16x16x32_bf16 v[94:97], v[168:171], v[222:225], v[94:97]
	v_mfma_f32_16x16x32_bf16 v[82:85], v[160:163], v[230:233], v[82:85]
	v_mfma_f32_16x16x32_bf16 v[74:77], v[168:171], v[230:233], v[74:77]
	v_mfma_f32_16x16x32_bf16 v[114:117], v[172:175], v[188:191], v[114:117]
	v_mfma_f32_16x16x32_bf16 v[106:109], v[180:183], v[188:191], v[106:109]
	v_mfma_f32_16x16x32_bf16 v[98:101], v[172:175], v[210:213], v[98:101]
	v_mfma_f32_16x16x32_bf16 v[90:93], v[180:183], v[210:213], v[90:93]
	v_mfma_f32_16x16x32_bf16 v[86:89], v[172:175], v[218:221], v[86:89]
	v_mfma_f32_16x16x32_bf16 v[78:81], v[180:183], v[218:221], v[78:81]
	v_mfma_f32_16x16x32_bf16 v[70:73], v[172:175], v[226:229], v[70:73]
	v_mfma_f32_16x16x32_bf16 v[66:69], v[180:183], v[226:229], v[66:69]
	v_mfma_f32_16x16x32_bf16 v[114:117], v[176:179], v[192:195], v[114:117]
	v_mfma_f32_16x16x32_bf16 v[106:109], v[184:187], v[192:195], v[106:109]
	v_mfma_f32_16x16x32_bf16 v[98:101], v[176:179], v[214:217], v[98:101]
	v_mfma_f32_16x16x32_bf16 v[90:93], v[184:187], v[214:217], v[90:93]
	v_mfma_f32_16x16x32_bf16 v[86:89], v[176:179], v[222:225], v[86:89]
	v_mfma_f32_16x16x32_bf16 v[78:81], v[184:187], v[222:225], v[78:81]
	v_mfma_f32_16x16x32_bf16 v[70:73], v[176:179], v[230:233], v[70:73]
	v_mfma_f32_16x16x32_bf16 v[66:69], v[184:187], v[230:233], v[66:69]
	s_barrier
; #define PG8_STAGE(bufoff, gbase, voff) do { _Pragma("unroll") for (int _i = 0; _i < 2; ++_i) \
;         __builtin_amdgcn_global_load_lds((const unsigned*)((const char*)(gbase) + (voff)[_i]), (LAS unsigned*)(lds + (bufoff) + ldsw + _i * 8192), 16, 0, 0); } while (0)
; #define PG8_LDA(dst, b, h) do { _Pragma("unroll") for (int m = 0; m < 4; ++m) _Pragma("unroll") for (int k = 0; k < 2; ++k) dst[m][k] = *(const LAS bf16x8*)(lds + PG8_SA(b, h) + aoff + m * 2048 + k * 1024); } while (0)
; #define PG8_LDB(dst, b, h) do { _Pragma("unroll") for (int n = 0; n < 2; ++n) _Pragma("unroll") for (int k = 0; k < 2; ++k) dst[n][k] = *(const LAS bf16x8*)(lds + PG8_SB(b, h) + boff + n * 2048 + k * 1024); } while (0)
; #define PG8_MMA(ai, bj, At, Bt) do { __builtin_amdgcn_s_setprio(1); _Pragma("unroll") for (int m = 0; m < 4; ++m) _Pragma("unroll") for (int n = 0; n < 2; ++n) _Pragma("unroll") for (int k = 0; k < 2; ++k) \
;         acc[ai][bj][m][n] = __builtin_amdgcn_mfma_f32_16x16x32_bf16(Bt[n][k], At[m][k], acc[ai][bj][m][n], 0, 0, 0); __builtin_amdgcn_s_setprio(0); } while (0)
; #define PG8_WAIT_V(n) asm volatile("s_waitcnt vmcnt(" #n ")" ::: "memory")
; template <class Epi, class Sched = StaticOrder, bool ALIGN_EPI = true>
; __device__ __forceinline__ void gemm_phase(LAS unsigned char* lds, const Gemm g, const Sched& S, const Epi& E) {
;     ...
;             PG8_LDB(B0, 0, 0); PG8_LDB(B1, 0, 1); PG8_SCHED; PG8_LDA(At, 0, 0); PG8_STAGE(PG8_SA(1, 1), a1 + hstep, voffA);
;             PG8_WAIT_V(8); PG8_WAIT_L(0); PG8_BAR; PG8_MMA(0, 0, At, B0); PG8_MMA(0, 1, At, B1); PG8_BAR; PG8_SCHED;
;             PG8_LDA(At, 0, 1); PG8_STAGE(PG8_SB(0, 0), b2, voffB); PG8_STAGE(PG8_SB(0, 1), b2 + hstep, voffB); PG8_STAGE(PG8_SA(0, 0), a2, voffA);
;             PG8_WAIT_V(8); PG8_WAIT_L(0); PG8_BAR; PG8_MMA(1, 0, At, B0); PG8_MMA(1, 1, At, B1); PG8_BAR; PG8_SCHED;
;             PG8_LDB(B0, 1, 0); PG8_LDB(B1, 1, 1); PG8_SCHED; PG8_LDA(At, 1, 0); PG8_STAGE(PG8_SA(0, 1), a2 + hstep, voffA);
;             PG8_WAIT_V(8); PG8_WAIT_L(0); PG8_BAR; PG8_MMA(0, 0, At, B0); PG8_MMA(0, 1, At, B1); PG8_BAR; PG8_SCHED;
;             PG8_LDA(At, 1, 1); PG8_STAGE(PG8_SB(1, 0), b3, voffB); PG8_STAGE(PG8_SB(1, 1), b3 + hstep, voffB); PG8_STAGE(PG8_SA(1, 0), a3, voffA);
;             PG8_WAIT_V(8); PG8_WAIT_L(0); PG8_BAR; PG8_MMA(1, 0, At, B0); PG8_MMA(1, 1, At, B1); PG8_BAR; PG8_SCHED;
	s_add_i32 s16, s33, s4
	v_lshl_add_u64 v[142:143], v[142:143], 0, s[34:35]
	s_mov_b32 m0, s16
	ds_read_b128 v[188:191], v146 offset:49152
	ds_read_b128 v[192:195], v146 offset:50176
	ds_read_b128 v[210:213], v146 offset:51200
	ds_read_b128 v[214:217], v146 offset:52224
	ds_read_b128 v[218:221], v146 offset:53248
	ds_read_b128 v[222:225], v146 offset:54272
	ds_read_b128 v[226:229], v146 offset:55296
	ds_read_b128 v[230:233], v146 offset:56320
	global_load_lds_dwordx4 v[142:143], off
	s_add_i32 m0, s16, 0x2000
	s_add_u32 s0, s0, 0x160080
	v_lshl_add_u64 v[142:143], v[152:153], 0, s[34:35]
	s_addc_u32 s1, s1, 0
	s_add_i32 s16, s44, s4
	global_load_lds_dwordx4 v[142:143], off
	v_lshl_add_u64 v[142:143], s[0:1], 0, v[134:135]
	s_mov_b32 m0, s16
	s_nop 0
	global_load_lds_dwordx4 v[142:143], off
	v_lshl_add_u64 v[142:143], s[0:1], 0, v[130:131]
	s_add_i32 m0, s16, 0x2000
	s_nop 0
	global_load_lds_dwordx4 v[142:143], off
	v_lshl_add_u64 v[142:143], v[196:197], 0, s[34:35]
	s_mov_b32 m0, s10
	s_nop 0
	global_load_lds_dwordx4 v[142:143], off
	v_lshl_add_u64 v[142:143], v[234:235], 0, s[34:35]
	s_mov_b32 m0, s11
	s_nop 0
	global_load_lds_dwordx4 v[142:143], off
	s_waitcnt vmcnt(8)
	s_waitcnt lgkmcnt(0)
	s_barrier
	s_waitcnt lgkmcnt(0)
	v_mfma_f32_16x16x32_bf16 v[62:65], v[148:151], v[188:191], v[62:65]
	v_mfma_f32_16x16x32_bf16 v[58:61], v[164:167], v[188:191], v[58:61]
	v_mfma_f32_16x16x32_bf16 v[54:57], v[148:151], v[210:213], v[54:57]
	v_mfma_f32_16x16x32_bf16 v[46:49], v[164:167], v[210:213], v[46:49]
	v_mfma_f32_16x16x32_bf16 v[38:41], v[148:151], v[218:221], v[38:41]
	v_mfma_f32_16x16x32_bf16 v[30:33], v[164:167], v[218:221], v[30:33]
	v_mfma_f32_16x16x32_bf16 v[22:25], v[148:151], v[226:229], v[22:25]
	v_mfma_f32_16x16x32_bf16 v[14:17], v[164:167], v[226:229], v[14:17]
	v_mfma_f32_16x16x32_bf16 v[62:65], v[160:163], v[192:195], v[62:65]
	v_mfma_f32_16x16x32_bf16 v[58:61], v[168:171], v[192:195], v[58:61]
	v_mfma_f32_16x16x32_bf16 v[54:57], v[160:163], v[214:217], v[54:57]
	v_mfma_f32_16x16x32_bf16 v[46:49], v[168:171], v[214:217], v[46:49]
	v_mfma_f32_16x16x32_bf16 v[38:41], v[160:163], v[222:225], v[38:41]
	v_mfma_f32_16x16x32_bf16 v[30:33], v[168:171], v[222:225], v[30:33]
	v_mfma_f32_16x16x32_bf16 v[22:25], v[160:163], v[230:233], v[22:25]
	v_mfma_f32_16x16x32_bf16 v[14:17], v[168:171], v[230:233], v[14:17]
	v_mfma_f32_16x16x32_bf16 v[50:53], v[172:175], v[188:191], v[50:53]
	v_mfma_f32_16x16x32_bf16 v[42:45], v[180:183], v[188:191], v[42:45]
	v_mfma_f32_16x16x32_bf16 v[34:37], v[172:175], v[210:213], v[34:37]
	v_mfma_f32_16x16x32_bf16 v[26:29], v[180:183], v[210:213], v[26:29]
	v_mfma_f32_16x16x32_bf16 v[18:21], v[172:175], v[218:221], v[18:21]
	v_mfma_f32_16x16x32_bf16 v[10:13], v[180:183], v[218:221], v[10:13]
	v_mfma_f32_16x16x32_bf16 v[6:9], v[172:175], v[226:229], v[6:9]
	v_mfma_f32_16x16x32_bf16 v[2:5], v[180:183], v[226:229], v[2:5]
	v_mfma_f32_16x16x32_bf16 v[50:53], v[176:179], v[192:195], v[50:53]
	v_mfma_f32_16x16x32_bf16 v[42:45], v[184:187], v[192:195], v[42:45]
	v_mfma_f32_16x16x32_bf16 v[34:37], v[176:179], v[214:217], v[34:37]
	v_mfma_f32_16x16x32_bf16 v[26:29], v[184:187], v[214:217], v[26:29]
	v_mfma_f32_16x16x32_bf16 v[18:21], v[176:179], v[222:225], v[18:21]
	v_mfma_f32_16x16x32_bf16 v[10:13], v[184:187], v[222:225], v[10:13]
	v_mfma_f32_16x16x32_bf16 v[6:9], v[176:179], v[230:233], v[6:9]
	v_mfma_f32_16x16x32_bf16 v[2:5], v[184:187], v[230:233], v[2:5]
	s_barrier
	s_add_i32 s82, s82, 2
	s_add_u32 s79, s79, 0x100
	s_addc_u32 s92, s92, 0
	s_cmpk_gt_u32 s82, 0x55
	s_mov_b64 s[44:45], s[46:47]
	s_cbranch_scc0 .LBB0_370
.LBB0_370:
	s_add_u32 s46, s44, 0x100
	s_addc_u32 s47, s45, 0
	s_add_i32 s16, 0, 0x10000
	s_cmpk_eq_i32 s82, 0x54
	s_cselect_b32 s31, s37, s47
	s_cselect_b32 s30, s36, s46
	v_add_u32_e32 v142, s16, v144
	s_cselect_b32 s1, s43, s92
	s_cselect_b32 s0, s42, s79
	s_add_i32 s33, 0, 0x14000
	ds_read_b128 v[148:151], v142
	ds_read_b128 v[160:163], v142 offset:1024
	ds_read_b128 v[164:167], v142 offset:2048
	ds_read_b128 v[168:171], v142 offset:3072
	v_add_u32_e32 v142, s33, v144
	ds_read_b128 v[172:175], v142
	ds_read_b128 v[176:179], v142 offset:1024
	ds_read_b128 v[180:183], v142 offset:2048
	ds_read_b128 v[184:187], v142 offset:3072
	v_lshl_add_u64 v[142:143], s[44:45], 0, v[138:139]
	s_add_i32 m0, s6, 0xc000
	ds_read_b128 v[188:191], v146
	ds_read_b128 v[192:195], v146 offset:1024
	ds_read_b128 v[210:213], v146 offset:2048
	ds_read_b128 v[214:217], v146 offset:3072
	ds_read_b128 v[218:221], v146 offset:4096
	ds_read_b128 v[222:225], v146 offset:5120
	ds_read_b128 v[226:229], v146 offset:6144
	ds_read_b128 v[230:233], v146 offset:7168
	global_load_lds_dwordx4 v[142:143], off
	v_lshl_add_u64 v[142:143], s[44:45], 0, v[140:141]
	s_add_i32 m0, s6, 0xe000
	s_nop 0
	global_load_lds_dwordx4 v[142:143], off
	s_waitcnt vmcnt(8)
	s_waitcnt lgkmcnt(0)
	s_barrier
; #define PG8_STAGE(bufoff, gbase, voff) do { _Pragma("unroll") for (int _i = 0; _i < 2; ++_i) \
;         __builtin_amdgcn_global_load_lds((const unsigned*)((const char*)(gbase) + (voff)[_i]), (LAS unsigned*)(lds + (bufoff) + ldsw + _i * 8192), 16, 0, 0); } while (0)
; #define PG8_LDA(dst, b, h) do { _Pragma("unroll") for (int m = 0; m < 4; ++m) _Pragma("unroll") for (int k = 0; k < 2; ++k) dst[m][k] = *(const LAS bf16x8*)(lds + PG8_SA(b, h) + aoff + m * 2048 + k * 1024); } while (0)
; #define PG8_MMA(ai, bj, At, Bt) do { __builtin_amdgcn_s_setprio(1); _Pragma("unroll") for (int m = 0; m < 4; ++m) _Pragma("unroll") for (int n = 0; n < 2; ++n) _Pragma("unroll") for (int k = 0; k < 2; ++k) \
;         acc[ai][bj][m][n] = __builtin_amdgcn_mfma_f32_16x16x32_bf16(Bt[n][k], At[m][k], acc[ai][bj][m][n], 0, 0, 0); __builtin_amdgcn_s_setprio(0); } while (0)
; #define PG8_WAIT_V(n) asm volatile("s_waitcnt vmcnt(" #n ")" ::: "memory")
; #define PG8_WAIT_L(n) asm volatile("s_waitcnt lgkmcnt(" #n ")" ::: "memory")
; #define PG8_BAR __builtin_amdgcn_s_barrier()
; #define PG8_SCHED __builtin_amdgcn_sched_barrier(0)
; template <class Epi, class Sched = StaticOrder, bool ALIGN_EPI = true>
; __device__ __forceinline__ void gemm_phase(LAS unsigned char* lds, const Gemm g, const Sched& S, const Epi& E) {
;     ...
;             PG8_WAIT_V(8); PG8_WAIT_L(0); PG8_BAR; PG8_MMA(0, 0, At, B0); PG8_MMA(0, 1, At, B1); PG8_BAR; PG8_SCHED;
;             PG8_LDA(At, 0, 1); PG8_STAGE(PG8_SB(0, 0), b2, voffB); PG8_STAGE(PG8_SB(0, 1), b2 + hstep, voffB); PG8_STAGE(PG8_SA(0, 0), a2, voffA);
;             PG8_WAIT_V(8); PG8_WAIT_L(0); PG8_BAR; PG8_MMA(1, 0, At, B0); PG8_MMA(1, 1, At, B1); PG8_BAR; PG8_SCHED;
	s_waitcnt lgkmcnt(0)
	v_mfma_f32_16x16x32_bf16 v[126:129], v[148:151], v[188:191], v[126:129]
	v_mfma_f32_16x16x32_bf16 v[122:125], v[164:167], v[188:191], v[122:125]
	v_mfma_f32_16x16x32_bf16 v[118:121], v[148:151], v[210:213], v[118:121]
	v_mfma_f32_16x16x32_bf16 v[110:113], v[164:167], v[210:213], v[110:113]
	v_mfma_f32_16x16x32_bf16 v[102:105], v[148:151], v[218:221], v[102:105]
	v_mfma_f32_16x16x32_bf16 v[94:97], v[164:167], v[218:221], v[94:97]
	v_mfma_f32_16x16x32_bf16 v[82:85], v[148:151], v[226:229], v[82:85]
	v_mfma_f32_16x16x32_bf16 v[74:77], v[164:167], v[226:229], v[74:77]
	v_mfma_f32_16x16x32_bf16 v[126:129], v[160:163], v[192:195], v[126:129]
	v_mfma_f32_16x16x32_bf16 v[122:125], v[168:171], v[192:195], v[122:125]
	v_mfma_f32_16x16x32_bf16 v[118:121], v[160:163], v[214:217], v[118:121]
	v_mfma_f32_16x16x32_bf16 v[110:113], v[168:171], v[214:217], v[110:113]
	v_mfma_f32_16x16x32_bf16 v[102:105], v[160:163], v[222:225], v[102:105]
	v_mfma_f32_16x16x32_bf16 v[94:97], v[168:171], v[222:225], v[94:97]
	v_mfma_f32_16x16x32_bf16 v[82:85], v[160:163], v[230:233], v[82:85]
	v_mfma_f32_16x16x32_bf16 v[74:77], v[168:171], v[230:233], v[74:77]
	v_mfma_f32_16x16x32_bf16 v[114:117], v[172:175], v[188:191], v[114:117]
	v_mfma_f32_16x16x32_bf16 v[106:109], v[180:183], v[188:191], v[106:109]
	v_mfma_f32_16x16x32_bf16 v[98:101], v[172:175], v[210:213], v[98:101]
	v_mfma_f32_16x16x32_bf16 v[90:93], v[180:183], v[210:213], v[90:93]
	v_mfma_f32_16x16x32_bf16 v[86:89], v[172:175], v[218:221], v[86:89]
	v_mfma_f32_16x16x32_bf16 v[78:81], v[180:183], v[218:221], v[78:81]
	v_mfma_f32_16x16x32_bf16 v[70:73], v[172:175], v[226:229], v[70:73]
	v_mfma_f32_16x16x32_bf16 v[66:69], v[180:183], v[226:229], v[66:69]
	v_mfma_f32_16x16x32_bf16 v[114:117], v[176:179], v[192:195], v[114:117]
	v_mfma_f32_16x16x32_bf16 v[106:109], v[184:187], v[192:195], v[106:109]
	v_mfma_f32_16x16x32_bf16 v[98:101], v[176:179], v[214:217], v[98:101]
	v_mfma_f32_16x16x32_bf16 v[90:93], v[184:187], v[214:217], v[90:93]
	v_mfma_f32_16x16x32_bf16 v[86:89], v[176:179], v[222:225], v[86:89]
	v_mfma_f32_16x16x32_bf16 v[78:81], v[184:187], v[222:225], v[78:81]
	v_mfma_f32_16x16x32_bf16 v[70:73], v[176:179], v[230:233], v[70:73]
	v_mfma_f32_16x16x32_bf16 v[66:69], v[184:187], v[230:233], v[66:69]
	s_barrier
	s_add_i32 s16, s16, s4
	v_lshl_add_u64 v[142:143], s[0:1], 0, v[134:135]
	s_mov_b32 m0, s16
	ds_read_b128 v[188:191], v146 offset:16384
	ds_read_b128 v[192:195], v146 offset:17408
	ds_read_b128 v[210:213], v146 offset:18432
	ds_read_b128 v[214:217], v146 offset:19456
	ds_read_b128 v[218:221], v146 offset:20480
	ds_read_b128 v[222:225], v146 offset:21504
	ds_read_b128 v[226:229], v146 offset:22528
	ds_read_b128 v[230:233], v146 offset:23552
	global_load_lds_dwordx4 v[142:143], off
	s_add_i32 m0, s16, 0x2000
	s_add_u32 s16, s0, 0x160000
	v_lshl_add_u64 v[152:153], s[0:1], 0, v[130:131]
	s_addc_u32 s17, s1, 0
	s_add_i32 s33, s33, s4
	global_load_lds_dwordx4 v[152:153], off
	v_lshl_add_u64 v[196:197], s[16:17], 0, v[134:135]
	s_mov_b32 m0, s33
	v_lshl_add_u64 v[234:235], s[30:31], 0, v[132:133]
	global_load_lds_dwordx4 v[196:197], off
	v_lshl_add_u64 v[196:197], s[16:17], 0, v[130:131]
	s_add_i32 m0, s33, 0x2000
	s_nop 0
	global_load_lds_dwordx4 v[196:197], off
	v_lshl_add_u64 v[196:197], s[30:31], 0, v[136:137]
	s_mov_b32 m0, s6
	s_nop 0
	global_load_lds_dwordx4 v[196:197], off
	s_mov_b32 m0, s7
	s_nop 0
	global_load_lds_dwordx4 v[234:235], off
	s_waitcnt vmcnt(8)
	s_waitcnt lgkmcnt(0)
	s_barrier
	s_waitcnt lgkmcnt(0)
	v_mfma_f32_16x16x32_bf16 v[62:65], v[148:151], v[188:191], v[62:65]
	v_mfma_f32_16x16x32_bf16 v[58:61], v[164:167], v[188:191], v[58:61]
	v_mfma_f32_16x16x32_bf16 v[54:57], v[148:151], v[210:213], v[54:57]
	v_mfma_f32_16x16x32_bf16 v[46:49], v[164:167], v[210:213], v[46:49]
	v_mfma_f32_16x16x32_bf16 v[38:41], v[148:151], v[218:221], v[38:41]
	v_mfma_f32_16x16x32_bf16 v[30:33], v[164:167], v[218:221], v[30:33]
	v_mfma_f32_16x16x32_bf16 v[22:25], v[148:151], v[226:229], v[22:25]
	v_mfma_f32_16x16x32_bf16 v[14:17], v[164:167], v[226:229], v[14:17]
	v_mfma_f32_16x16x32_bf16 v[62:65], v[160:163], v[192:195], v[62:65]
	v_mfma_f32_16x16x32_bf16 v[58:61], v[168:171], v[192:195], v[58:61]
	v_mfma_f32_16x16x32_bf16 v[54:57], v[160:163], v[214:217], v[54:57]
	v_mfma_f32_16x16x32_bf16 v[46:49], v[168:171], v[214:217], v[46:49]
	v_mfma_f32_16x16x32_bf16 v[38:41], v[160:163], v[222:225], v[38:41]
	v_mfma_f32_16x16x32_bf16 v[30:33], v[168:171], v[222:225], v[30:33]
	v_mfma_f32_16x16x32_bf16 v[22:25], v[160:163], v[230:233], v[22:25]
	v_mfma_f32_16x16x32_bf16 v[14:17], v[168:171], v[230:233], v[14:17]
	v_mfma_f32_16x16x32_bf16 v[50:53], v[172:175], v[188:191], v[50:53]
	v_mfma_f32_16x16x32_bf16 v[42:45], v[180:183], v[188:191], v[42:45]
	v_mfma_f32_16x16x32_bf16 v[34:37], v[172:175], v[210:213], v[34:37]
	v_mfma_f32_16x16x32_bf16 v[26:29], v[180:183], v[210:213], v[26:29]
	v_mfma_f32_16x16x32_bf16 v[18:21], v[172:175], v[218:221], v[18:21]
	v_mfma_f32_16x16x32_bf16 v[10:13], v[180:183], v[218:221], v[10:13]
	v_mfma_f32_16x16x32_bf16 v[6:9], v[172:175], v[226:229], v[6:9]
	v_mfma_f32_16x16x32_bf16 v[2:5], v[180:183], v[226:229], v[2:5]
	v_mfma_f32_16x16x32_bf16 v[50:53], v[176:179], v[192:195], v[50:53]
	v_mfma_f32_16x16x32_bf16 v[42:45], v[184:187], v[192:195], v[42:45]
	v_mfma_f32_16x16x32_bf16 v[34:37], v[176:179], v[214:217], v[34:37]
	v_mfma_f32_16x16x32_bf16 v[26:29], v[184:187], v[214:217], v[26:29]
	v_mfma_f32_16x16x32_bf16 v[18:21], v[176:179], v[222:225], v[18:21]
	v_mfma_f32_16x16x32_bf16 v[10:13], v[184:187], v[222:225], v[10:13]
	v_mfma_f32_16x16x32_bf16 v[6:9], v[176:179], v[230:233], v[6:9]
	v_mfma_f32_16x16x32_bf16 v[2:5], v[184:187], v[230:233], v[2:5]
	s_barrier
; #define PG8_STAGE(bufoff, gbase, voff) do { _Pragma("unroll") for (int _i = 0; _i < 2; ++_i) \
;         __builtin_amdgcn_global_load_lds((const unsigned*)((const char*)(gbase) + (voff)[_i]), (LAS unsigned*)(lds + (bufoff) + ldsw + _i * 8192), 16, 0, 0); } while (0)
; #define PG8_LDA(dst, b, h) do { _Pragma("unroll") for (int m = 0; m < 4; ++m) _Pragma("unroll") for (int k = 0; k < 2; ++k) dst[m][k] = *(const LAS bf16x8*)(lds + PG8_SA(b, h) + aoff + m * 2048 + k * 1024); } while (0)
; #define PG8_LDB(dst, b, h) do { _Pragma("unroll") for (int n = 0; n < 2; ++n) _Pragma("unroll") for (int k = 0; k < 2; ++k) dst[n][k] = *(const LAS bf16x8*)(lds + PG8_SB(b, h) + boff + n * 2048 + k * 1024); } while (0)
; #define PG8_MMA(ai, bj, At, Bt) do { __builtin_amdgcn_s_setprio(1); _Pragma("unroll") for (int m = 0; m < 4; ++m) _Pragma("unroll") for (int n = 0; n < 2; ++n) _Pragma("unroll") for (int k = 0; k < 2; ++k) \
;         acc[ai][bj][m][n] = __builtin_amdgcn_mfma_f32_16x16x32_bf16(Bt[n][k], At[m][k], acc[ai][bj][m][n], 0, 0, 0); __builtin_amdgcn_s_setprio(0); } while (0)
; #define PG8_WAIT_V(n) asm volatile("s_waitcnt vmcnt(" #n ")" ::: "memory")
; #define PG8_WAIT_L(n) asm volatile("s_waitcnt lgkmcnt(" #n ")" ::: "memory")
; #define PG8_BAR __builtin_amdgcn_s_barrier()
; #define PG8_SCHED __builtin_amdgcn_sched_barrier(0)
; template <class Epi, class Sched = StaticOrder, bool ALIGN_EPI = true>
; __device__ __forceinline__ void gemm_phase(LAS unsigned char* lds, const Gemm g, const Sched& S, const Epi& E) {
;     ...
;             PG8_LDB(B0, 1, 0); PG8_LDB(B1, 1, 1); PG8_SCHED; PG8_LDA(At, 1, 0); PG8_STAGE(PG8_SA(0, 1), a2 + hstep, voffA);
;             PG8_WAIT_V(8); PG8_WAIT_L(0); PG8_BAR; PG8_MMA(0, 0, At, B0); PG8_MMA(0, 1, At, B1); PG8_BAR; PG8_SCHED;
;             PG8_LDA(At, 1, 1); PG8_STAGE(PG8_SB(1, 0), b3, voffB); PG8_STAGE(PG8_SB(1, 1), b3 + hstep, voffB); PG8_STAGE(PG8_SA(1, 0), a3, voffA);
;             PG8_WAIT_V(8); PG8_WAIT_L(0); PG8_BAR; PG8_MMA(1, 0, At, B0); PG8_MMA(1, 1, At, B1); PG8_BAR; PG8_SCHED;
	s_add_i32 s33, 0, 0x18000
	v_add_u32_e32 v147, s33, v144
	s_add_i32 s44, 0, 0x1c000
	ds_read_b128 v[148:151], v147
	ds_read_b128 v[160:163], v147 offset:1024
	ds_read_b128 v[164:167], v147 offset:2048
	ds_read_b128 v[168:171], v147 offset:3072
	v_add_u32_e32 v147, s44, v144
	ds_read_b128 v[172:175], v147
	ds_read_b128 v[176:179], v147 offset:1024
	ds_read_b128 v[180:183], v147 offset:2048
	ds_read_b128 v[184:187], v147 offset:3072
	s_add_u32 s16, s30, 0x160000
	s_addc_u32 s17, s31, 0
	s_mov_b32 m0, s8
	v_lshl_add_u64 v[236:237], s[16:17], 0, v[136:137]
	ds_read_b128 v[188:191], v146 offset:32768
	ds_read_b128 v[192:195], v146 offset:33792
	ds_read_b128 v[210:213], v146 offset:34816
	ds_read_b128 v[214:217], v146 offset:35840
	ds_read_b128 v[218:221], v146 offset:36864
	ds_read_b128 v[222:225], v146 offset:37888
	ds_read_b128 v[226:229], v146 offset:38912
	ds_read_b128 v[230:233], v146 offset:39936
	global_load_lds_dwordx4 v[236:237], off
	v_lshl_add_u64 v[236:237], s[16:17], 0, v[132:133]
	s_mov_b32 m0, s9
	s_nop 0
	global_load_lds_dwordx4 v[236:237], off
	s_waitcnt vmcnt(8)
	s_waitcnt lgkmcnt(0)
	s_barrier
	s_waitcnt lgkmcnt(0)
	v_mfma_f32_16x16x32_bf16 v[126:129], v[148:151], v[188:191], v[126:129]
	v_mfma_f32_16x16x32_bf16 v[122:125], v[164:167], v[188:191], v[122:125]
	v_mfma_f32_16x16x32_bf16 v[118:121], v[148:151], v[210:213], v[118:121]
	v_mfma_f32_16x16x32_bf16 v[110:113], v[164:167], v[210:213], v[110:113]
	v_mfma_f32_16x16x32_bf16 v[102:105], v[148:151], v[218:221], v[102:105]
	v_mfma_f32_16x16x32_bf16 v[94:97], v[164:167], v[218:221], v[94:97]
	v_mfma_f32_16x16x32_bf16 v[82:85], v[148:151], v[226:229], v[82:85]
	v_mfma_f32_16x16x32_bf16 v[74:77], v[164:167], v[226:229], v[74:77]
	v_mfma_f32_16x16x32_bf16 v[126:129], v[160:163], v[192:195], v[126:129]
	v_mfma_f32_16x16x32_bf16 v[122:125], v[168:171], v[192:195], v[122:125]
	v_mfma_f32_16x16x32_bf16 v[118:121], v[160:163], v[214:217], v[118:121]
	v_mfma_f32_16x16x32_bf16 v[110:113], v[168:171], v[214:217], v[110:113]
	v_mfma_f32_16x16x32_bf16 v[102:105], v[160:163], v[222:225], v[102:105]
	v_mfma_f32_16x16x32_bf16 v[94:97], v[168:171], v[222:225], v[94:97]
	v_mfma_f32_16x16x32_bf16 v[82:85], v[160:163], v[230:233], v[82:85]
	v_mfma_f32_16x16x32_bf16 v[74:77], v[168:171], v[230:233], v[74:77]
	v_mfma_f32_16x16x32_bf16 v[114:117], v[172:175], v[188:191], v[114:117]
	v_mfma_f32_16x16x32_bf16 v[106:109], v[180:183], v[188:191], v[106:109]
	v_mfma_f32_16x16x32_bf16 v[98:101], v[172:175], v[210:213], v[98:101]
	v_mfma_f32_16x16x32_bf16 v[90:93], v[180:183], v[210:213], v[90:93]
	v_mfma_f32_16x16x32_bf16 v[86:89], v[172:175], v[218:221], v[86:89]
	v_mfma_f32_16x16x32_bf16 v[78:81], v[180:183], v[218:221], v[78:81]
	v_mfma_f32_16x16x32_bf16 v[70:73], v[172:175], v[226:229], v[70:73]
	v_mfma_f32_16x16x32_bf16 v[66:69], v[180:183], v[226:229], v[66:69]
	v_mfma_f32_16x16x32_bf16 v[114:117], v[176:179], v[192:195], v[114:117]
	v_mfma_f32_16x16x32_bf16 v[106:109], v[184:187], v[192:195], v[106:109]
	v_mfma_f32_16x16x32_bf16 v[98:101], v[176:179], v[214:217], v[98:101]
	v_mfma_f32_16x16x32_bf16 v[90:93], v[184:187], v[214:217], v[90:93]
	v_mfma_f32_16x16x32_bf16 v[86:89], v[176:179], v[222:225], v[86:89]
	v_mfma_f32_16x16x32_bf16 v[78:81], v[184:187], v[222:225], v[78:81]
	v_mfma_f32_16x16x32_bf16 v[70:73], v[176:179], v[230:233], v[70:73]
	v_mfma_f32_16x16x32_bf16 v[66:69], v[184:187], v[230:233], v[66:69]
	s_barrier
	s_add_i32 s16, s33, s4
	v_lshl_add_u64 v[142:143], v[142:143], 0, s[34:35]
	s_mov_b32 m0, s16
	ds_read_b128 v[188:191], v146 offset:49152
	ds_read_b128 v[192:195], v146 offset:50176
	ds_read_b128 v[210:213], v146 offset:51200
	ds_read_b128 v[214:217], v146 offset:52224
	ds_read_b128 v[218:221], v146 offset:53248
	ds_read_b128 v[222:225], v146 offset:54272
	ds_read_b128 v[226:229], v146 offset:55296
	ds_read_b128 v[230:233], v146 offset:56320
	global_load_lds_dwordx4 v[142:143], off
	s_add_i32 m0, s16, 0x2000
	s_add_u32 s0, s0, 0x160080
	v_lshl_add_u64 v[142:143], v[152:153], 0, s[34:35]
	s_addc_u32 s1, s1, 0
	s_add_i32 s16, s44, s4
	global_load_lds_dwordx4 v[142:143], off
	v_lshl_add_u64 v[142:143], s[0:1], 0, v[134:135]
	s_mov_b32 m0, s16
	s_nop 0
	global_load_lds_dwordx4 v[142:143], off
	v_lshl_add_u64 v[142:143], s[0:1], 0, v[130:131]
	s_add_i32 m0, s16, 0x2000
	s_nop 0
	global_load_lds_dwordx4 v[142:143], off
	v_lshl_add_u64 v[142:143], v[196:197], 0, s[34:35]
	s_mov_b32 m0, s10
	s_nop 0
	global_load_lds_dwordx4 v[142:143], off
	v_lshl_add_u64 v[142:143], v[234:235], 0, s[34:35]
	s_mov_b32 m0, s11
	s_nop 0
	global_load_lds_dwordx4 v[142:143], off
	s_waitcnt vmcnt(8)
	s_waitcnt lgkmcnt(0)
	s_barrier
	s_waitcnt lgkmcnt(0)
	v_mfma_f32_16x16x32_bf16 v[62:65], v[148:151], v[188:191], v[62:65]
	v_mfma_f32_16x16x32_bf16 v[58:61], v[164:167], v[188:191], v[58:61]
	v_mfma_f32_16x16x32_bf16 v[54:57], v[148:151], v[210:213], v[54:57]
	v_mfma_f32_16x16x32_bf16 v[46:49], v[164:167], v[210:213], v[46:49]
	v_mfma_f32_16x16x32_bf16 v[38:41], v[148:151], v[218:221], v[38:41]
	v_mfma_f32_16x16x32_bf16 v[30:33], v[164:167], v[218:221], v[30:33]
	v_mfma_f32_16x16x32_bf16 v[22:25], v[148:151], v[226:229], v[22:25]
	v_mfma_f32_16x16x32_bf16 v[14:17], v[164:167], v[226:229], v[14:17]
	v_mfma_f32_16x16x32_bf16 v[62:65], v[160:163], v[192:195], v[62:65]
	v_mfma_f32_16x16x32_bf16 v[58:61], v[168:171], v[192:195], v[58:61]
	v_mfma_f32_16x16x32_bf16 v[54:57], v[160:163], v[214:217], v[54:57]
	v_mfma_f32_16x16x32_bf16 v[46:49], v[168:171], v[214:217], v[46:49]
	v_mfma_f32_16x16x32_bf16 v[38:41], v[160:163], v[222:225], v[38:41]
	v_mfma_f32_16x16x32_bf16 v[30:33], v[168:171], v[222:225], v[30:33]
	v_mfma_f32_16x16x32_bf16 v[22:25], v[160:163], v[230:233], v[22:25]
	v_mfma_f32_16x16x32_bf16 v[14:17], v[168:171], v[230:233], v[14:17]
	v_mfma_f32_16x16x32_bf16 v[50:53], v[172:175], v[188:191], v[50:53]
	v_mfma_f32_16x16x32_bf16 v[42:45], v[180:183], v[188:191], v[42:45]
	v_mfma_f32_16x16x32_bf16 v[34:37], v[172:175], v[210:213], v[34:37]
	v_mfma_f32_16x16x32_bf16 v[26:29], v[180:183], v[210:213], v[26:29]
	v_mfma_f32_16x16x32_bf16 v[18:21], v[172:175], v[218:221], v[18:21]
	v_mfma_f32_16x16x32_bf16 v[10:13], v[180:183], v[218:221], v[10:13]
	v_mfma_f32_16x16x32_bf16 v[6:9], v[172:175], v[226:229], v[6:9]
	v_mfma_f32_16x16x32_bf16 v[2:5], v[180:183], v[226:229], v[2:5]
	v_mfma_f32_16x16x32_bf16 v[50:53], v[176:179], v[192:195], v[50:53]
	v_mfma_f32_16x16x32_bf16 v[42:45], v[184:187], v[192:195], v[42:45]
	v_mfma_f32_16x16x32_bf16 v[34:37], v[176:179], v[214:217], v[34:37]
	v_mfma_f32_16x16x32_bf16 v[26:29], v[184:187], v[214:217], v[26:29]
	v_mfma_f32_16x16x32_bf16 v[18:21], v[176:179], v[222:225], v[18:21]
	v_mfma_f32_16x16x32_bf16 v[10:13], v[184:187], v[222:225], v[10:13]
	v_mfma_f32_16x16x32_bf16 v[6:9], v[176:179], v[230:233], v[6:9]
	v_mfma_f32_16x16x32_bf16 v[2:5], v[184:187], v[230:233], v[2:5]
	s_barrier
	s_add_i32 s82, s82, 2
	s_add_u32 s79, s79, 0x100
	s_addc_u32 s92, s92, 0
	s_cmpk_gt_u32 s82, 0x55
	s_mov_b64 s[44:45], s[46:47]
	s_cbranch_scc0 .LBB0_370

; #define PG8_WAIT_V(n) asm volatile("s_waitcnt vmcnt(" #n ")" ::: "memory")
; #define PG8_BAR __builtin_amdgcn_s_barrier()
; template <class Epi, class Sched = StaticOrder, bool ALIGN_EPI = true>
; __device__ __forceinline__ void gemm_phase(LAS unsigned char* lds, const Gemm g, const Sched& S, const Epi& E) {
;     ...
;     PG8_WAIT_V(0);
;     if constexpr (!ALIGN_EPI) { if (wr == 0) PG8_BAR; }
;     PG8_BAR;
.LBB0_376:
	s_setprio 0
	s_waitcnt vmcnt(0)
	v_readlane_b32 s22, v254, 39
	v_readlane_b32 s33, v254, 40
	v_readlane_b32 s23, v254, 45
	v_readlane_b32 s77, v254, 46
	s_mov_b32 s70, 0x3a000000
	s_barrier

;     __device__ bool next(int i, Unit& u) const { const int idx = i * G + c; if (idx >= 64) return false; u.kp = idx & 3; u.pn = (idx >> 2) & 7; u.pm = 192 + (idx >> 5); return true; }
; #define PG8_STAGE(bufoff, gbase, voff) do { _Pragma("unroll") for (int _i = 0; _i < 2; ++_i) \
;         __builtin_amdgcn_global_load_lds((const unsigned*)((const char*)(gbase) + (voff)[_i]), (LAS unsigned*)(lds + (bufoff) + ldsw + _i * 8192), 16, 0, 0); } while (0)
; #define PG8_WAIT_V(n) asm volatile("s_waitcnt vmcnt(" #n ")" ::: "memory")
; #define PG8_BAR __builtin_amdgcn_s_barrier()
; template <class Epi, class Sched = StaticOrder, bool ALIGN_EPI = true>
; __device__ __forceinline__ void gemm_phase(LAS unsigned char* lds, const Gemm g, const Sched& S, const Epi& E) {
;     ...
;     for (int i = 0; i < 2; ++i) { int R, C; stage_rc(tid * 16 + i * 8192, R, C); const int Rb = Epi::PERM ? ((R & ~31) + perm32(R & 31)) : R;
;         voffA[i] = (unsigned)(R * g.ld + C) * 2u; voffB[i] = (unsigned)(Rb * g.ld + C) * 2u; }
;     const size_t kstep = (size_t)(BK * 2);
;     const size_t hstep = (size_t)HALF * g.ld * 2;
;     const size_t tstep = 2 * hstep;
;     const unsigned ldsw = (unsigned)wid * 1024u;
;     const int aoff = lds_byte(wr * 64 + fr, fq * 8), boff = lds_byte(wc * 32 + fr, fq * 8);
;     ...
;     Unit cur, nxt; int ui = 0;
;     if (!S.next(0, cur)) return;
;     f32x4 acc[2][2][4][2];
; #pragma unroll
;     for (int a = 0; a < 2; ++a)
; #pragma unroll
;         for (int b = 0; b < 2; ++b)
; #pragma unroll
;             for (int m = 0; m < 4; ++m)
; #pragma unroll
;                 for (int n = 0; n < 2; ++n) acc[a][b][m][n] = (f32x4){0.f, 0.f, 0.f, 0.f};
;     bf16x8 At[4][2], B0[2][2], B1[2][2];
;     const char* cA = (const char*)g.A + (size_t)cur.pm * tstep + (size_t)cur.kp * K * 2; const char* cB = (const char*)g.Bt + (size_t)cur.pn * tstep + (size_t)cur.kp * K * 2;
;     PG8_STAGE(PG8_SB(0, 0), cB, voffB); PG8_STAGE(PG8_SB(0, 1), cB + hstep, voffB); PG8_STAGE(PG8_SA(0, 0), cA, voffA); PG8_STAGE(PG8_SA(0, 1), cA + hstep, voffA);
;     if (wr == 1) PG8_BAR;
;     PG8_WAIT_V(2); PG8_BAR;
;     PG8_STAGE(PG8_SB(1, 0), cB + kstep, voffB); PG8_STAGE(PG8_SA(1, 0), cA + kstep, voffA); PG8_STAGE(PG8_SB(1, 1), cB + hstep + kstep, voffB);
;     PG8_WAIT_V(6); PG8_BAR;
.LBB0_382:
	v_bfe_u32 v20, v18, 4, 2
	s_lshl_b32 s10, s10, 5
	v_and_b32_e32 v19, 15, v18
	v_lshlrev_b32_e32 v21, 4, v20
	v_lshlrev_b32_e32 v18, 2, v18
	s_and_b32 s22, s10, 0x60
	v_lshl_or_b32 v1, s11, 6, v19
	v_lshl_or_b32 v19, v19, 6, v21
	s_lshl_b32 s11, s11, 13
	v_and_b32_e32 v18, 32, v18
	s_lshl_b32 s10, s22, 7
	s_add_i32 m0, s6, 0x18000
	v_lshl_add_u64 v[8:9], v[8:9], 0, s[34:35]
	v_bitop3_b32 v21, v19, s11, v18 bitop3:0xde
	v_bitop3_b32 v135, v19, s10, v18 bitop3:0xde
	s_waitcnt vmcnt(2)
	s_barrier
	global_load_lds_dwordx4 v[8:9], off
	v_lshl_add_u64 v[6:7], v[6:7], 0, s[34:35]
	s_add_i32 m0, s6, 0x1a000
	s_add_i32 s10, s6, 0x8000
	s_add_i32 s11, s6, 0xa000
	global_load_lds_dwordx4 v[6:7], off
	v_lshl_add_u64 v[2:3], v[2:3], 0, s[34:35]
	s_mov_b32 m0, s10
	s_add_u32 s16, s0, 0x160080
	global_load_lds_dwordx4 v[2:3], off
	v_lshl_add_u64 v[2:3], v[4:5], 0, s[34:35]
	s_mov_b32 m0, s11
	s_addc_u32 s17, s1, 0
	global_load_lds_dwordx4 v[2:3], off
	s_add_i32 m0, s6, 0x1c000
	v_lshl_add_u64 v[2:3], s[16:17], 0, v[132:133]
	global_load_lds_dwordx4 v[2:3], off
	v_lshl_add_u64 v[2:3], s[16:17], 0, v[130:131]
	s_add_i32 m0, s6, 0x1e000
	s_movk_i32 s23, 0x1600
	global_load_lds_dwordx4 v[2:3], off
	v_lshl_or_b32 v134, v20, 2, s22
	v_lshrrev_b32_e32 v3, 1, v15
	v_mul_lo_u32 v2, v14, s23
	s_mov_b32 s22, 0x16000
	v_mad_u64_u32 v[2:3], s[16:17], v3, s22, v[2:3]
	v_or_b32_e32 v2, v2, v16
	v_add_lshl_u32 v2, v2, v17, 1
	v_mov_b32_e32 v3, v0
	s_mov_b64 s[30:31], 0x160080
	v_lshl_add_u64 v[136:137], v[2:3], 0, s[30:31]
	v_lshrrev_b32_e32 v3, 1, v10
	v_mul_lo_u32 v2, v11, s23
	v_mad_u64_u32 v[2:3], s[16:17], v3, s22, v[2:3]
	s_waitcnt vmcnt(6)
	v_or_b32_e32 v2, v2, v12
	s_cmpk_lt_u32 s20, 0x100
	v_add_lshl_u32 v2, v2, v13, 1
	v_mov_b32_e32 v3, v0
	s_sext_i32_i8 s70, s21
	s_cselect_b64 s[20:21], -1, 0
	v_lshl_add_u64 v[138:139], v[2:3], 0, s[30:31]
	s_mov_b32 s22, 0
	v_add_u32_e32 v170, 0, v21
	s_barrier
	s_cmp_eq_u64 s[12:13], 0
	s_cbranch_scc1 .Lmy_pr_385
	s_setprio 1
.Lmy_pr_385:
	s_branch .LBB0_385
.LBB0_383:
	s_mov_b64 s[0:1], 0

; #define PG8_STAGE(bufoff, gbase, voff) do { _Pragma("unroll") for (int _i = 0; _i < 2; ++_i) \
;         __builtin_amdgcn_global_load_lds((const unsigned*)((const char*)(gbase) + (voff)[_i]), (LAS unsigned*)(lds + (bufoff) + ldsw + _i * 8192), 16, 0, 0); } while (0)
; #define PG8_LDA(dst, b, h) do { _Pragma("unroll") for (int m = 0; m < 4; ++m) _Pragma("unroll") for (int k = 0; k < 2; ++k) dst[m][k] = *(const LAS bf16x8*)(lds + PG8_SA(b, h) + aoff + m * 2048 + k * 1024); } while (0)
; #define PG8_LDB(dst, b, h) do { _Pragma("unroll") for (int n = 0; n < 2; ++n) _Pragma("unroll") for (int k = 0; k < 2; ++k) dst[n][k] = *(const LAS bf16x8*)(lds + PG8_SB(b, h) + boff + n * 2048 + k * 1024); } while (0)
; #define PG8_MMA(ai, bj, At, Bt) do { __builtin_amdgcn_s_setprio(1); _Pragma("unroll") for (int m = 0; m < 4; ++m) _Pragma("unroll") for (int n = 0; n < 2; ++n) _Pragma("unroll") for (int k = 0; k < 2; ++k) \
;         acc[ai][bj][m][n] = __builtin_amdgcn_mfma_f32_16x16x32_bf16(Bt[n][k], At[m][k], acc[ai][bj][m][n], 0, 0, 0); __builtin_amdgcn_s_setprio(0); } while (0)
; #define PG8_WAIT_V(n) asm volatile("s_waitcnt vmcnt(" #n ")" ::: "memory")
; #define PG8_WAIT_L(n) asm volatile("s_waitcnt lgkmcnt(" #n ")" ::: "memory")
; template <class Epi, class Sched = StaticOrder, bool ALIGN_EPI = true>
; __device__ __forceinline__ void gemm_phase(LAS unsigned char* lds, const Gemm g, const Sched& S, const Epi& E) {
;     ...
;         const char* nA = has_next ? (const char*)g.A + (size_t)nxt.pm * tstep + (size_t)nxt.kp * K * 2 : cA; const char* nB = has_next ? (const char*)g.Bt + (size_t)nxt.pn * tstep + (size_t)nxt.kp * K * 2 : cB;
;         for (int t = 0; t < nt; t += 2) {
;             const bool last = (t == nt - 2);
;             const char* a1 = cA + (size_t)(t + 1) * kstep;
;             const char* a2 = last ? nA : cA + (size_t)(t + 2) * kstep; const char* b2 = last ? nB : cB + (size_t)(t + 2) * kstep;
;             const char* a3 = a2 + kstep; const char* b3 = b2 + kstep;
;             PG8_LDB(B0, 0, 0); PG8_LDB(B1, 0, 1); PG8_SCHED; PG8_LDA(At, 0, 0); PG8_STAGE(PG8_SA(1, 1), a1 + hstep, voffA);
;             PG8_WAIT_V(8); PG8_WAIT_L(0); PG8_BAR; PG8_MMA(0, 0, At, B0); PG8_MMA(0, 1, At, B1); PG8_BAR; PG8_SCHED;
;             PG8_LDA(At, 0, 1); PG8_STAGE(PG8_SB(0, 0), b2, voffB); PG8_STAGE(PG8_SB(0, 1), b2 + hstep, voffB); PG8_STAGE(PG8_SA(0, 0), a2, voffA);
.Lmy_nb_392:
	s_add_u32 s46, s44, 0x100
	s_addc_u32 s47, s45, 0
	s_add_i32 s16, 0, 0x10000
	s_cmpk_eq_i32 s82, 0x54
	s_cselect_b32 s31, s37, s47
	s_cselect_b32 s30, s36, s46
	v_add_u32_e32 v152, s16, v135
	s_cselect_b32 s1, s43, s92
	s_cselect_b32 s0, s42, s79
	s_add_i32 s33, 0, 0x14000
	ds_read_b128 v[140:143], v152
	ds_read_b128 v[144:147], v152 offset:1024
	ds_read_b128 v[148:151], v152 offset:2048
	ds_read_b128 v[160:163], v152 offset:3072
	v_add_u32_e32 v152, s33, v135
	ds_read_b128 v[164:167], v152
	ds_read_b128 v[172:175], v152 offset:1024
	ds_read_b128 v[176:179], v152 offset:2048
	ds_read_b128 v[180:183], v152 offset:3072
	v_lshl_add_u64 v[152:153], s[44:45], 0, v[136:137]
	s_add_i32 m0, s6, 0xc000
	ds_read_b128 v[184:187], v170
	ds_read_b128 v[188:191], v170 offset:1024
	ds_read_b128 v[192:195], v170 offset:2048
	ds_read_b128 v[210:213], v170 offset:3072
	ds_read_b128 v[214:217], v170 offset:4096
	ds_read_b128 v[218:221], v170 offset:5120
	ds_read_b128 v[222:225], v170 offset:6144
	ds_read_b128 v[226:229], v170 offset:7168
	global_load_lds_dwordx4 v[152:153], off
	v_lshl_add_u64 v[152:153], s[44:45], 0, v[138:139]
	s_add_i32 m0, s6, 0xe000
	s_nop 0
	global_load_lds_dwordx4 v[152:153], off
	s_waitcnt vmcnt(8)
	s_waitcnt lgkmcnt(0)
	s_barrier
	s_waitcnt lgkmcnt(0)
	v_mfma_f32_16x16x32_bf16 v[126:129], v[140:143], v[184:187], 0
	v_mfma_f32_16x16x32_bf16 v[122:125], v[148:151], v[184:187], 0
	v_mfma_f32_16x16x32_bf16 v[118:121], v[140:143], v[192:195], 0
	v_mfma_f32_16x16x32_bf16 v[106:109], v[148:151], v[192:195], 0
	v_mfma_f32_16x16x32_bf16 v[98:101], v[140:143], v[214:217], 0
	v_mfma_f32_16x16x32_bf16 v[90:93], v[148:151], v[214:217], 0
	v_mfma_f32_16x16x32_bf16 v[82:85], v[140:143], v[222:225], 0
	v_mfma_f32_16x16x32_bf16 v[74:77], v[148:151], v[222:225], 0
	v_mfma_f32_16x16x32_bf16 v[126:129], v[144:147], v[188:191], v[126:129]
	v_mfma_f32_16x16x32_bf16 v[122:125], v[160:163], v[188:191], v[122:125]
	v_mfma_f32_16x16x32_bf16 v[118:121], v[144:147], v[210:213], v[118:121]
	v_mfma_f32_16x16x32_bf16 v[106:109], v[160:163], v[210:213], v[106:109]
	v_mfma_f32_16x16x32_bf16 v[98:101], v[144:147], v[218:221], v[98:101]
	v_mfma_f32_16x16x32_bf16 v[90:93], v[160:163], v[218:221], v[90:93]
	v_mfma_f32_16x16x32_bf16 v[82:85], v[144:147], v[226:229], v[82:85]
	v_mfma_f32_16x16x32_bf16 v[74:77], v[160:163], v[226:229], v[74:77]
	v_mfma_f32_16x16x32_bf16 v[114:117], v[164:167], v[184:187], 0
	v_mfma_f32_16x16x32_bf16 v[110:113], v[176:179], v[184:187], 0
	v_mfma_f32_16x16x32_bf16 v[102:105], v[164:167], v[192:195], 0
	v_mfma_f32_16x16x32_bf16 v[94:97], v[176:179], v[192:195], 0
	v_mfma_f32_16x16x32_bf16 v[86:89], v[164:167], v[214:217], 0
	v_mfma_f32_16x16x32_bf16 v[78:81], v[176:179], v[214:217], 0
	v_mfma_f32_16x16x32_bf16 v[70:73], v[164:167], v[222:225], 0
	v_mfma_f32_16x16x32_bf16 v[66:69], v[176:179], v[222:225], 0
	v_mfma_f32_16x16x32_bf16 v[114:117], v[172:175], v[188:191], v[114:117]
	v_mfma_f32_16x16x32_bf16 v[110:113], v[180:183], v[188:191], v[110:113]
	v_mfma_f32_16x16x32_bf16 v[102:105], v[172:175], v[210:213], v[102:105]
	v_mfma_f32_16x16x32_bf16 v[94:97], v[180:183], v[210:213], v[94:97]
	v_mfma_f32_16x16x32_bf16 v[86:89], v[172:175], v[218:221], v[86:89]
	v_mfma_f32_16x16x32_bf16 v[78:81], v[180:183], v[218:221], v[78:81]
	v_mfma_f32_16x16x32_bf16 v[70:73], v[172:175], v[226:229], v[70:73]
	v_mfma_f32_16x16x32_bf16 v[66:69], v[180:183], v[226:229], v[66:69]
	s_barrier
	s_add_i32 s16, s16, s4
	v_lshl_add_u64 v[152:153], s[0:1], 0, v[132:133]
	s_mov_b32 m0, s16
	ds_read_b128 v[184:187], v170 offset:16384
	ds_read_b128 v[188:191], v170 offset:17408
	ds_read_b128 v[192:195], v170 offset:18432
	ds_read_b128 v[210:213], v170 offset:19456
	ds_read_b128 v[214:217], v170 offset:20480
	ds_read_b128 v[218:221], v170 offset:21504
	ds_read_b128 v[222:225], v170 offset:22528
	ds_read_b128 v[226:229], v170 offset:23552
	global_load_lds_dwordx4 v[152:153], off
	s_add_i32 m0, s16, 0x2000
	s_add_u32 s16, s0, 0x160000
	v_lshl_add_u64 v[168:169], s[0:1], 0, v[130:131]
	s_addc_u32 s17, s1, 0
	s_add_i32 s33, s33, s4
	global_load_lds_dwordx4 v[168:169], off
	v_lshl_add_u64 v[196:197], s[16:17], 0, v[132:133]
	s_mov_b32 m0, s33
	v_lshl_add_u64 v[230:231], s[30:31], 0, v[130:131]
	global_load_lds_dwordx4 v[196:197], off
	v_lshl_add_u64 v[196:197], s[16:17], 0, v[130:131]
	s_add_i32 m0, s33, 0x2000
	s_nop 0
	global_load_lds_dwordx4 v[196:197], off
	v_lshl_add_u64 v[196:197], s[30:31], 0, v[132:133]
	s_mov_b32 m0, s6
	s_nop 0
	global_load_lds_dwordx4 v[196:197], off
	s_mov_b32 m0, s7
	s_nop 0
	global_load_lds_dwordx4 v[230:231], off
	s_waitcnt vmcnt(8)
	s_waitcnt lgkmcnt(0)
	s_barrier
; #define PG8_STAGE(bufoff, gbase, voff) do { _Pragma("unroll") for (int _i = 0; _i < 2; ++_i) \
;         __builtin_amdgcn_global_load_lds((const unsigned*)((const char*)(gbase) + (voff)[_i]), (LAS unsigned*)(lds + (bufoff) + ldsw + _i * 8192), 16, 0, 0); } while (0)
; #define PG8_LDA(dst, b, h) do { _Pragma("unroll") for (int m = 0; m < 4; ++m) _Pragma("unroll") for (int k = 0; k < 2; ++k) dst[m][k] = *(const LAS bf16x8*)(lds + PG8_SA(b, h) + aoff + m * 2048 + k * 1024); } while (0)
; #define PG8_LDB(dst, b, h) do { _Pragma("unroll") for (int n = 0; n < 2; ++n) _Pragma("unroll") for (int k = 0; k < 2; ++k) dst[n][k] = *(const LAS bf16x8*)(lds + PG8_SB(b, h) + boff + n * 2048 + k * 1024); } while (0)
; #define PG8_MMA(ai, bj, At, Bt) do { __builtin_amdgcn_s_setprio(1); _Pragma("unroll") for (int m = 0; m < 4; ++m) _Pragma("unroll") for (int n = 0; n < 2; ++n) _Pragma("unroll") for (int k = 0; k < 2; ++k) \
;         acc[ai][bj][m][n] = __builtin_amdgcn_mfma_f32_16x16x32_bf16(Bt[n][k], At[m][k], acc[ai][bj][m][n], 0, 0, 0); __builtin_amdgcn_s_setprio(0); } while (0)
; #define PG8_WAIT_V(n) asm volatile("s_waitcnt vmcnt(" #n ")" ::: "memory")
; #define PG8_WAIT_L(n) asm volatile("s_waitcnt lgkmcnt(" #n ")" ::: "memory")
; #define PG8_BAR __builtin_amdgcn_s_barrier()
; #define PG8_SCHED __builtin_amdgcn_sched_barrier(0)
; template <class Epi, class Sched = StaticOrder, bool ALIGN_EPI = true>
; __device__ __forceinline__ void gemm_phase(LAS unsigned char* lds, const Gemm g, const Sched& S, const Epi& E) {
;     ...
;             PG8_WAIT_V(8); PG8_WAIT_L(0); PG8_BAR; PG8_MMA(1, 0, At, B0); PG8_MMA(1, 1, At, B1); PG8_BAR; PG8_SCHED;
;             PG8_LDB(B0, 1, 0); PG8_LDB(B1, 1, 1); PG8_SCHED; PG8_LDA(At, 1, 0); PG8_STAGE(PG8_SA(0, 1), a2 + hstep, voffA);
;             PG8_WAIT_V(8); PG8_WAIT_L(0); PG8_BAR; PG8_MMA(0, 0, At, B0); PG8_MMA(0, 1, At, B1); PG8_BAR; PG8_SCHED;
	s_waitcnt lgkmcnt(0)
	v_mfma_f32_16x16x32_bf16 v[62:65], v[140:143], v[184:187], 0
	v_mfma_f32_16x16x32_bf16 v[58:61], v[148:151], v[184:187], 0
	v_mfma_f32_16x16x32_bf16 v[50:53], v[140:143], v[192:195], 0
	v_mfma_f32_16x16x32_bf16 v[42:45], v[148:151], v[192:195], 0
	v_mfma_f32_16x16x32_bf16 v[34:37], v[140:143], v[214:217], 0
	v_mfma_f32_16x16x32_bf16 v[26:29], v[148:151], v[214:217], 0
	v_mfma_f32_16x16x32_bf16 v[18:21], v[140:143], v[222:225], 0
	v_mfma_f32_16x16x32_bf16 v[10:13], v[148:151], v[222:225], 0
	v_mfma_f32_16x16x32_bf16 v[62:65], v[144:147], v[188:191], v[62:65]
	v_mfma_f32_16x16x32_bf16 v[58:61], v[160:163], v[188:191], v[58:61]
	v_mfma_f32_16x16x32_bf16 v[50:53], v[144:147], v[210:213], v[50:53]
	v_mfma_f32_16x16x32_bf16 v[42:45], v[160:163], v[210:213], v[42:45]
	v_mfma_f32_16x16x32_bf16 v[34:37], v[144:147], v[218:221], v[34:37]
	v_mfma_f32_16x16x32_bf16 v[26:29], v[160:163], v[218:221], v[26:29]
	v_mfma_f32_16x16x32_bf16 v[18:21], v[144:147], v[226:229], v[18:21]
	v_mfma_f32_16x16x32_bf16 v[10:13], v[160:163], v[226:229], v[10:13]
	v_mfma_f32_16x16x32_bf16 v[54:57], v[164:167], v[184:187], 0
	v_mfma_f32_16x16x32_bf16 v[46:49], v[176:179], v[184:187], 0
	v_mfma_f32_16x16x32_bf16 v[38:41], v[164:167], v[192:195], 0
	v_mfma_f32_16x16x32_bf16 v[30:33], v[176:179], v[192:195], 0
	v_mfma_f32_16x16x32_bf16 v[22:25], v[164:167], v[214:217], 0
	v_mfma_f32_16x16x32_bf16 v[14:17], v[176:179], v[214:217], 0
	v_mfma_f32_16x16x32_bf16 v[6:9], v[164:167], v[222:225], 0
	v_mfma_f32_16x16x32_bf16 v[2:5], v[176:179], v[222:225], 0
	v_mfma_f32_16x16x32_bf16 v[54:57], v[172:175], v[188:191], v[54:57]
	v_mfma_f32_16x16x32_bf16 v[46:49], v[180:183], v[188:191], v[46:49]
	v_mfma_f32_16x16x32_bf16 v[38:41], v[172:175], v[210:213], v[38:41]
	v_mfma_f32_16x16x32_bf16 v[30:33], v[180:183], v[210:213], v[30:33]
	v_mfma_f32_16x16x32_bf16 v[22:25], v[172:175], v[218:221], v[22:25]
	v_mfma_f32_16x16x32_bf16 v[14:17], v[180:183], v[218:221], v[14:17]
	v_mfma_f32_16x16x32_bf16 v[6:9], v[172:175], v[226:229], v[6:9]
	v_mfma_f32_16x16x32_bf16 v[2:5], v[180:183], v[226:229], v[2:5]
	s_barrier
	s_add_i32 s33, 0, 0x18000
	s_add_i32 s44, 0, 0x1c000
	v_add_u32_e32 v160, s33, v135
	v_add_u32_e32 v171, s44, v135
	ds_read_b128 v[140:143], v160
	ds_read_b128 v[144:147], v160 offset:1024
	ds_read_b128 v[148:151], v160 offset:2048
	ds_read_b128 v[160:163], v160 offset:3072
	ds_read_b128 v[164:167], v171
	ds_read_b128 v[172:175], v171 offset:1024
	ds_read_b128 v[176:179], v171 offset:2048
	ds_read_b128 v[180:183], v171 offset:3072
	s_add_u32 s16, s30, 0x160000
	s_addc_u32 s17, s31, 0
	s_mov_b32 m0, s8
	v_lshl_add_u64 v[232:233], s[16:17], 0, v[132:133]
	ds_read_b128 v[184:187], v170 offset:32768
	ds_read_b128 v[188:191], v170 offset:33792
	ds_read_b128 v[192:195], v170 offset:34816
	ds_read_b128 v[210:213], v170 offset:35840
	ds_read_b128 v[214:217], v170 offset:36864
	ds_read_b128 v[218:221], v170 offset:37888
	ds_read_b128 v[222:225], v170 offset:38912
	ds_read_b128 v[226:229], v170 offset:39936
	global_load_lds_dwordx4 v[232:233], off
	v_lshl_add_u64 v[232:233], s[16:17], 0, v[130:131]
	s_mov_b32 m0, s9
	s_nop 0
	global_load_lds_dwordx4 v[232:233], off
	s_waitcnt vmcnt(8)
	s_waitcnt lgkmcnt(0)
	s_barrier
	s_waitcnt lgkmcnt(0)
	v_mfma_f32_16x16x32_bf16 v[126:129], v[140:143], v[184:187], v[126:129]
	v_mfma_f32_16x16x32_bf16 v[122:125], v[148:151], v[184:187], v[122:125]
	v_mfma_f32_16x16x32_bf16 v[118:121], v[140:143], v[192:195], v[118:121]
	v_mfma_f32_16x16x32_bf16 v[106:109], v[148:151], v[192:195], v[106:109]
	v_mfma_f32_16x16x32_bf16 v[98:101], v[140:143], v[214:217], v[98:101]
	v_mfma_f32_16x16x32_bf16 v[90:93], v[148:151], v[214:217], v[90:93]
	v_mfma_f32_16x16x32_bf16 v[82:85], v[140:143], v[222:225], v[82:85]
	v_mfma_f32_16x16x32_bf16 v[74:77], v[148:151], v[222:225], v[74:77]
	v_mfma_f32_16x16x32_bf16 v[126:129], v[144:147], v[188:191], v[126:129]
	v_mfma_f32_16x16x32_bf16 v[122:125], v[160:163], v[188:191], v[122:125]
	v_mfma_f32_16x16x32_bf16 v[118:121], v[144:147], v[210:213], v[118:121]
	v_mfma_f32_16x16x32_bf16 v[106:109], v[160:163], v[210:213], v[106:109]
	v_mfma_f32_16x16x32_bf16 v[98:101], v[144:147], v[218:221], v[98:101]
	v_mfma_f32_16x16x32_bf16 v[90:93], v[160:163], v[218:221], v[90:93]
	v_mfma_f32_16x16x32_bf16 v[82:85], v[144:147], v[226:229], v[82:85]
	v_mfma_f32_16x16x32_bf16 v[74:77], v[160:163], v[226:229], v[74:77]
	v_mfma_f32_16x16x32_bf16 v[114:117], v[164:167], v[184:187], v[114:117]
	v_mfma_f32_16x16x32_bf16 v[110:113], v[176:179], v[184:187], v[110:113]
	v_mfma_f32_16x16x32_bf16 v[102:105], v[164:167], v[192:195], v[102:105]
	v_mfma_f32_16x16x32_bf16 v[94:97], v[176:179], v[192:195], v[94:97]
	v_mfma_f32_16x16x32_bf16 v[86:89], v[164:167], v[214:217], v[86:89]
	v_mfma_f32_16x16x32_bf16 v[78:81], v[176:179], v[214:217], v[78:81]
	v_mfma_f32_16x16x32_bf16 v[70:73], v[164:167], v[222:225], v[70:73]
	v_mfma_f32_16x16x32_bf16 v[66:69], v[176:179], v[222:225], v[66:69]
	v_mfma_f32_16x16x32_bf16 v[114:117], v[172:175], v[188:191], v[114:117]
	v_mfma_f32_16x16x32_bf16 v[110:113], v[180:183], v[188:191], v[110:113]
	v_mfma_f32_16x16x32_bf16 v[102:105], v[172:175], v[210:213], v[102:105]
	v_mfma_f32_16x16x32_bf16 v[94:97], v[180:183], v[210:213], v[94:97]
	v_mfma_f32_16x16x32_bf16 v[86:89], v[172:175], v[218:221], v[86:89]
	v_mfma_f32_16x16x32_bf16 v[78:81], v[180:183], v[218:221], v[78:81]
	v_mfma_f32_16x16x32_bf16 v[70:73], v[172:175], v[226:229], v[70:73]
	v_mfma_f32_16x16x32_bf16 v[66:69], v[180:183], v[226:229], v[66:69]
	s_barrier
; #define PG8_STAGE(bufoff, gbase, voff) do { _Pragma("unroll") for (int _i = 0; _i < 2; ++_i) \
;         __builtin_amdgcn_global_load_lds((const unsigned*)((const char*)(gbase) + (voff)[_i]), (LAS unsigned*)(lds + (bufoff) + ldsw + _i * 8192), 16, 0, 0); } while (0)
; #define PG8_LDA(dst, b, h) do { _Pragma("unroll") for (int m = 0; m < 4; ++m) _Pragma("unroll") for (int k = 0; k < 2; ++k) dst[m][k] = *(const LAS bf16x8*)(lds + PG8_SA(b, h) + aoff + m * 2048 + k * 1024); } while (0)
; #define PG8_LDB(dst, b, h) do { _Pragma("unroll") for (int n = 0; n < 2; ++n) _Pragma("unroll") for (int k = 0; k < 2; ++k) dst[n][k] = *(const LAS bf16x8*)(lds + PG8_SB(b, h) + boff + n * 2048 + k * 1024); } while (0)
; #define PG8_MMA(ai, bj, At, Bt) do { __builtin_amdgcn_s_setprio(1); _Pragma("unroll") for (int m = 0; m < 4; ++m) _Pragma("unroll") for (int n = 0; n < 2; ++n) _Pragma("unroll") for (int k = 0; k < 2; ++k) \
;         acc[ai][bj][m][n] = __builtin_amdgcn_mfma_f32_16x16x32_bf16(Bt[n][k], At[m][k], acc[ai][bj][m][n], 0, 0, 0); __builtin_amdgcn_s_setprio(0); } while (0)
; #define PG8_WAIT_V(n) asm volatile("s_waitcnt vmcnt(" #n ")" ::: "memory")
; template <class Epi, class Sched = StaticOrder, bool ALIGN_EPI = true>
; __device__ __forceinline__ void gemm_phase(LAS unsigned char* lds, const Gemm g, const Sched& S, const Epi& E) {
;     ...
;             PG8_LDB(B0, 0, 0); PG8_LDB(B1, 0, 1); PG8_SCHED; PG8_LDA(At, 0, 0); PG8_STAGE(PG8_SA(1, 1), a1 + hstep, voffA);
;             PG8_WAIT_V(8); PG8_WAIT_L(0); PG8_BAR; PG8_MMA(0, 0, At, B0); PG8_MMA(0, 1, At, B1); PG8_BAR; PG8_SCHED;
;             PG8_LDA(At, 0, 1); PG8_STAGE(PG8_SB(0, 0), b2, voffB); PG8_STAGE(PG8_SB(0, 1), b2 + hstep, voffB); PG8_STAGE(PG8_SA(0, 0), a2, voffA);
;             PG8_WAIT_V(8); PG8_WAIT_L(0); PG8_BAR; PG8_MMA(1, 0, At, B0); PG8_MMA(1, 1, At, B1); PG8_BAR; PG8_SCHED;
;             PG8_LDB(B0, 1, 0); PG8_LDB(B1, 1, 1); PG8_SCHED; PG8_LDA(At, 1, 0); PG8_STAGE(PG8_SA(0, 1), a2 + hstep, voffA);
;             PG8_WAIT_V(8); PG8_WAIT_L(0); PG8_BAR; PG8_MMA(0, 0, At, B0); PG8_MMA(0, 1, At, B1); PG8_BAR; PG8_SCHED;
;             PG8_LDA(At, 1, 1); PG8_STAGE(PG8_SB(1, 0), b3, voffB); PG8_STAGE(PG8_SB(1, 1), b3 + hstep, voffB); PG8_STAGE(PG8_SA(1, 0), a3, voffA);
;             PG8_WAIT_V(8); PG8_WAIT_L(0); PG8_BAR; PG8_MMA(1, 0, At, B0); PG8_MMA(1, 1, At, B1); PG8_BAR; PG8_SCHED;
	s_add_i32 s16, s33, s4
	v_lshl_add_u64 v[152:153], v[152:153], 0, s[34:35]
	s_mov_b32 m0, s16
	ds_read_b128 v[184:187], v170 offset:49152
	ds_read_b128 v[188:191], v170 offset:50176
	ds_read_b128 v[192:195], v170 offset:51200
	ds_read_b128 v[210:213], v170 offset:52224
	ds_read_b128 v[214:217], v170 offset:53248
	ds_read_b128 v[218:221], v170 offset:54272
	ds_read_b128 v[222:225], v170 offset:55296
	ds_read_b128 v[226:229], v170 offset:56320
	global_load_lds_dwordx4 v[152:153], off
	s_add_i32 m0, s16, 0x2000
	s_add_u32 s0, s0, 0x160080
	v_lshl_add_u64 v[152:153], v[168:169], 0, s[34:35]
	s_addc_u32 s1, s1, 0
	s_add_i32 s16, s44, s4
	global_load_lds_dwordx4 v[152:153], off
	v_lshl_add_u64 v[152:153], s[0:1], 0, v[132:133]
	s_mov_b32 m0, s16
	s_nop 0
	global_load_lds_dwordx4 v[152:153], off
	v_lshl_add_u64 v[152:153], s[0:1], 0, v[130:131]
	s_add_i32 m0, s16, 0x2000
	s_nop 0
	global_load_lds_dwordx4 v[152:153], off
	v_lshl_add_u64 v[152:153], v[196:197], 0, s[34:35]
	s_mov_b32 m0, s10
	s_nop 0
	global_load_lds_dwordx4 v[152:153], off
	v_lshl_add_u64 v[152:153], v[230:231], 0, s[34:35]
	s_mov_b32 m0, s11
	s_nop 0
	global_load_lds_dwordx4 v[152:153], off
	s_waitcnt vmcnt(8)
	s_waitcnt lgkmcnt(0)
	s_barrier
	s_waitcnt lgkmcnt(0)
	v_mfma_f32_16x16x32_bf16 v[62:65], v[140:143], v[184:187], v[62:65]
	v_mfma_f32_16x16x32_bf16 v[58:61], v[148:151], v[184:187], v[58:61]
	v_mfma_f32_16x16x32_bf16 v[50:53], v[140:143], v[192:195], v[50:53]
	v_mfma_f32_16x16x32_bf16 v[42:45], v[148:151], v[192:195], v[42:45]
	v_mfma_f32_16x16x32_bf16 v[34:37], v[140:143], v[214:217], v[34:37]
	v_mfma_f32_16x16x32_bf16 v[26:29], v[148:151], v[214:217], v[26:29]
	v_mfma_f32_16x16x32_bf16 v[18:21], v[140:143], v[222:225], v[18:21]
	v_mfma_f32_16x16x32_bf16 v[10:13], v[148:151], v[222:225], v[10:13]
	v_mfma_f32_16x16x32_bf16 v[62:65], v[144:147], v[188:191], v[62:65]
	v_mfma_f32_16x16x32_bf16 v[58:61], v[160:163], v[188:191], v[58:61]
	v_mfma_f32_16x16x32_bf16 v[50:53], v[144:147], v[210:213], v[50:53]
	v_mfma_f32_16x16x32_bf16 v[42:45], v[160:163], v[210:213], v[42:45]
	v_mfma_f32_16x16x32_bf16 v[34:37], v[144:147], v[218:221], v[34:37]
	v_mfma_f32_16x16x32_bf16 v[26:29], v[160:163], v[218:221], v[26:29]
	v_mfma_f32_16x16x32_bf16 v[18:21], v[144:147], v[226:229], v[18:21]
	v_mfma_f32_16x16x32_bf16 v[10:13], v[160:163], v[226:229], v[10:13]
	v_mfma_f32_16x16x32_bf16 v[54:57], v[164:167], v[184:187], v[54:57]
	v_mfma_f32_16x16x32_bf16 v[46:49], v[176:179], v[184:187], v[46:49]
	v_mfma_f32_16x16x32_bf16 v[38:41], v[164:167], v[192:195], v[38:41]
	v_mfma_f32_16x16x32_bf16 v[30:33], v[176:179], v[192:195], v[30:33]
	v_mfma_f32_16x16x32_bf16 v[22:25], v[164:167], v[214:217], v[22:25]
	v_mfma_f32_16x16x32_bf16 v[14:17], v[176:179], v[214:217], v[14:17]
	v_mfma_f32_16x16x32_bf16 v[6:9], v[164:167], v[222:225], v[6:9]
	v_mfma_f32_16x16x32_bf16 v[2:5], v[176:179], v[222:225], v[2:5]
	v_mfma_f32_16x16x32_bf16 v[54:57], v[172:175], v[188:191], v[54:57]
	v_mfma_f32_16x16x32_bf16 v[46:49], v[180:183], v[188:191], v[46:49]
	v_mfma_f32_16x16x32_bf16 v[38:41], v[172:175], v[210:213], v[38:41]
	v_mfma_f32_16x16x32_bf16 v[30:33], v[180:183], v[210:213], v[30:33]
	v_mfma_f32_16x16x32_bf16 v[22:25], v[172:175], v[218:221], v[22:25]
	v_mfma_f32_16x16x32_bf16 v[14:17], v[180:183], v[218:221], v[14:17]
	v_mfma_f32_16x16x32_bf16 v[6:9], v[172:175], v[226:229], v[6:9]
	v_mfma_f32_16x16x32_bf16 v[2:5], v[180:183], v[226:229], v[2:5]
	s_barrier
	s_add_i32 s82, s82, 2
	s_add_u32 s79, s79, 0x100
	s_addc_u32 s92, s92, 0
	s_cmpk_gt_u32 s82, 0x55
	s_mov_b64 s[44:45], s[46:47]
	s_cbranch_scc0 .LBB0_392
.LBB0_392:
	s_add_u32 s46, s44, 0x100
	s_addc_u32 s47, s45, 0
	s_add_i32 s16, 0, 0x10000
	s_cmpk_eq_i32 s82, 0x54
	s_cselect_b32 s31, s37, s47
	s_cselect_b32 s30, s36, s46
	v_add_u32_e32 v152, s16, v135
	s_cselect_b32 s1, s43, s92
	s_cselect_b32 s0, s42, s79
	s_add_i32 s33, 0, 0x14000
	ds_read_b128 v[140:143], v152
	ds_read_b128 v[144:147], v152 offset:1024
	ds_read_b128 v[148:151], v152 offset:2048
	ds_read_b128 v[160:163], v152 offset:3072
	v_add_u32_e32 v152, s33, v135
	ds_read_b128 v[164:167], v152
	ds_read_b128 v[172:175], v152 offset:1024
	ds_read_b128 v[176:179], v152 offset:2048
	ds_read_b128 v[180:183], v152 offset:3072
	v_lshl_add_u64 v[152:153], s[44:45], 0, v[136:137]
	s_add_i32 m0, s6, 0xc000
	ds_read_b128 v[184:187], v170
	ds_read_b128 v[188:191], v170 offset:1024
	ds_read_b128 v[192:195], v170 offset:2048
	ds_read_b128 v[210:213], v170 offset:3072
	ds_read_b128 v[214:217], v170 offset:4096
	ds_read_b128 v[218:221], v170 offset:5120
	ds_read_b128 v[222:225], v170 offset:6144
	ds_read_b128 v[226:229], v170 offset:7168
	global_load_lds_dwordx4 v[152:153], off
	v_lshl_add_u64 v[152:153], s[44:45], 0, v[138:139]
	s_add_i32 m0, s6, 0xe000
	s_nop 0
	global_load_lds_dwordx4 v[152:153], off
	s_waitcnt vmcnt(8)
	s_waitcnt lgkmcnt(0)
	s_barrier
; #define PG8_STAGE(bufoff, gbase, voff) do { _Pragma("unroll") for (int _i = 0; _i < 2; ++_i) \
;         __builtin_amdgcn_global_load_lds((const unsigned*)((const char*)(gbase) + (voff)[_i]), (LAS unsigned*)(lds + (bufoff) + ldsw + _i * 8192), 16, 0, 0); } while (0)
; #define PG8_LDA(dst, b, h) do { _Pragma("unroll") for (int m = 0; m < 4; ++m) _Pragma("unroll") for (int k = 0; k < 2; ++k) dst[m][k] = *(const LAS bf16x8*)(lds + PG8_SA(b, h) + aoff + m * 2048 + k * 1024); } while (0)
; #define PG8_MMA(ai, bj, At, Bt) do { __builtin_amdgcn_s_setprio(1); _Pragma("unroll") for (int m = 0; m < 4; ++m) _Pragma("unroll") for (int n = 0; n < 2; ++n) _Pragma("unroll") for (int k = 0; k < 2; ++k) \
;         acc[ai][bj][m][n] = __builtin_amdgcn_mfma_f32_16x16x32_bf16(Bt[n][k], At[m][k], acc[ai][bj][m][n], 0, 0, 0); __builtin_amdgcn_s_setprio(0); } while (0)
; #define PG8_WAIT_V(n) asm volatile("s_waitcnt vmcnt(" #n ")" ::: "memory")
; #define PG8_WAIT_L(n) asm volatile("s_waitcnt lgkmcnt(" #n ")" ::: "memory")
; #define PG8_BAR __builtin_amdgcn_s_barrier()
; #define PG8_SCHED __builtin_amdgcn_sched_barrier(0)
; template <class Epi, class Sched = StaticOrder, bool ALIGN_EPI = true>
; __device__ __forceinline__ void gemm_phase(LAS unsigned char* lds, const Gemm g, const Sched& S, const Epi& E) {
;     ...
;             PG8_WAIT_V(8); PG8_WAIT_L(0); PG8_BAR; PG8_MMA(0, 0, At, B0); PG8_MMA(0, 1, At, B1); PG8_BAR; PG8_SCHED;
;             PG8_LDA(At, 0, 1); PG8_STAGE(PG8_SB(0, 0), b2, voffB); PG8_STAGE(PG8_SB(0, 1), b2 + hstep, voffB); PG8_STAGE(PG8_SA(0, 0), a2, voffA);
;             PG8_WAIT_V(8); PG8_WAIT_L(0); PG8_BAR; PG8_MMA(1, 0, At, B0); PG8_MMA(1, 1, At, B1); PG8_BAR; PG8_SCHED;
	s_waitcnt lgkmcnt(0)
	v_mfma_f32_16x16x32_bf16 v[126:129], v[140:143], v[184:187], v[126:129]
	v_mfma_f32_16x16x32_bf16 v[122:125], v[148:151], v[184:187], v[122:125]
	v_mfma_f32_16x16x32_bf16 v[118:121], v[140:143], v[192:195], v[118:121]
	v_mfma_f32_16x16x32_bf16 v[106:109], v[148:151], v[192:195], v[106:109]
	v_mfma_f32_16x16x32_bf16 v[98:101], v[140:143], v[214:217], v[98:101]
	v_mfma_f32_16x16x32_bf16 v[90:93], v[148:151], v[214:217], v[90:93]
	v_mfma_f32_16x16x32_bf16 v[82:85], v[140:143], v[222:225], v[82:85]
	v_mfma_f32_16x16x32_bf16 v[74:77], v[148:151], v[222:225], v[74:77]
	v_mfma_f32_16x16x32_bf16 v[126:129], v[144:147], v[188:191], v[126:129]
	v_mfma_f32_16x16x32_bf16 v[122:125], v[160:163], v[188:191], v[122:125]
	v_mfma_f32_16x16x32_bf16 v[118:121], v[144:147], v[210:213], v[118:121]
	v_mfma_f32_16x16x32_bf16 v[106:109], v[160:163], v[210:213], v[106:109]
	v_mfma_f32_16x16x32_bf16 v[98:101], v[144:147], v[218:221], v[98:101]
	v_mfma_f32_16x16x32_bf16 v[90:93], v[160:163], v[218:221], v[90:93]
	v_mfma_f32_16x16x32_bf16 v[82:85], v[144:147], v[226:229], v[82:85]
	v_mfma_f32_16x16x32_bf16 v[74:77], v[160:163], v[226:229], v[74:77]
	v_mfma_f32_16x16x32_bf16 v[114:117], v[164:167], v[184:187], v[114:117]
	v_mfma_f32_16x16x32_bf16 v[110:113], v[176:179], v[184:187], v[110:113]
	v_mfma_f32_16x16x32_bf16 v[102:105], v[164:167], v[192:195], v[102:105]
	v_mfma_f32_16x16x32_bf16 v[94:97], v[176:179], v[192:195], v[94:97]
	v_mfma_f32_16x16x32_bf16 v[86:89], v[164:167], v[214:217], v[86:89]
	v_mfma_f32_16x16x32_bf16 v[78:81], v[176:179], v[214:217], v[78:81]
	v_mfma_f32_16x16x32_bf16 v[70:73], v[164:167], v[222:225], v[70:73]
	v_mfma_f32_16x16x32_bf16 v[66:69], v[176:179], v[222:225], v[66:69]
	v_mfma_f32_16x16x32_bf16 v[114:117], v[172:175], v[188:191], v[114:117]
	v_mfma_f32_16x16x32_bf16 v[110:113], v[180:183], v[188:191], v[110:113]
	v_mfma_f32_16x16x32_bf16 v[102:105], v[172:175], v[210:213], v[102:105]
	v_mfma_f32_16x16x32_bf16 v[94:97], v[180:183], v[210:213], v[94:97]
	v_mfma_f32_16x16x32_bf16 v[86:89], v[172:175], v[218:221], v[86:89]
	v_mfma_f32_16x16x32_bf16 v[78:81], v[180:183], v[218:221], v[78:81]
	v_mfma_f32_16x16x32_bf16 v[70:73], v[172:175], v[226:229], v[70:73]
	v_mfma_f32_16x16x32_bf16 v[66:69], v[180:183], v[226:229], v[66:69]
	s_barrier
	s_add_i32 s16, s16, s4
	v_lshl_add_u64 v[152:153], s[0:1], 0, v[132:133]
	s_mov_b32 m0, s16
	ds_read_b128 v[184:187], v170 offset:16384
	ds_read_b128 v[188:191], v170 offset:17408
	ds_read_b128 v[192:195], v170 offset:18432
	ds_read_b128 v[210:213], v170 offset:19456
	ds_read_b128 v[214:217], v170 offset:20480
	ds_read_b128 v[218:221], v170 offset:21504
	ds_read_b128 v[222:225], v170 offset:22528
	ds_read_b128 v[226:229], v170 offset:23552
	global_load_lds_dwordx4 v[152:153], off
	s_add_i32 m0, s16, 0x2000
	s_add_u32 s16, s0, 0x160000
	v_lshl_add_u64 v[168:169], s[0:1], 0, v[130:131]
	s_addc_u32 s17, s1, 0
	s_add_i32 s33, s33, s4
	global_load_lds_dwordx4 v[168:169], off
	v_lshl_add_u64 v[196:197], s[16:17], 0, v[132:133]
	s_mov_b32 m0, s33
	v_lshl_add_u64 v[230:231], s[30:31], 0, v[130:131]
	global_load_lds_dwordx4 v[196:197], off
	v_lshl_add_u64 v[196:197], s[16:17], 0, v[130:131]
	s_add_i32 m0, s33, 0x2000
	s_nop 0
	global_load_lds_dwordx4 v[196:197], off
	v_lshl_add_u64 v[196:197], s[30:31], 0, v[132:133]
	s_mov_b32 m0, s6
	s_nop 0
	global_load_lds_dwordx4 v[196:197], off
	s_mov_b32 m0, s7
	s_nop 0
	global_load_lds_dwordx4 v[230:231], off
	s_waitcnt vmcnt(8)
	s_waitcnt lgkmcnt(0)
	s_barrier
	s_waitcnt lgkmcnt(0)
	v_mfma_f32_16x16x32_bf16 v[62:65], v[140:143], v[184:187], v[62:65]
	v_mfma_f32_16x16x32_bf16 v[58:61], v[148:151], v[184:187], v[58:61]
	v_mfma_f32_16x16x32_bf16 v[50:53], v[140:143], v[192:195], v[50:53]
	v_mfma_f32_16x16x32_bf16 v[42:45], v[148:151], v[192:195], v[42:45]
	v_mfma_f32_16x16x32_bf16 v[34:37], v[140:143], v[214:217], v[34:37]
	v_mfma_f32_16x16x32_bf16 v[26:29], v[148:151], v[214:217], v[26:29]
	v_mfma_f32_16x16x32_bf16 v[18:21], v[140:143], v[222:225], v[18:21]
	v_mfma_f32_16x16x32_bf16 v[10:13], v[148:151], v[222:225], v[10:13]
	v_mfma_f32_16x16x32_bf16 v[62:65], v[144:147], v[188:191], v[62:65]
	v_mfma_f32_16x16x32_bf16 v[58:61], v[160:163], v[188:191], v[58:61]
	v_mfma_f32_16x16x32_bf16 v[50:53], v[144:147], v[210:213], v[50:53]
	v_mfma_f32_16x16x32_bf16 v[42:45], v[160:163], v[210:213], v[42:45]
	v_mfma_f32_16x16x32_bf16 v[34:37], v[144:147], v[218:221], v[34:37]
	v_mfma_f32_16x16x32_bf16 v[26:29], v[160:163], v[218:221], v[26:29]
	v_mfma_f32_16x16x32_bf16 v[18:21], v[144:147], v[226:229], v[18:21]
	v_mfma_f32_16x16x32_bf16 v[10:13], v[160:163], v[226:229], v[10:13]
	v_mfma_f32_16x16x32_bf16 v[54:57], v[164:167], v[184:187], v[54:57]
	v_mfma_f32_16x16x32_bf16 v[46:49], v[176:179], v[184:187], v[46:49]
	v_mfma_f32_16x16x32_bf16 v[38:41], v[164:167], v[192:195], v[38:41]
	v_mfma_f32_16x16x32_bf16 v[30:33], v[176:179], v[192:195], v[30:33]
	v_mfma_f32_16x16x32_bf16 v[22:25], v[164:167], v[214:217], v[22:25]
	v_mfma_f32_16x16x32_bf16 v[14:17], v[176:179], v[214:217], v[14:17]
	v_mfma_f32_16x16x32_bf16 v[6:9], v[164:167], v[222:225], v[6:9]
	v_mfma_f32_16x16x32_bf16 v[2:5], v[176:179], v[222:225], v[2:5]
	v_mfma_f32_16x16x32_bf16 v[54:57], v[172:175], v[188:191], v[54:57]
	v_mfma_f32_16x16x32_bf16 v[46:49], v[180:183], v[188:191], v[46:49]
	v_mfma_f32_16x16x32_bf16 v[38:41], v[172:175], v[210:213], v[38:41]
	v_mfma_f32_16x16x32_bf16 v[30:33], v[180:183], v[210:213], v[30:33]
	v_mfma_f32_16x16x32_bf16 v[22:25], v[172:175], v[218:221], v[22:25]
	v_mfma_f32_16x16x32_bf16 v[14:17], v[180:183], v[218:221], v[14:17]
	v_mfma_f32_16x16x32_bf16 v[6:9], v[172:175], v[226:229], v[6:9]
	v_mfma_f32_16x16x32_bf16 v[2:5], v[180:183], v[226:229], v[2:5]
	s_barrier
; #define PG8_STAGE(bufoff, gbase, voff) do { _Pragma("unroll") for (int _i = 0; _i < 2; ++_i) \
;         __builtin_amdgcn_global_load_lds((const unsigned*)((const char*)(gbase) + (voff)[_i]), (LAS unsigned*)(lds + (bufoff) + ldsw + _i * 8192), 16, 0, 0); } while (0)
; #define PG8_LDA(dst, b, h) do { _Pragma("unroll") for (int m = 0; m < 4; ++m) _Pragma("unroll") for (int k = 0; k < 2; ++k) dst[m][k] = *(const LAS bf16x8*)(lds + PG8_SA(b, h) + aoff + m * 2048 + k * 1024); } while (0)
; #define PG8_LDB(dst, b, h) do { _Pragma("unroll") for (int n = 0; n < 2; ++n) _Pragma("unroll") for (int k = 0; k < 2; ++k) dst[n][k] = *(const LAS bf16x8*)(lds + PG8_SB(b, h) + boff + n * 2048 + k * 1024); } while (0)
; #define PG8_MMA(ai, bj, At, Bt) do { __builtin_amdgcn_s_setprio(1); _Pragma("unroll") for (int m = 0; m < 4; ++m) _Pragma("unroll") for (int n = 0; n < 2; ++n) _Pragma("unroll") for (int k = 0; k < 2; ++k) \
;         acc[ai][bj][m][n] = __builtin_amdgcn_mfma_f32_16x16x32_bf16(Bt[n][k], At[m][k], acc[ai][bj][m][n], 0, 0, 0); __builtin_amdgcn_s_setprio(0); } while (0)
; #define PG8_WAIT_V(n) asm volatile("s_waitcnt vmcnt(" #n ")" ::: "memory")
; #define PG8_WAIT_L(n) asm volatile("s_waitcnt lgkmcnt(" #n ")" ::: "memory")
; #define PG8_BAR __builtin_amdgcn_s_barrier()
; #define PG8_SCHED __builtin_amdgcn_sched_barrier(0)
; template <class Epi, class Sched = StaticOrder, bool ALIGN_EPI = true>
; __device__ __forceinline__ void gemm_phase(LAS unsigned char* lds, const Gemm g, const Sched& S, const Epi& E) {
;     ...
;             PG8_LDB(B0, 1, 0); PG8_LDB(B1, 1, 1); PG8_SCHED; PG8_LDA(At, 1, 0); PG8_STAGE(PG8_SA(0, 1), a2 + hstep, voffA);
;             PG8_WAIT_V(8); PG8_WAIT_L(0); PG8_BAR; PG8_MMA(0, 0, At, B0); PG8_MMA(0, 1, At, B1); PG8_BAR; PG8_SCHED;
;             PG8_LDA(At, 1, 1); PG8_STAGE(PG8_SB(1, 0), b3, voffB); PG8_STAGE(PG8_SB(1, 1), b3 + hstep, voffB); PG8_STAGE(PG8_SA(1, 0), a3, voffA);
;             PG8_WAIT_V(8); PG8_WAIT_L(0); PG8_BAR; PG8_MMA(1, 0, At, B0); PG8_MMA(1, 1, At, B1); PG8_BAR; PG8_SCHED;
	s_add_i32 s33, 0, 0x18000
	s_add_i32 s44, 0, 0x1c000
	v_add_u32_e32 v160, s33, v135
	v_add_u32_e32 v171, s44, v135
	ds_read_b128 v[140:143], v160
	ds_read_b128 v[144:147], v160 offset:1024
	ds_read_b128 v[148:151], v160 offset:2048
	ds_read_b128 v[160:163], v160 offset:3072
	ds_read_b128 v[164:167], v171
	ds_read_b128 v[172:175], v171 offset:1024
	ds_read_b128 v[176:179], v171 offset:2048
	ds_read_b128 v[180:183], v171 offset:3072
	s_add_u32 s16, s30, 0x160000
	s_addc_u32 s17, s31, 0
	s_mov_b32 m0, s8
	v_lshl_add_u64 v[232:233], s[16:17], 0, v[132:133]
	ds_read_b128 v[184:187], v170 offset:32768
	ds_read_b128 v[188:191], v170 offset:33792
	ds_read_b128 v[192:195], v170 offset:34816
	ds_read_b128 v[210:213], v170 offset:35840
	ds_read_b128 v[214:217], v170 offset:36864
	ds_read_b128 v[218:221], v170 offset:37888
	ds_read_b128 v[222:225], v170 offset:38912
	ds_read_b128 v[226:229], v170 offset:39936
	global_load_lds_dwordx4 v[232:233], off
	v_lshl_add_u64 v[232:233], s[16:17], 0, v[130:131]
	s_mov_b32 m0, s9
	s_nop 0
	global_load_lds_dwordx4 v[232:233], off
	s_waitcnt vmcnt(8)
	s_waitcnt lgkmcnt(0)
	s_barrier
	s_waitcnt lgkmcnt(0)
	v_mfma_f32_16x16x32_bf16 v[126:129], v[140:143], v[184:187], v[126:129]
	v_mfma_f32_16x16x32_bf16 v[122:125], v[148:151], v[184:187], v[122:125]
	v_mfma_f32_16x16x32_bf16 v[118:121], v[140:143], v[192:195], v[118:121]
	v_mfma_f32_16x16x32_bf16 v[106:109], v[148:151], v[192:195], v[106:109]
	v_mfma_f32_16x16x32_bf16 v[98:101], v[140:143], v[214:217], v[98:101]
	v_mfma_f32_16x16x32_bf16 v[90:93], v[148:151], v[214:217], v[90:93]
	v_mfma_f32_16x16x32_bf16 v[82:85], v[140:143], v[222:225], v[82:85]
	v_mfma_f32_16x16x32_bf16 v[74:77], v[148:151], v[222:225], v[74:77]
	v_mfma_f32_16x16x32_bf16 v[126:129], v[144:147], v[188:191], v[126:129]
	v_mfma_f32_16x16x32_bf16 v[122:125], v[160:163], v[188:191], v[122:125]
	v_mfma_f32_16x16x32_bf16 v[118:121], v[144:147], v[210:213], v[118:121]
	v_mfma_f32_16x16x32_bf16 v[106:109], v[160:163], v[210:213], v[106:109]
	v_mfma_f32_16x16x32_bf16 v[98:101], v[144:147], v[218:221], v[98:101]
	v_mfma_f32_16x16x32_bf16 v[90:93], v[160:163], v[218:221], v[90:93]
	v_mfma_f32_16x16x32_bf16 v[82:85], v[144:147], v[226:229], v[82:85]
	v_mfma_f32_16x16x32_bf16 v[74:77], v[160:163], v[226:229], v[74:77]
	v_mfma_f32_16x16x32_bf16 v[114:117], v[164:167], v[184:187], v[114:117]
	v_mfma_f32_16x16x32_bf16 v[110:113], v[176:179], v[184:187], v[110:113]
	v_mfma_f32_16x16x32_bf16 v[102:105], v[164:167], v[192:195], v[102:105]
	v_mfma_f32_16x16x32_bf16 v[94:97], v[176:179], v[192:195], v[94:97]
	v_mfma_f32_16x16x32_bf16 v[86:89], v[164:167], v[214:217], v[86:89]
	v_mfma_f32_16x16x32_bf16 v[78:81], v[176:179], v[214:217], v[78:81]
	v_mfma_f32_16x16x32_bf16 v[70:73], v[164:167], v[222:225], v[70:73]
	v_mfma_f32_16x16x32_bf16 v[66:69], v[176:179], v[222:225], v[66:69]
	v_mfma_f32_16x16x32_bf16 v[114:117], v[172:175], v[188:191], v[114:117]
	v_mfma_f32_16x16x32_bf16 v[110:113], v[180:183], v[188:191], v[110:113]
	v_mfma_f32_16x16x32_bf16 v[102:105], v[172:175], v[210:213], v[102:105]
	v_mfma_f32_16x16x32_bf16 v[94:97], v[180:183], v[210:213], v[94:97]
	v_mfma_f32_16x16x32_bf16 v[86:89], v[172:175], v[218:221], v[86:89]
	v_mfma_f32_16x16x32_bf16 v[78:81], v[180:183], v[218:221], v[78:81]
	v_mfma_f32_16x16x32_bf16 v[70:73], v[172:175], v[226:229], v[70:73]
	v_mfma_f32_16x16x32_bf16 v[66:69], v[180:183], v[226:229], v[66:69]
	s_barrier
	s_add_i32 s16, s33, s4
	v_lshl_add_u64 v[152:153], v[152:153], 0, s[34:35]
	s_mov_b32 m0, s16
	ds_read_b128 v[184:187], v170 offset:49152
	ds_read_b128 v[188:191], v170 offset:50176
	ds_read_b128 v[192:195], v170 offset:51200
	ds_read_b128 v[210:213], v170 offset:52224
	ds_read_b128 v[214:217], v170 offset:53248
	ds_read_b128 v[218:221], v170 offset:54272
	ds_read_b128 v[222:225], v170 offset:55296
	ds_read_b128 v[226:229], v170 offset:56320
	global_load_lds_dwordx4 v[152:153], off
	s_add_i32 m0, s16, 0x2000
	s_add_u32 s0, s0, 0x160080
	v_lshl_add_u64 v[152:153], v[168:169], 0, s[34:35]
	s_addc_u32 s1, s1, 0
	s_add_i32 s16, s44, s4
	global_load_lds_dwordx4 v[152:153], off
	v_lshl_add_u64 v[152:153], s[0:1], 0, v[132:133]
	s_mov_b32 m0, s16
	s_nop 0
	global_load_lds_dwordx4 v[152:153], off
	v_lshl_add_u64 v[152:153], s[0:1], 0, v[130:131]
	s_add_i32 m0, s16, 0x2000
	s_nop 0
	global_load_lds_dwordx4 v[152:153], off
	v_lshl_add_u64 v[152:153], v[196:197], 0, s[34:35]
	s_mov_b32 m0, s10
	s_nop 0
	global_load_lds_dwordx4 v[152:153], off
	v_lshl_add_u64 v[152:153], v[230:231], 0, s[34:35]
	s_mov_b32 m0, s11
	s_nop 0
	global_load_lds_dwordx4 v[152:153], off
	s_waitcnt vmcnt(8)
	s_waitcnt lgkmcnt(0)
	s_barrier
	s_waitcnt lgkmcnt(0)
	v_mfma_f32_16x16x32_bf16 v[62:65], v[140:143], v[184:187], v[62:65]
	v_mfma_f32_16x16x32_bf16 v[58:61], v[148:151], v[184:187], v[58:61]
	v_mfma_f32_16x16x32_bf16 v[50:53], v[140:143], v[192:195], v[50:53]
	v_mfma_f32_16x16x32_bf16 v[42:45], v[148:151], v[192:195], v[42:45]
	v_mfma_f32_16x16x32_bf16 v[34:37], v[140:143], v[214:217], v[34:37]
	v_mfma_f32_16x16x32_bf16 v[26:29], v[148:151], v[214:217], v[26:29]
	v_mfma_f32_16x16x32_bf16 v[18:21], v[140:143], v[222:225], v[18:21]
	v_mfma_f32_16x16x32_bf16 v[10:13], v[148:151], v[222:225], v[10:13]
	v_mfma_f32_16x16x32_bf16 v[62:65], v[144:147], v[188:191], v[62:65]
	v_mfma_f32_16x16x32_bf16 v[58:61], v[160:163], v[188:191], v[58:61]
	v_mfma_f32_16x16x32_bf16 v[50:53], v[144:147], v[210:213], v[50:53]
	v_mfma_f32_16x16x32_bf16 v[42:45], v[160:163], v[210:213], v[42:45]
	v_mfma_f32_16x16x32_bf16 v[34:37], v[144:147], v[218:221], v[34:37]
	v_mfma_f32_16x16x32_bf16 v[26:29], v[160:163], v[218:221], v[26:29]
	v_mfma_f32_16x16x32_bf16 v[18:21], v[144:147], v[226:229], v[18:21]
	v_mfma_f32_16x16x32_bf16 v[10:13], v[160:163], v[226:229], v[10:13]
	v_mfma_f32_16x16x32_bf16 v[54:57], v[164:167], v[184:187], v[54:57]
	v_mfma_f32_16x16x32_bf16 v[46:49], v[176:179], v[184:187], v[46:49]
	v_mfma_f32_16x16x32_bf16 v[38:41], v[164:167], v[192:195], v[38:41]
	v_mfma_f32_16x16x32_bf16 v[30:33], v[176:179], v[192:195], v[30:33]
	v_mfma_f32_16x16x32_bf16 v[22:25], v[164:167], v[214:217], v[22:25]
	v_mfma_f32_16x16x32_bf16 v[14:17], v[176:179], v[214:217], v[14:17]
	v_mfma_f32_16x16x32_bf16 v[6:9], v[164:167], v[222:225], v[6:9]
	v_mfma_f32_16x16x32_bf16 v[2:5], v[176:179], v[222:225], v[2:5]
	v_mfma_f32_16x16x32_bf16 v[54:57], v[172:175], v[188:191], v[54:57]
	v_mfma_f32_16x16x32_bf16 v[46:49], v[180:183], v[188:191], v[46:49]
	v_mfma_f32_16x16x32_bf16 v[38:41], v[172:175], v[210:213], v[38:41]
	v_mfma_f32_16x16x32_bf16 v[30:33], v[180:183], v[210:213], v[30:33]
	v_mfma_f32_16x16x32_bf16 v[22:25], v[172:175], v[218:221], v[22:25]
	v_mfma_f32_16x16x32_bf16 v[14:17], v[180:183], v[218:221], v[14:17]
	v_mfma_f32_16x16x32_bf16 v[6:9], v[172:175], v[226:229], v[6:9]
	v_mfma_f32_16x16x32_bf16 v[2:5], v[180:183], v[226:229], v[2:5]
	s_barrier
	s_add_i32 s82, s82, 2
	s_add_u32 s79, s79, 0x100
	s_addc_u32 s92, s92, 0
	s_cmpk_gt_u32 s82, 0x55
	s_mov_b64 s[44:45], s[46:47]
	s_cbranch_scc0 .LBB0_392

; #define PG8_WAIT_V(n) asm volatile("s_waitcnt vmcnt(" #n ")" ::: "memory")
; #define PG8_BAR __builtin_amdgcn_s_barrier()
; template <class Epi, class Sched = StaticOrder, bool ALIGN_EPI = true>
; __device__ __forceinline__ void gemm_phase(LAS unsigned char* lds, const Gemm g, const Sched& S, const Epi& E) {
;     ...
;     PG8_WAIT_V(0);
;     if constexpr (!ALIGN_EPI) { if (wr == 0) PG8_BAR; }
;     PG8_BAR;
.LBB0_398:
	s_setprio 0
	s_waitcnt vmcnt(0)
	v_readlane_b32 s16, v254, 43
	v_readlane_b32 s22, v254, 39
	v_readlane_b32 s33, v254, 40
	v_readlane_b32 s17, v254, 44
	v_readlane_b32 s23, v254, 45
	v_readlane_b32 s77, v254, 46
	s_mov_b32 s70, 0x3a000000
	s_barrier

;     __device__ bool next(int i, Unit& u) const { const int idx = i * G + c; if (idx >= 64) return false; u.kp = idx & 3; u.pn = (idx >> 2) & 7; u.pm = 192 + (idx >> 5); return true; }
; #define PG8_STAGE(bufoff, gbase, voff) do { _Pragma("unroll") for (int _i = 0; _i < 2; ++_i) \
;         __builtin_amdgcn_global_load_lds((const unsigned*)((const char*)(gbase) + (voff)[_i]), (LAS unsigned*)(lds + (bufoff) + ldsw + _i * 8192), 16, 0, 0); } while (0)
; #define PG8_WAIT_V(n) asm volatile("s_waitcnt vmcnt(" #n ")" ::: "memory")
; #define PG8_BAR __builtin_amdgcn_s_barrier()
; template <class Epi, class Sched = StaticOrder, bool ALIGN_EPI = true>
; __device__ __forceinline__ void gemm_phase(LAS unsigned char* lds, const Gemm g, const Sched& S, const Epi& E) {
;     ...
;     for (int i = 0; i < 2; ++i) { int R, C; stage_rc(tid * 16 + i * 8192, R, C); const int Rb = Epi::PERM ? ((R & ~31) + perm32(R & 31)) : R;
;         voffA[i] = (unsigned)(R * g.ld + C) * 2u; voffB[i] = (unsigned)(Rb * g.ld + C) * 2u; }
;     const size_t kstep = (size_t)(BK * 2);
;     const size_t hstep = (size_t)HALF * g.ld * 2;
;     const size_t tstep = 2 * hstep;
;     const unsigned ldsw = (unsigned)wid * 1024u;
;     const int aoff = lds_byte(wr * 64 + fr, fq * 8), boff = lds_byte(wc * 32 + fr, fq * 8);
;     ...
;     Unit cur, nxt; int ui = 0;
;     if (!S.next(0, cur)) return;
;     f32x4 acc[2][2][4][2];
; #pragma unroll
;     for (int a = 0; a < 2; ++a)
; #pragma unroll
;         for (int b = 0; b < 2; ++b)
; #pragma unroll
;             for (int m = 0; m < 4; ++m)
; #pragma unroll
;                 for (int n = 0; n < 2; ++n) acc[a][b][m][n] = (f32x4){0.f, 0.f, 0.f, 0.f};
;     bf16x8 At[4][2], B0[2][2], B1[2][2];
;     const char* cA = (const char*)g.A + (size_t)cur.pm * tstep + (size_t)cur.kp * K * 2; const char* cB = (const char*)g.Bt + (size_t)cur.pn * tstep + (size_t)cur.kp * K * 2;
;     PG8_STAGE(PG8_SB(0, 0), cB, voffB); PG8_STAGE(PG8_SB(0, 1), cB + hstep, voffB); PG8_STAGE(PG8_SA(0, 0), cA, voffA); PG8_STAGE(PG8_SA(0, 1), cA + hstep, voffA);
;     if (wr == 1) PG8_BAR;
;     PG8_WAIT_V(2); PG8_BAR;
;     PG8_STAGE(PG8_SB(1, 0), cB + kstep, voffB); PG8_STAGE(PG8_SA(1, 0), cA + kstep, voffA); PG8_STAGE(PG8_SB(1, 1), cB + hstep + kstep, voffB);
;     PG8_WAIT_V(6); PG8_BAR;
.LBB0_461:
	v_lshrrev_b32_e32 v18, 1, v16
	v_and_b32_e32 v18, 24, v18
	s_lshl_b32 s7, s7, 5
	v_and_b32_e32 v17, 15, v16
	v_lshlrev_b32_e32 v19, 1, v18
	v_lshlrev_b32_e32 v16, 2, v16
	s_and_b32 s16, s7, 0x60
	v_lshl_or_b32 v1, s8, 6, v17
	v_lshl_or_b32 v17, v17, 6, v19
	s_lshl_b32 s8, s8, 13
	v_and_b32_e32 v16, 32, v16
	s_lshl_b32 s7, s16, 7
	s_add_i32 m0, s23, 0x18000
	v_lshl_add_u64 v[8:9], v[8:9], 0, s[34:35]
	v_bitop3_b32 v19, v17, s8, v16 bitop3:0xde
	v_bitop3_b32 v144, v17, s7, v16 bitop3:0xde
	s_waitcnt vmcnt(2)
	s_barrier
	global_load_lds_dwordx4 v[8:9], off
	v_lshl_add_u64 v[6:7], v[6:7], 0, s[34:35]
	s_add_i32 m0, s23, 0x1a000
	s_add_i32 s7, s23, 0x8000
	s_add_i32 s8, s23, 0xa000
	global_load_lds_dwordx4 v[6:7], off
	v_lshl_add_u64 v[2:3], v[2:3], 0, s[34:35]
	s_mov_b32 m0, s7
	s_add_u32 s10, s46, 0x80080
	global_load_lds_dwordx4 v[2:3], off
	v_lshl_add_u64 v[2:3], v[4:5], 0, s[34:35]
	s_mov_b32 m0, s8
	s_addc_u32 s11, s47, 0
	global_load_lds_dwordx4 v[2:3], off
	s_add_i32 m0, s23, 0x1c000
	v_lshl_add_u64 v[2:3], s[10:11], 0, v[134:135]
	global_load_lds_dwordx4 v[2:3], off
	v_lshl_add_u64 v[2:3], s[10:11], 0, v[130:131]
	s_add_i32 m0, s23, 0x1e000
	s_cmpk_lt_u32 s9, 0x100
	global_load_lds_dwordx4 v[2:3], off
	v_lshlrev_b32_e32 v2, 15, v14
	v_and_b32_e32 v2, 0xffff0000, v2
	v_lshl_add_u32 v2, v13, 12, v2
	v_and_b32_e32 v3, 1, v14
	v_lshl_or_b32 v2, v3, 6, v2
	v_lshl_add_u32 v138, v15, 1, v2
	v_lshlrev_b32_e32 v2, 15, v10
	v_and_b32_e32 v2, 0xffff0000, v2
	s_waitcnt vmcnt(6)
	v_lshl_add_u32 v2, v11, 12, v2
	v_and_b32_e32 v3, 1, v10
	v_lshl_or_b32 v2, v3, 6, v2
	s_sext_i32_i16 s1, s12
	s_cselect_b64 s[12:13], -1, 0
	v_or_b32_e32 v145, s16, v18
	v_mov_b32_e32 v139, v0
	v_lshl_add_u32 v140, v12, 1, v2
	v_mov_b32_e32 v141, v0
	s_mov_b32 s9, 0
	v_add_u32_e32 v146, 0, v19
	s_barrier
	s_waitcnt vmcnt(0)
	s_cmp_eq_u64 s[2:3], 0
	s_cbranch_scc1 .Lmy_pr_464
	s_setprio 1
.Lmy_pr_464:
	s_branch .LBB0_464
.LBB0_462:
	s_mov_b64 s[0:1], 0

; #define PG8_STAGE(bufoff, gbase, voff) do { _Pragma("unroll") for (int _i = 0; _i < 2; ++_i) \
;         __builtin_amdgcn_global_load_lds((const unsigned*)((const char*)(gbase) + (voff)[_i]), (LAS unsigned*)(lds + (bufoff) + ldsw + _i * 8192), 16, 0, 0); } while (0)
; #define PG8_LDA(dst, b, h) do { _Pragma("unroll") for (int m = 0; m < 4; ++m) _Pragma("unroll") for (int k = 0; k < 2; ++k) dst[m][k] = *(const LAS bf16x8*)(lds + PG8_SA(b, h) + aoff + m * 2048 + k * 1024); } while (0)
; #define PG8_LDB(dst, b, h) do { _Pragma("unroll") for (int n = 0; n < 2; ++n) _Pragma("unroll") for (int k = 0; k < 2; ++k) dst[n][k] = *(const LAS bf16x8*)(lds + PG8_SB(b, h) + boff + n * 2048 + k * 1024); } while (0)
; #define PG8_MMA(ai, bj, At, Bt) do { __builtin_amdgcn_s_setprio(1); _Pragma("unroll") for (int m = 0; m < 4; ++m) _Pragma("unroll") for (int n = 0; n < 2; ++n) _Pragma("unroll") for (int k = 0; k < 2; ++k) \
;         acc[ai][bj][m][n] = __builtin_amdgcn_mfma_f32_16x16x32_bf16(Bt[n][k], At[m][k], acc[ai][bj][m][n], 0, 0, 0); __builtin_amdgcn_s_setprio(0); } while (0)
; #define PG8_WAIT_V(n) asm volatile("s_waitcnt vmcnt(" #n ")" ::: "memory")
; #define PG8_WAIT_L(n) asm volatile("s_waitcnt lgkmcnt(" #n ")" ::: "memory")
; template <class Epi, class Sched = StaticOrder, bool ALIGN_EPI = true>
; __device__ __forceinline__ void gemm_phase(LAS unsigned char* lds, const Gemm g, const Sched& S, const Epi& E) {
;     ...
;         const char* nA = has_next ? (const char*)g.A + (size_t)nxt.pm * tstep + (size_t)nxt.kp * K * 2 : cA; const char* nB = has_next ? (const char*)g.Bt + (size_t)nxt.pn * tstep + (size_t)nxt.kp * K * 2 : cB;
;         for (int t = 0; t < nt; t += 2) {
;             const bool last = (t == nt - 2);
;             const char* a1 = cA + (size_t)(t + 1) * kstep;
;             const char* a2 = last ? nA : cA + (size_t)(t + 2) * kstep; const char* b2 = last ? nB : cB + (size_t)(t + 2) * kstep;
;             const char* a3 = a2 + kstep; const char* b3 = b2 + kstep;
;             PG8_LDB(B0, 0, 0); PG8_LDB(B1, 0, 1); PG8_SCHED; PG8_LDA(At, 0, 0); PG8_STAGE(PG8_SA(1, 1), a1 + hstep, voffA);
;             PG8_WAIT_V(8); PG8_WAIT_L(0); PG8_BAR; PG8_MMA(0, 0, At, B0); PG8_MMA(0, 1, At, B1); PG8_BAR; PG8_SCHED;
;             PG8_LDA(At, 0, 1); PG8_STAGE(PG8_SB(0, 0), b2, voffB); PG8_STAGE(PG8_SB(0, 1), b2 + hstep, voffB); PG8_STAGE(PG8_SA(0, 0), a2, voffA);
.Lmy_nb_467:
	s_add_u32 s16, s44, 0xfff80080
	s_addc_u32 s17, s45, -1
	s_add_i32 s83, 0, 0x10000
	s_cmp_eq_u32 s82, 28
	s_cselect_b32 s49, s10, s17
	s_cselect_b32 s48, s11, s16
	v_add_u32_e32 v142, s83, v144
	s_cselect_b32 s47, s21, vcc_hi
	s_cselect_b32 s46, s31, vcc_lo
	s_add_i32 s33, 0, 0x14000
	ds_read_b128 v[148:151], v142
	ds_read_b128 v[160:163], v142 offset:1024
	ds_read_b128 v[164:167], v142 offset:2048
	ds_read_b128 v[168:171], v142 offset:3072
	v_add_u32_e32 v142, s33, v144
	ds_read_b128 v[172:175], v142
	ds_read_b128 v[176:179], v142 offset:1024
	ds_read_b128 v[180:183], v142 offset:2048
	ds_read_b128 v[184:187], v142 offset:3072
	v_lshl_add_u64 v[142:143], s[44:45], 0, v[138:139]
	s_add_i32 m0, s23, 0xc000
	ds_read_b128 v[188:191], v146
	ds_read_b128 v[192:195], v146 offset:1024
	ds_read_b128 v[210:213], v146 offset:2048
	ds_read_b128 v[214:217], v146 offset:3072
	ds_read_b128 v[218:221], v146 offset:4096
	ds_read_b128 v[222:225], v146 offset:5120
	ds_read_b128 v[226:229], v146 offset:6144
	ds_read_b128 v[230:233], v146 offset:7168
	global_load_lds_dwordx4 v[142:143], off
	v_lshl_add_u64 v[142:143], s[44:45], 0, v[140:141]
	s_add_i32 m0, s23, 0xe000
	s_nop 0
	global_load_lds_dwordx4 v[142:143], off
	s_waitcnt vmcnt(8)
	s_waitcnt lgkmcnt(0)
	s_barrier
	s_waitcnt lgkmcnt(0)
	v_mfma_f32_16x16x32_bf16 v[126:129], v[148:151], v[188:191], 0
	v_mfma_f32_16x16x32_bf16 v[118:121], v[164:167], v[188:191], 0
	v_mfma_f32_16x16x32_bf16 v[110:113], v[148:151], v[210:213], 0
	v_mfma_f32_16x16x32_bf16 v[102:105], v[164:167], v[210:213], 0
	v_mfma_f32_16x16x32_bf16 v[94:97], v[148:151], v[218:221], 0
	v_mfma_f32_16x16x32_bf16 v[86:89], v[164:167], v[218:221], 0
	v_mfma_f32_16x16x32_bf16 v[78:81], v[148:151], v[226:229], 0
	v_mfma_f32_16x16x32_bf16 v[70:73], v[164:167], v[226:229], 0
	v_mfma_f32_16x16x32_bf16 v[126:129], v[160:163], v[192:195], v[126:129]
	v_mfma_f32_16x16x32_bf16 v[118:121], v[168:171], v[192:195], v[118:121]
	v_mfma_f32_16x16x32_bf16 v[110:113], v[160:163], v[214:217], v[110:113]
	v_mfma_f32_16x16x32_bf16 v[102:105], v[168:171], v[214:217], v[102:105]
	v_mfma_f32_16x16x32_bf16 v[94:97], v[160:163], v[222:225], v[94:97]
	v_mfma_f32_16x16x32_bf16 v[86:89], v[168:171], v[222:225], v[86:89]
	v_mfma_f32_16x16x32_bf16 v[78:81], v[160:163], v[230:233], v[78:81]
	v_mfma_f32_16x16x32_bf16 v[70:73], v[168:171], v[230:233], v[70:73]
	v_mfma_f32_16x16x32_bf16 v[122:125], v[172:175], v[188:191], 0
	v_mfma_f32_16x16x32_bf16 v[114:117], v[180:183], v[188:191], 0
	v_mfma_f32_16x16x32_bf16 v[106:109], v[172:175], v[210:213], 0
	v_mfma_f32_16x16x32_bf16 v[98:101], v[180:183], v[210:213], 0
	v_mfma_f32_16x16x32_bf16 v[90:93], v[172:175], v[218:221], 0
	v_mfma_f32_16x16x32_bf16 v[82:85], v[180:183], v[218:221], 0
	v_mfma_f32_16x16x32_bf16 v[74:77], v[172:175], v[226:229], 0
	v_mfma_f32_16x16x32_bf16 v[66:69], v[180:183], v[226:229], 0
	v_mfma_f32_16x16x32_bf16 v[122:125], v[176:179], v[192:195], v[122:125]
	v_mfma_f32_16x16x32_bf16 v[114:117], v[184:187], v[192:195], v[114:117]
	v_mfma_f32_16x16x32_bf16 v[106:109], v[176:179], v[214:217], v[106:109]
	v_mfma_f32_16x16x32_bf16 v[98:101], v[184:187], v[214:217], v[98:101]
	v_mfma_f32_16x16x32_bf16 v[90:93], v[176:179], v[222:225], v[90:93]
	v_mfma_f32_16x16x32_bf16 v[82:85], v[184:187], v[222:225], v[82:85]
	v_mfma_f32_16x16x32_bf16 v[74:77], v[176:179], v[230:233], v[74:77]
	v_mfma_f32_16x16x32_bf16 v[66:69], v[184:187], v[230:233], v[66:69]
	s_barrier
	s_add_i32 s16, s83, s92
	v_lshl_add_u64 v[142:143], s[46:47], 0, v[134:135]
	s_mov_b32 m0, s16
	ds_read_b128 v[188:191], v146 offset:16384
	ds_read_b128 v[192:195], v146 offset:17408
	ds_read_b128 v[210:213], v146 offset:18432
	ds_read_b128 v[214:217], v146 offset:19456
	ds_read_b128 v[218:221], v146 offset:20480
	ds_read_b128 v[222:225], v146 offset:21504
	ds_read_b128 v[226:229], v146 offset:22528
	ds_read_b128 v[230:233], v146 offset:23552
	global_load_lds_dwordx4 v[142:143], off
	s_add_i32 m0, s16, 0x2000
	s_add_u32 s16, s46, 0x80000
	v_lshl_add_u64 v[152:153], s[46:47], 0, v[130:131]
	s_addc_u32 s17, s47, 0
	s_add_i32 s33, s33, s92
	global_load_lds_dwordx4 v[152:153], off
	v_lshl_add_u64 v[196:197], s[16:17], 0, v[134:135]
	s_mov_b32 m0, s33
	v_lshl_add_u64 v[234:235], s[48:49], 0, v[132:133]
	global_load_lds_dwordx4 v[196:197], off
	v_lshl_add_u64 v[196:197], s[16:17], 0, v[130:131]
	s_add_i32 m0, s33, 0x2000
	s_nop 0
	global_load_lds_dwordx4 v[196:197], off
	v_lshl_add_u64 v[196:197], s[48:49], 0, v[136:137]
	s_mov_b32 m0, s23
	s_nop 0
	global_load_lds_dwordx4 v[196:197], off
	s_mov_b32 m0, s4
	s_nop 0
	global_load_lds_dwordx4 v[234:235], off
	s_waitcnt vmcnt(8)
	s_waitcnt lgkmcnt(0)
	s_barrier
; #define PG8_STAGE(bufoff, gbase, voff) do { _Pragma("unroll") for (int _i = 0; _i < 2; ++_i) \
;         __builtin_amdgcn_global_load_lds((const unsigned*)((const char*)(gbase) + (voff)[_i]), (LAS unsigned*)(lds + (bufoff) + ldsw + _i * 8192), 16, 0, 0); } while (0)
; #define PG8_LDA(dst, b, h) do { _Pragma("unroll") for (int m = 0; m < 4; ++m) _Pragma("unroll") for (int k = 0; k < 2; ++k) dst[m][k] = *(const LAS bf16x8*)(lds + PG8_SA(b, h) + aoff + m * 2048 + k * 1024); } while (0)
; #define PG8_LDB(dst, b, h) do { _Pragma("unroll") for (int n = 0; n < 2; ++n) _Pragma("unroll") for (int k = 0; k < 2; ++k) dst[n][k] = *(const LAS bf16x8*)(lds + PG8_SB(b, h) + boff + n * 2048 + k * 1024); } while (0)
; #define PG8_MMA(ai, bj, At, Bt) do { __builtin_amdgcn_s_setprio(1); _Pragma("unroll") for (int m = 0; m < 4; ++m) _Pragma("unroll") for (int n = 0; n < 2; ++n) _Pragma("unroll") for (int k = 0; k < 2; ++k) \
;         acc[ai][bj][m][n] = __builtin_amdgcn_mfma_f32_16x16x32_bf16(Bt[n][k], At[m][k], acc[ai][bj][m][n], 0, 0, 0); __builtin_amdgcn_s_setprio(0); } while (0)
; #define PG8_WAIT_V(n) asm volatile("s_waitcnt vmcnt(" #n ")" ::: "memory")
; #define PG8_WAIT_L(n) asm volatile("s_waitcnt lgkmcnt(" #n ")" ::: "memory")
; #define PG8_BAR __builtin_amdgcn_s_barrier()
; #define PG8_SCHED __builtin_amdgcn_sched_barrier(0)
; template <class Epi, class Sched = StaticOrder, bool ALIGN_EPI = true>
; __device__ __forceinline__ void gemm_phase(LAS unsigned char* lds, const Gemm g, const Sched& S, const Epi& E) {
;     ...
;             PG8_WAIT_V(8); PG8_WAIT_L(0); PG8_BAR; PG8_MMA(1, 0, At, B0); PG8_MMA(1, 1, At, B1); PG8_BAR; PG8_SCHED;
;             PG8_LDB(B0, 1, 0); PG8_LDB(B1, 1, 1); PG8_SCHED; PG8_LDA(At, 1, 0); PG8_STAGE(PG8_SA(0, 1), a2 + hstep, voffA);
;             PG8_WAIT_V(8); PG8_WAIT_L(0); PG8_BAR; PG8_MMA(0, 0, At, B0); PG8_MMA(0, 1, At, B1); PG8_BAR; PG8_SCHED;
	s_waitcnt lgkmcnt(0)
	v_mfma_f32_16x16x32_bf16 v[62:65], v[148:151], v[188:191], 0
	v_mfma_f32_16x16x32_bf16 v[54:57], v[164:167], v[188:191], 0
	v_mfma_f32_16x16x32_bf16 v[46:49], v[148:151], v[210:213], 0
	v_mfma_f32_16x16x32_bf16 v[38:41], v[164:167], v[210:213], 0
	v_mfma_f32_16x16x32_bf16 v[30:33], v[148:151], v[218:221], 0
	v_mfma_f32_16x16x32_bf16 v[22:25], v[164:167], v[218:221], 0
	v_mfma_f32_16x16x32_bf16 v[14:17], v[148:151], v[226:229], 0
	v_mfma_f32_16x16x32_bf16 v[6:9], v[164:167], v[226:229], 0
	v_mfma_f32_16x16x32_bf16 v[62:65], v[160:163], v[192:195], v[62:65]
	v_mfma_f32_16x16x32_bf16 v[54:57], v[168:171], v[192:195], v[54:57]
	v_mfma_f32_16x16x32_bf16 v[46:49], v[160:163], v[214:217], v[46:49]
	v_mfma_f32_16x16x32_bf16 v[38:41], v[168:171], v[214:217], v[38:41]
	v_mfma_f32_16x16x32_bf16 v[30:33], v[160:163], v[222:225], v[30:33]
	v_mfma_f32_16x16x32_bf16 v[22:25], v[168:171], v[222:225], v[22:25]
	v_mfma_f32_16x16x32_bf16 v[14:17], v[160:163], v[230:233], v[14:17]
	v_mfma_f32_16x16x32_bf16 v[6:9], v[168:171], v[230:233], v[6:9]
	v_mfma_f32_16x16x32_bf16 v[58:61], v[172:175], v[188:191], 0
	v_mfma_f32_16x16x32_bf16 v[50:53], v[180:183], v[188:191], 0
	v_mfma_f32_16x16x32_bf16 v[42:45], v[172:175], v[210:213], 0
	v_mfma_f32_16x16x32_bf16 v[34:37], v[180:183], v[210:213], 0
	v_mfma_f32_16x16x32_bf16 v[26:29], v[172:175], v[218:221], 0
	v_mfma_f32_16x16x32_bf16 v[18:21], v[180:183], v[218:221], 0
	v_mfma_f32_16x16x32_bf16 v[10:13], v[172:175], v[226:229], 0
	v_mfma_f32_16x16x32_bf16 v[2:5], v[180:183], v[226:229], 0
	v_mfma_f32_16x16x32_bf16 v[58:61], v[176:179], v[192:195], v[58:61]
	v_mfma_f32_16x16x32_bf16 v[50:53], v[184:187], v[192:195], v[50:53]
	v_mfma_f32_16x16x32_bf16 v[42:45], v[176:179], v[214:217], v[42:45]
	v_mfma_f32_16x16x32_bf16 v[34:37], v[184:187], v[214:217], v[34:37]
	v_mfma_f32_16x16x32_bf16 v[26:29], v[176:179], v[222:225], v[26:29]
	v_mfma_f32_16x16x32_bf16 v[18:21], v[184:187], v[222:225], v[18:21]
	v_mfma_f32_16x16x32_bf16 v[10:13], v[176:179], v[230:233], v[10:13]
	v_mfma_f32_16x16x32_bf16 v[2:5], v[184:187], v[230:233], v[2:5]
	s_barrier
	s_add_i32 s33, 0, 0x18000
	v_add_u32_e32 v147, s33, v144
	s_add_i32 s83, 0, 0x1c000
	ds_read_b128 v[148:151], v147
	ds_read_b128 v[160:163], v147 offset:1024
	ds_read_b128 v[164:167], v147 offset:2048
	ds_read_b128 v[168:171], v147 offset:3072
	v_add_u32_e32 v147, s83, v144
	ds_read_b128 v[172:175], v147
	ds_read_b128 v[176:179], v147 offset:1024
	ds_read_b128 v[180:183], v147 offset:2048
	ds_read_b128 v[184:187], v147 offset:3072
	s_add_u32 s16, s48, 0x80000
	s_addc_u32 s17, s49, 0
	s_mov_b32 m0, s5
	v_lshl_add_u64 v[236:237], s[16:17], 0, v[136:137]
	ds_read_b128 v[188:191], v146 offset:32768
	ds_read_b128 v[192:195], v146 offset:33792
	ds_read_b128 v[210:213], v146 offset:34816
	ds_read_b128 v[214:217], v146 offset:35840
	ds_read_b128 v[218:221], v146 offset:36864
	ds_read_b128 v[222:225], v146 offset:37888
	ds_read_b128 v[226:229], v146 offset:38912
	ds_read_b128 v[230:233], v146 offset:39936
	global_load_lds_dwordx4 v[236:237], off
	v_lshl_add_u64 v[236:237], s[16:17], 0, v[132:133]
	s_mov_b32 m0, s6
	s_nop 0
	global_load_lds_dwordx4 v[236:237], off
	s_waitcnt vmcnt(8)
	s_waitcnt lgkmcnt(0)
	s_barrier
	s_waitcnt lgkmcnt(0)
	v_mfma_f32_16x16x32_bf16 v[126:129], v[148:151], v[188:191], v[126:129]
	v_mfma_f32_16x16x32_bf16 v[118:121], v[164:167], v[188:191], v[118:121]
	v_mfma_f32_16x16x32_bf16 v[110:113], v[148:151], v[210:213], v[110:113]
	v_mfma_f32_16x16x32_bf16 v[102:105], v[164:167], v[210:213], v[102:105]
	v_mfma_f32_16x16x32_bf16 v[94:97], v[148:151], v[218:221], v[94:97]
	v_mfma_f32_16x16x32_bf16 v[86:89], v[164:167], v[218:221], v[86:89]
	v_mfma_f32_16x16x32_bf16 v[78:81], v[148:151], v[226:229], v[78:81]
	v_mfma_f32_16x16x32_bf16 v[70:73], v[164:167], v[226:229], v[70:73]
	v_mfma_f32_16x16x32_bf16 v[126:129], v[160:163], v[192:195], v[126:129]
	v_mfma_f32_16x16x32_bf16 v[118:121], v[168:171], v[192:195], v[118:121]
	v_mfma_f32_16x16x32_bf16 v[110:113], v[160:163], v[214:217], v[110:113]
	v_mfma_f32_16x16x32_bf16 v[102:105], v[168:171], v[214:217], v[102:105]
	v_mfma_f32_16x16x32_bf16 v[94:97], v[160:163], v[222:225], v[94:97]
	v_mfma_f32_16x16x32_bf16 v[86:89], v[168:171], v[222:225], v[86:89]
	v_mfma_f32_16x16x32_bf16 v[78:81], v[160:163], v[230:233], v[78:81]
	v_mfma_f32_16x16x32_bf16 v[70:73], v[168:171], v[230:233], v[70:73]
	v_mfma_f32_16x16x32_bf16 v[122:125], v[172:175], v[188:191], v[122:125]
	v_mfma_f32_16x16x32_bf16 v[114:117], v[180:183], v[188:191], v[114:117]
	v_mfma_f32_16x16x32_bf16 v[106:109], v[172:175], v[210:213], v[106:109]
	v_mfma_f32_16x16x32_bf16 v[98:101], v[180:183], v[210:213], v[98:101]
	v_mfma_f32_16x16x32_bf16 v[90:93], v[172:175], v[218:221], v[90:93]
	v_mfma_f32_16x16x32_bf16 v[82:85], v[180:183], v[218:221], v[82:85]
	v_mfma_f32_16x16x32_bf16 v[74:77], v[172:175], v[226:229], v[74:77]
	v_mfma_f32_16x16x32_bf16 v[66:69], v[180:183], v[226:229], v[66:69]
	v_mfma_f32_16x16x32_bf16 v[122:125], v[176:179], v[192:195], v[122:125]
	v_mfma_f32_16x16x32_bf16 v[114:117], v[184:187], v[192:195], v[114:117]
	v_mfma_f32_16x16x32_bf16 v[106:109], v[176:179], v[214:217], v[106:109]
	v_mfma_f32_16x16x32_bf16 v[98:101], v[184:187], v[214:217], v[98:101]
	v_mfma_f32_16x16x32_bf16 v[90:93], v[176:179], v[222:225], v[90:93]
	v_mfma_f32_16x16x32_bf16 v[82:85], v[184:187], v[222:225], v[82:85]
	v_mfma_f32_16x16x32_bf16 v[74:77], v[176:179], v[230:233], v[74:77]
	v_mfma_f32_16x16x32_bf16 v[66:69], v[184:187], v[230:233], v[66:69]
	s_barrier
; #define PG8_STAGE(bufoff, gbase, voff) do { _Pragma("unroll") for (int _i = 0; _i < 2; ++_i) \
;         __builtin_amdgcn_global_load_lds((const unsigned*)((const char*)(gbase) + (voff)[_i]), (LAS unsigned*)(lds + (bufoff) + ldsw + _i * 8192), 16, 0, 0); } while (0)
; #define PG8_LDA(dst, b, h) do { _Pragma("unroll") for (int m = 0; m < 4; ++m) _Pragma("unroll") for (int k = 0; k < 2; ++k) dst[m][k] = *(const LAS bf16x8*)(lds + PG8_SA(b, h) + aoff + m * 2048 + k * 1024); } while (0)
; #define PG8_LDB(dst, b, h) do { _Pragma("unroll") for (int n = 0; n < 2; ++n) _Pragma("unroll") for (int k = 0; k < 2; ++k) dst[n][k] = *(const LAS bf16x8*)(lds + PG8_SB(b, h) + boff + n * 2048 + k * 1024); } while (0)
; #define PG8_MMA(ai, bj, At, Bt) do { __builtin_amdgcn_s_setprio(1); _Pragma("unroll") for (int m = 0; m < 4; ++m) _Pragma("unroll") for (int n = 0; n < 2; ++n) _Pragma("unroll") for (int k = 0; k < 2; ++k) \
;         acc[ai][bj][m][n] = __builtin_amdgcn_mfma_f32_16x16x32_bf16(Bt[n][k], At[m][k], acc[ai][bj][m][n], 0, 0, 0); __builtin_amdgcn_s_setprio(0); } while (0)
; #define PG8_WAIT_V(n) asm volatile("s_waitcnt vmcnt(" #n ")" ::: "memory")
; template <class Epi, class Sched = StaticOrder, bool ALIGN_EPI = true>
; __device__ __forceinline__ void gemm_phase(LAS unsigned char* lds, const Gemm g, const Sched& S, const Epi& E) {
;     ...
;             PG8_LDB(B0, 0, 0); PG8_LDB(B1, 0, 1); PG8_SCHED; PG8_LDA(At, 0, 0); PG8_STAGE(PG8_SA(1, 1), a1 + hstep, voffA);
;             PG8_WAIT_V(8); PG8_WAIT_L(0); PG8_BAR; PG8_MMA(0, 0, At, B0); PG8_MMA(0, 1, At, B1); PG8_BAR; PG8_SCHED;
;             PG8_LDA(At, 0, 1); PG8_STAGE(PG8_SB(0, 0), b2, voffB); PG8_STAGE(PG8_SB(0, 1), b2 + hstep, voffB); PG8_STAGE(PG8_SA(0, 0), a2, voffA);
;             PG8_WAIT_V(8); PG8_WAIT_L(0); PG8_BAR; PG8_MMA(1, 0, At, B0); PG8_MMA(1, 1, At, B1); PG8_BAR; PG8_SCHED;
;             PG8_LDB(B0, 1, 0); PG8_LDB(B1, 1, 1); PG8_SCHED; PG8_LDA(At, 1, 0); PG8_STAGE(PG8_SA(0, 1), a2 + hstep, voffA);
;             PG8_WAIT_V(8); PG8_WAIT_L(0); PG8_BAR; PG8_MMA(0, 0, At, B0); PG8_MMA(0, 1, At, B1); PG8_BAR; PG8_SCHED;
;             PG8_LDA(At, 1, 1); PG8_STAGE(PG8_SB(1, 0), b3, voffB); PG8_STAGE(PG8_SB(1, 1), b3 + hstep, voffB); PG8_STAGE(PG8_SA(1, 0), a3, voffA);
;             PG8_WAIT_V(8); PG8_WAIT_L(0); PG8_BAR; PG8_MMA(1, 0, At, B0); PG8_MMA(1, 1, At, B1); PG8_BAR; PG8_SCHED;
	s_add_i32 s16, s33, s92
	v_lshl_add_u64 v[142:143], v[142:143], 0, s[34:35]
	s_mov_b32 m0, s16
	ds_read_b128 v[188:191], v146 offset:49152
	ds_read_b128 v[192:195], v146 offset:50176
	ds_read_b128 v[210:213], v146 offset:51200
	ds_read_b128 v[214:217], v146 offset:52224
	ds_read_b128 v[218:221], v146 offset:53248
	ds_read_b128 v[222:225], v146 offset:54272
	ds_read_b128 v[226:229], v146 offset:55296
	ds_read_b128 v[230:233], v146 offset:56320
	global_load_lds_dwordx4 v[142:143], off
	s_add_i32 m0, s16, 0x2000
	s_add_u32 s16, s46, 0x80080
	v_lshl_add_u64 v[142:143], v[152:153], 0, s[34:35]
	s_addc_u32 s17, s47, 0
	s_add_i32 s33, s83, s92
	global_load_lds_dwordx4 v[142:143], off
	v_lshl_add_u64 v[142:143], s[16:17], 0, v[134:135]
	s_mov_b32 m0, s33
	s_nop 0
	global_load_lds_dwordx4 v[142:143], off
	v_lshl_add_u64 v[142:143], s[16:17], 0, v[130:131]
	s_add_i32 m0, s33, 0x2000
	s_nop 0
	global_load_lds_dwordx4 v[142:143], off
	v_lshl_add_u64 v[142:143], v[196:197], 0, s[34:35]
	s_mov_b32 m0, s7
	s_nop 0
	global_load_lds_dwordx4 v[142:143], off
	v_lshl_add_u64 v[142:143], v[234:235], 0, s[34:35]
	s_mov_b32 m0, s8
	s_nop 0
	global_load_lds_dwordx4 v[142:143], off
	s_waitcnt vmcnt(8)
	s_waitcnt lgkmcnt(0)
	s_barrier
	s_waitcnt lgkmcnt(0)
	v_mfma_f32_16x16x32_bf16 v[62:65], v[148:151], v[188:191], v[62:65]
	v_mfma_f32_16x16x32_bf16 v[54:57], v[164:167], v[188:191], v[54:57]
	v_mfma_f32_16x16x32_bf16 v[46:49], v[148:151], v[210:213], v[46:49]
	v_mfma_f32_16x16x32_bf16 v[38:41], v[164:167], v[210:213], v[38:41]
	v_mfma_f32_16x16x32_bf16 v[30:33], v[148:151], v[218:221], v[30:33]
	v_mfma_f32_16x16x32_bf16 v[22:25], v[164:167], v[218:221], v[22:25]
	v_mfma_f32_16x16x32_bf16 v[14:17], v[148:151], v[226:229], v[14:17]
	v_mfma_f32_16x16x32_bf16 v[6:9], v[164:167], v[226:229], v[6:9]
	v_mfma_f32_16x16x32_bf16 v[62:65], v[160:163], v[192:195], v[62:65]
	v_mfma_f32_16x16x32_bf16 v[54:57], v[168:171], v[192:195], v[54:57]
	v_mfma_f32_16x16x32_bf16 v[46:49], v[160:163], v[214:217], v[46:49]
	v_mfma_f32_16x16x32_bf16 v[38:41], v[168:171], v[214:217], v[38:41]
	v_mfma_f32_16x16x32_bf16 v[30:33], v[160:163], v[222:225], v[30:33]
	v_mfma_f32_16x16x32_bf16 v[22:25], v[168:171], v[222:225], v[22:25]
	v_mfma_f32_16x16x32_bf16 v[14:17], v[160:163], v[230:233], v[14:17]
	v_mfma_f32_16x16x32_bf16 v[6:9], v[168:171], v[230:233], v[6:9]
	v_mfma_f32_16x16x32_bf16 v[58:61], v[172:175], v[188:191], v[58:61]
	v_mfma_f32_16x16x32_bf16 v[50:53], v[180:183], v[188:191], v[50:53]
	v_mfma_f32_16x16x32_bf16 v[42:45], v[172:175], v[210:213], v[42:45]
	v_mfma_f32_16x16x32_bf16 v[34:37], v[180:183], v[210:213], v[34:37]
	v_mfma_f32_16x16x32_bf16 v[26:29], v[172:175], v[218:221], v[26:29]
	v_mfma_f32_16x16x32_bf16 v[18:21], v[180:183], v[218:221], v[18:21]
	v_mfma_f32_16x16x32_bf16 v[10:13], v[172:175], v[226:229], v[10:13]
	v_mfma_f32_16x16x32_bf16 v[2:5], v[180:183], v[226:229], v[2:5]
	v_mfma_f32_16x16x32_bf16 v[58:61], v[176:179], v[192:195], v[58:61]
	v_mfma_f32_16x16x32_bf16 v[50:53], v[184:187], v[192:195], v[50:53]
	v_mfma_f32_16x16x32_bf16 v[42:45], v[176:179], v[214:217], v[42:45]
	v_mfma_f32_16x16x32_bf16 v[34:37], v[184:187], v[214:217], v[34:37]
	v_mfma_f32_16x16x32_bf16 v[26:29], v[176:179], v[222:225], v[26:29]
	v_mfma_f32_16x16x32_bf16 v[18:21], v[184:187], v[222:225], v[18:21]
	v_mfma_f32_16x16x32_bf16 v[10:13], v[176:179], v[230:233], v[10:13]
	v_mfma_f32_16x16x32_bf16 v[2:5], v[184:187], v[230:233], v[2:5]
	s_barrier
	s_add_i32 s82, s82, 2
	s_add_u32 s44, s44, 0x100
	s_addc_u32 s45, s45, 0
	s_add_u32 vcc_lo, vcc_lo, 0x100
	s_addc_u32 vcc_hi, vcc_hi, 0
	s_cmp_gt_u32 s82, 29
	s_cbranch_scc0 .LBB0_467
.LBB0_467:
	s_add_u32 s16, s44, 0xfff80080
	s_addc_u32 s17, s45, -1
	s_add_i32 s83, 0, 0x10000
	s_cmp_eq_u32 s82, 28
	s_cselect_b32 s49, s10, s17
	s_cselect_b32 s48, s11, s16
	v_add_u32_e32 v142, s83, v144
	s_cselect_b32 s47, s21, vcc_hi
	s_cselect_b32 s46, s31, vcc_lo
	s_add_i32 s33, 0, 0x14000
	ds_read_b128 v[148:151], v142
	ds_read_b128 v[160:163], v142 offset:1024
	ds_read_b128 v[164:167], v142 offset:2048
	ds_read_b128 v[168:171], v142 offset:3072
	v_add_u32_e32 v142, s33, v144
	ds_read_b128 v[172:175], v142
	ds_read_b128 v[176:179], v142 offset:1024
	ds_read_b128 v[180:183], v142 offset:2048
	ds_read_b128 v[184:187], v142 offset:3072
	v_lshl_add_u64 v[142:143], s[44:45], 0, v[138:139]
	s_add_i32 m0, s23, 0xc000
	ds_read_b128 v[188:191], v146
	ds_read_b128 v[192:195], v146 offset:1024
	ds_read_b128 v[210:213], v146 offset:2048
	ds_read_b128 v[214:217], v146 offset:3072
	ds_read_b128 v[218:221], v146 offset:4096
	ds_read_b128 v[222:225], v146 offset:5120
	ds_read_b128 v[226:229], v146 offset:6144
	ds_read_b128 v[230:233], v146 offset:7168
	global_load_lds_dwordx4 v[142:143], off
	v_lshl_add_u64 v[142:143], s[44:45], 0, v[140:141]
	s_add_i32 m0, s23, 0xe000
	s_nop 0
	global_load_lds_dwordx4 v[142:143], off
	s_waitcnt vmcnt(8)
	s_waitcnt lgkmcnt(0)
	s_barrier
; #define PG8_STAGE(bufoff, gbase, voff) do { _Pragma("unroll") for (int _i = 0; _i < 2; ++_i) \
;         __builtin_amdgcn_global_load_lds((const unsigned*)((const char*)(gbase) + (voff)[_i]), (LAS unsigned*)(lds + (bufoff) + ldsw + _i * 8192), 16, 0, 0); } while (0)
; #define PG8_LDA(dst, b, h) do { _Pragma("unroll") for (int m = 0; m < 4; ++m) _Pragma("unroll") for (int k = 0; k < 2; ++k) dst[m][k] = *(const LAS bf16x8*)(lds + PG8_SA(b, h) + aoff + m * 2048 + k * 1024); } while (0)
; #define PG8_MMA(ai, bj, At, Bt) do { __builtin_amdgcn_s_setprio(1); _Pragma("unroll") for (int m = 0; m < 4; ++m) _Pragma("unroll") for (int n = 0; n < 2; ++n) _Pragma("unroll") for (int k = 0; k < 2; ++k) \
;         acc[ai][bj][m][n] = __builtin_amdgcn_mfma_f32_16x16x32_bf16(Bt[n][k], At[m][k], acc[ai][bj][m][n], 0, 0, 0); __builtin_amdgcn_s_setprio(0); } while (0)
; #define PG8_WAIT_V(n) asm volatile("s_waitcnt vmcnt(" #n ")" ::: "memory")
; #define PG8_WAIT_L(n) asm volatile("s_waitcnt lgkmcnt(" #n ")" ::: "memory")
; #define PG8_BAR __builtin_amdgcn_s_barrier()
; #define PG8_SCHED __builtin_amdgcn_sched_barrier(0)
; template <class Epi, class Sched = StaticOrder, bool ALIGN_EPI = true>
; __device__ __forceinline__ void gemm_phase(LAS unsigned char* lds, const Gemm g, const Sched& S, const Epi& E) {
;     ...
;             PG8_WAIT_V(8); PG8_WAIT_L(0); PG8_BAR; PG8_MMA(0, 0, At, B0); PG8_MMA(0, 1, At, B1); PG8_BAR; PG8_SCHED;
;             PG8_LDA(At, 0, 1); PG8_STAGE(PG8_SB(0, 0), b2, voffB); PG8_STAGE(PG8_SB(0, 1), b2 + hstep, voffB); PG8_STAGE(PG8_SA(0, 0), a2, voffA);
;             PG8_WAIT_V(8); PG8_WAIT_L(0); PG8_BAR; PG8_MMA(1, 0, At, B0); PG8_MMA(1, 1, At, B1); PG8_BAR; PG8_SCHED;
	s_waitcnt lgkmcnt(0)
	v_mfma_f32_16x16x32_bf16 v[126:129], v[148:151], v[188:191], v[126:129]
	v_mfma_f32_16x16x32_bf16 v[118:121], v[164:167], v[188:191], v[118:121]
	v_mfma_f32_16x16x32_bf16 v[110:113], v[148:151], v[210:213], v[110:113]
	v_mfma_f32_16x16x32_bf16 v[102:105], v[164:167], v[210:213], v[102:105]
	v_mfma_f32_16x16x32_bf16 v[94:97], v[148:151], v[218:221], v[94:97]
	v_mfma_f32_16x16x32_bf16 v[86:89], v[164:167], v[218:221], v[86:89]
	v_mfma_f32_16x16x32_bf16 v[78:81], v[148:151], v[226:229], v[78:81]
	v_mfma_f32_16x16x32_bf16 v[70:73], v[164:167], v[226:229], v[70:73]
	v_mfma_f32_16x16x32_bf16 v[126:129], v[160:163], v[192:195], v[126:129]
	v_mfma_f32_16x16x32_bf16 v[118:121], v[168:171], v[192:195], v[118:121]
	v_mfma_f32_16x16x32_bf16 v[110:113], v[160:163], v[214:217], v[110:113]
	v_mfma_f32_16x16x32_bf16 v[102:105], v[168:171], v[214:217], v[102:105]
	v_mfma_f32_16x16x32_bf16 v[94:97], v[160:163], v[222:225], v[94:97]
	v_mfma_f32_16x16x32_bf16 v[86:89], v[168:171], v[222:225], v[86:89]
	v_mfma_f32_16x16x32_bf16 v[78:81], v[160:163], v[230:233], v[78:81]
	v_mfma_f32_16x16x32_bf16 v[70:73], v[168:171], v[230:233], v[70:73]
	v_mfma_f32_16x16x32_bf16 v[122:125], v[172:175], v[188:191], v[122:125]
	v_mfma_f32_16x16x32_bf16 v[114:117], v[180:183], v[188:191], v[114:117]
	v_mfma_f32_16x16x32_bf16 v[106:109], v[172:175], v[210:213], v[106:109]
	v_mfma_f32_16x16x32_bf16 v[98:101], v[180:183], v[210:213], v[98:101]
	v_mfma_f32_16x16x32_bf16 v[90:93], v[172:175], v[218:221], v[90:93]
	v_mfma_f32_16x16x32_bf16 v[82:85], v[180:183], v[218:221], v[82:85]
	v_mfma_f32_16x16x32_bf16 v[74:77], v[172:175], v[226:229], v[74:77]
	v_mfma_f32_16x16x32_bf16 v[66:69], v[180:183], v[226:229], v[66:69]
	v_mfma_f32_16x16x32_bf16 v[122:125], v[176:179], v[192:195], v[122:125]
	v_mfma_f32_16x16x32_bf16 v[114:117], v[184:187], v[192:195], v[114:117]
	v_mfma_f32_16x16x32_bf16 v[106:109], v[176:179], v[214:217], v[106:109]
	v_mfma_f32_16x16x32_bf16 v[98:101], v[184:187], v[214:217], v[98:101]
	v_mfma_f32_16x16x32_bf16 v[90:93], v[176:179], v[222:225], v[90:93]
	v_mfma_f32_16x16x32_bf16 v[82:85], v[184:187], v[222:225], v[82:85]
	v_mfma_f32_16x16x32_bf16 v[74:77], v[176:179], v[230:233], v[74:77]
	v_mfma_f32_16x16x32_bf16 v[66:69], v[184:187], v[230:233], v[66:69]
	s_barrier
	s_add_i32 s16, s83, s92
	v_lshl_add_u64 v[142:143], s[46:47], 0, v[134:135]
	s_mov_b32 m0, s16
	ds_read_b128 v[188:191], v146 offset:16384
	ds_read_b128 v[192:195], v146 offset:17408
	ds_read_b128 v[210:213], v146 offset:18432
	ds_read_b128 v[214:217], v146 offset:19456
	ds_read_b128 v[218:221], v146 offset:20480
	ds_read_b128 v[222:225], v146 offset:21504
	ds_read_b128 v[226:229], v146 offset:22528
	ds_read_b128 v[230:233], v146 offset:23552
	global_load_lds_dwordx4 v[142:143], off
	s_add_i32 m0, s16, 0x2000
	s_add_u32 s16, s46, 0x80000
	v_lshl_add_u64 v[152:153], s[46:47], 0, v[130:131]
	s_addc_u32 s17, s47, 0
	s_add_i32 s33, s33, s92
	global_load_lds_dwordx4 v[152:153], off
	v_lshl_add_u64 v[196:197], s[16:17], 0, v[134:135]
	s_mov_b32 m0, s33
	v_lshl_add_u64 v[234:235], s[48:49], 0, v[132:133]
	global_load_lds_dwordx4 v[196:197], off
	v_lshl_add_u64 v[196:197], s[16:17], 0, v[130:131]
	s_add_i32 m0, s33, 0x2000
	s_nop 0
	global_load_lds_dwordx4 v[196:197], off
	v_lshl_add_u64 v[196:197], s[48:49], 0, v[136:137]
	s_mov_b32 m0, s23
	s_nop 0
	global_load_lds_dwordx4 v[196:197], off
	s_mov_b32 m0, s4
	s_nop 0
	global_load_lds_dwordx4 v[234:235], off
	s_waitcnt vmcnt(8)
	s_waitcnt lgkmcnt(0)
	s_barrier
	s_waitcnt lgkmcnt(0)
	v_mfma_f32_16x16x32_bf16 v[62:65], v[148:151], v[188:191], v[62:65]
	v_mfma_f32_16x16x32_bf16 v[54:57], v[164:167], v[188:191], v[54:57]
	v_mfma_f32_16x16x32_bf16 v[46:49], v[148:151], v[210:213], v[46:49]
	v_mfma_f32_16x16x32_bf16 v[38:41], v[164:167], v[210:213], v[38:41]
	v_mfma_f32_16x16x32_bf16 v[30:33], v[148:151], v[218:221], v[30:33]
	v_mfma_f32_16x16x32_bf16 v[22:25], v[164:167], v[218:221], v[22:25]
	v_mfma_f32_16x16x32_bf16 v[14:17], v[148:151], v[226:229], v[14:17]
	v_mfma_f32_16x16x32_bf16 v[6:9], v[164:167], v[226:229], v[6:9]
	v_mfma_f32_16x16x32_bf16 v[62:65], v[160:163], v[192:195], v[62:65]
	v_mfma_f32_16x16x32_bf16 v[54:57], v[168:171], v[192:195], v[54:57]
	v_mfma_f32_16x16x32_bf16 v[46:49], v[160:163], v[214:217], v[46:49]
	v_mfma_f32_16x16x32_bf16 v[38:41], v[168:171], v[214:217], v[38:41]
	v_mfma_f32_16x16x32_bf16 v[30:33], v[160:163], v[222:225], v[30:33]
	v_mfma_f32_16x16x32_bf16 v[22:25], v[168:171], v[222:225], v[22:25]
	v_mfma_f32_16x16x32_bf16 v[14:17], v[160:163], v[230:233], v[14:17]
	v_mfma_f32_16x16x32_bf16 v[6:9], v[168:171], v[230:233], v[6:9]
	v_mfma_f32_16x16x32_bf16 v[58:61], v[172:175], v[188:191], v[58:61]
	v_mfma_f32_16x16x32_bf16 v[50:53], v[180:183], v[188:191], v[50:53]
	v_mfma_f32_16x16x32_bf16 v[42:45], v[172:175], v[210:213], v[42:45]
	v_mfma_f32_16x16x32_bf16 v[34:37], v[180:183], v[210:213], v[34:37]
	v_mfma_f32_16x16x32_bf16 v[26:29], v[172:175], v[218:221], v[26:29]
	v_mfma_f32_16x16x32_bf16 v[18:21], v[180:183], v[218:221], v[18:21]
	v_mfma_f32_16x16x32_bf16 v[10:13], v[172:175], v[226:229], v[10:13]
	v_mfma_f32_16x16x32_bf16 v[2:5], v[180:183], v[226:229], v[2:5]
	v_mfma_f32_16x16x32_bf16 v[58:61], v[176:179], v[192:195], v[58:61]
	v_mfma_f32_16x16x32_bf16 v[50:53], v[184:187], v[192:195], v[50:53]
	v_mfma_f32_16x16x32_bf16 v[42:45], v[176:179], v[214:217], v[42:45]
	v_mfma_f32_16x16x32_bf16 v[34:37], v[184:187], v[214:217], v[34:37]
	v_mfma_f32_16x16x32_bf16 v[26:29], v[176:179], v[222:225], v[26:29]
	v_mfma_f32_16x16x32_bf16 v[18:21], v[184:187], v[222:225], v[18:21]
	v_mfma_f32_16x16x32_bf16 v[10:13], v[176:179], v[230:233], v[10:13]
	v_mfma_f32_16x16x32_bf16 v[2:5], v[184:187], v[230:233], v[2:5]
	s_barrier
; #define PG8_STAGE(bufoff, gbase, voff) do { _Pragma("unroll") for (int _i = 0; _i < 2; ++_i) \
;         __builtin_amdgcn_global_load_lds((const unsigned*)((const char*)(gbase) + (voff)[_i]), (LAS unsigned*)(lds + (bufoff) + ldsw + _i * 8192), 16, 0, 0); } while (0)
; #define PG8_LDA(dst, b, h) do { _Pragma("unroll") for (int m = 0; m < 4; ++m) _Pragma("unroll") for (int k = 0; k < 2; ++k) dst[m][k] = *(const LAS bf16x8*)(lds + PG8_SA(b, h) + aoff + m * 2048 + k * 1024); } while (0)
; #define PG8_LDB(dst, b, h) do { _Pragma("unroll") for (int n = 0; n < 2; ++n) _Pragma("unroll") for (int k = 0; k < 2; ++k) dst[n][k] = *(const LAS bf16x8*)(lds + PG8_SB(b, h) + boff + n * 2048 + k * 1024); } while (0)
; #define PG8_MMA(ai, bj, At, Bt) do { __builtin_amdgcn_s_setprio(1); _Pragma("unroll") for (int m = 0; m < 4; ++m) _Pragma("unroll") for (int n = 0; n < 2; ++n) _Pragma("unroll") for (int k = 0; k < 2; ++k) \
;         acc[ai][bj][m][n] = __builtin_amdgcn_mfma_f32_16x16x32_bf16(Bt[n][k], At[m][k], acc[ai][bj][m][n], 0, 0, 0); __builtin_amdgcn_s_setprio(0); } while (0)
; #define PG8_WAIT_V(n) asm volatile("s_waitcnt vmcnt(" #n ")" ::: "memory")
; #define PG8_WAIT_L(n) asm volatile("s_waitcnt lgkmcnt(" #n ")" ::: "memory")
; #define PG8_BAR __builtin_amdgcn_s_barrier()
; #define PG8_SCHED __builtin_amdgcn_sched_barrier(0)
; template <class Epi, class Sched = StaticOrder, bool ALIGN_EPI = true>
; __device__ __forceinline__ void gemm_phase(LAS unsigned char* lds, const Gemm g, const Sched& S, const Epi& E) {
;     ...
;             PG8_LDB(B0, 1, 0); PG8_LDB(B1, 1, 1); PG8_SCHED; PG8_LDA(At, 1, 0); PG8_STAGE(PG8_SA(0, 1), a2 + hstep, voffA);
;             PG8_WAIT_V(8); PG8_WAIT_L(0); PG8_BAR; PG8_MMA(0, 0, At, B0); PG8_MMA(0, 1, At, B1); PG8_BAR; PG8_SCHED;
	s_add_i32 s33, 0, 0x18000
	v_add_u32_e32 v147, s33, v144
	s_add_i32 s83, 0, 0x1c000
	ds_read_b128 v[148:151], v147
	ds_read_b128 v[160:163], v147 offset:1024
	ds_read_b128 v[164:167], v147 offset:2048
	ds_read_b128 v[168:171], v147 offset:3072
	v_add_u32_e32 v147, s83, v144
	ds_read_b128 v[172:175], v147
	ds_read_b128 v[176:179], v147 offset:1024
	ds_read_b128 v[180:183], v147 offset:2048
	ds_read_b128 v[184:187], v147 offset:3072
	s_add_u32 s16, s48, 0x80000
	s_addc_u32 s17, s49, 0
	s_mov_b32 m0, s5
	v_lshl_add_u64 v[236:237], s[16:17], 0, v[136:137]
	ds_read_b128 v[188:191], v146 offset:32768
	ds_read_b128 v[192:195], v146 offset:33792
	ds_read_b128 v[210:213], v146 offset:34816
	ds_read_b128 v[214:217], v146 offset:35840
	ds_read_b128 v[218:221], v146 offset:36864
	ds_read_b128 v[222:225], v146 offset:37888
	ds_read_b128 v[226:229], v146 offset:38912
	ds_read_b128 v[230:233], v146 offset:39936
	global_load_lds_dwordx4 v[236:237], off
	v_lshl_add_u64 v[236:237], s[16:17], 0, v[132:133]
	s_mov_b32 m0, s6
	s_nop 0
	global_load_lds_dwordx4 v[236:237], off
	s_waitcnt vmcnt(8)
	s_waitcnt lgkmcnt(0)
	s_barrier
	s_waitcnt lgkmcnt(0)
	v_mfma_f32_16x16x32_bf16 v[126:129], v[148:151], v[188:191], v[126:129]
	v_mfma_f32_16x16x32_bf16 v[118:121], v[164:167], v[188:191], v[118:121]
	v_mfma_f32_16x16x32_bf16 v[110:113], v[148:151], v[210:213], v[110:113]
	v_mfma_f32_16x16x32_bf16 v[102:105], v[164:167], v[210:213], v[102:105]
	v_mfma_f32_16x16x32_bf16 v[94:97], v[148:151], v[218:221], v[94:97]
	v_mfma_f32_16x16x32_bf16 v[86:89], v[164:167], v[218:221], v[86:89]
	v_mfma_f32_16x16x32_bf16 v[78:81], v[148:151], v[226:229], v[78:81]
	v_mfma_f32_16x16x32_bf16 v[70:73], v[164:167], v[226:229], v[70:73]
	v_mfma_f32_16x16x32_bf16 v[126:129], v[160:163], v[192:195], v[126:129]
	v_mfma_f32_16x16x32_bf16 v[118:121], v[168:171], v[192:195], v[118:121]
	v_mfma_f32_16x16x32_bf16 v[110:113], v[160:163], v[214:217], v[110:113]
	v_mfma_f32_16x16x32_bf16 v[102:105], v[168:171], v[214:217], v[102:105]
	v_mfma_f32_16x16x32_bf16 v[94:97], v[160:163], v[222:225], v[94:97]
	v_mfma_f32_16x16x32_bf16 v[86:89], v[168:171], v[222:225], v[86:89]
	v_mfma_f32_16x16x32_bf16 v[78:81], v[160:163], v[230:233], v[78:81]
	v_mfma_f32_16x16x32_bf16 v[70:73], v[168:171], v[230:233], v[70:73]
	v_mfma_f32_16x16x32_bf16 v[122:125], v[172:175], v[188:191], v[122:125]
	v_mfma_f32_16x16x32_bf16 v[114:117], v[180:183], v[188:191], v[114:117]
	v_mfma_f32_16x16x32_bf16 v[106:109], v[172:175], v[210:213], v[106:109]
	v_mfma_f32_16x16x32_bf16 v[98:101], v[180:183], v[210:213], v[98:101]
	v_mfma_f32_16x16x32_bf16 v[90:93], v[172:175], v[218:221], v[90:93]
	v_mfma_f32_16x16x32_bf16 v[82:85], v[180:183], v[218:221], v[82:85]
	v_mfma_f32_16x16x32_bf16 v[74:77], v[172:175], v[226:229], v[74:77]
	v_mfma_f32_16x16x32_bf16 v[66:69], v[180:183], v[226:229], v[66:69]
	v_mfma_f32_16x16x32_bf16 v[122:125], v[176:179], v[192:195], v[122:125]
	v_mfma_f32_16x16x32_bf16 v[114:117], v[184:187], v[192:195], v[114:117]
	v_mfma_f32_16x16x32_bf16 v[106:109], v[176:179], v[214:217], v[106:109]
	v_mfma_f32_16x16x32_bf16 v[98:101], v[184:187], v[214:217], v[98:101]
	v_mfma_f32_16x16x32_bf16 v[90:93], v[176:179], v[222:225], v[90:93]
	v_mfma_f32_16x16x32_bf16 v[82:85], v[184:187], v[222:225], v[82:85]
	v_mfma_f32_16x16x32_bf16 v[74:77], v[176:179], v[230:233], v[74:77]
	v_mfma_f32_16x16x32_bf16 v[66:69], v[184:187], v[230:233], v[66:69]
	s_barrier
; #define PG8_STAGE(bufoff, gbase, voff) do { _Pragma("unroll") for (int _i = 0; _i < 2; ++_i) \
;         __builtin_amdgcn_global_load_lds((const unsigned*)((const char*)(gbase) + (voff)[_i]), (LAS unsigned*)(lds + (bufoff) + ldsw + _i * 8192), 16, 0, 0); } while (0)
; #define PG8_LDA(dst, b, h) do { _Pragma("unroll") for (int m = 0; m < 4; ++m) _Pragma("unroll") for (int k = 0; k < 2; ++k) dst[m][k] = *(const LAS bf16x8*)(lds + PG8_SA(b, h) + aoff + m * 2048 + k * 1024); } while (0)
; #define PG8_MMA(ai, bj, At, Bt) do { __builtin_amdgcn_s_setprio(1); _Pragma("unroll") for (int m = 0; m < 4; ++m) _Pragma("unroll") for (int n = 0; n < 2; ++n) _Pragma("unroll") for (int k = 0; k < 2; ++k) \
;         acc[ai][bj][m][n] = __builtin_amdgcn_mfma_f32_16x16x32_bf16(Bt[n][k], At[m][k], acc[ai][bj][m][n], 0, 0, 0); __builtin_amdgcn_s_setprio(0); } while (0)
; #define PG8_WAIT_V(n) asm volatile("s_waitcnt vmcnt(" #n ")" ::: "memory")
; #define PG8_WAIT_L(n) asm volatile("s_waitcnt lgkmcnt(" #n ")" ::: "memory")
; #define PG8_BAR __builtin_amdgcn_s_barrier()
; #define PG8_SCHED __builtin_amdgcn_sched_barrier(0)
; template <class Epi, class Sched = StaticOrder, bool ALIGN_EPI = true>
; __device__ __forceinline__ void gemm_phase(LAS unsigned char* lds, const Gemm g, const Sched& S, const Epi& E) {
;     ...
;             PG8_LDA(At, 1, 1); PG8_STAGE(PG8_SB(1, 0), b3, voffB); PG8_STAGE(PG8_SB(1, 1), b3 + hstep, voffB); PG8_STAGE(PG8_SA(1, 0), a3, voffA);
;             PG8_WAIT_V(8); PG8_WAIT_L(0); PG8_BAR; PG8_MMA(1, 0, At, B0); PG8_MMA(1, 1, At, B1); PG8_BAR; PG8_SCHED;
	s_add_i32 s16, s33, s92
	v_lshl_add_u64 v[142:143], v[142:143], 0, s[34:35]
	s_mov_b32 m0, s16
	ds_read_b128 v[188:191], v146 offset:49152
	ds_read_b128 v[192:195], v146 offset:50176
	ds_read_b128 v[210:213], v146 offset:51200
	ds_read_b128 v[214:217], v146 offset:52224
	ds_read_b128 v[218:221], v146 offset:53248
	ds_read_b128 v[222:225], v146 offset:54272
	ds_read_b128 v[226:229], v146 offset:55296
	ds_read_b128 v[230:233], v146 offset:56320
	global_load_lds_dwordx4 v[142:143], off
	s_add_i32 m0, s16, 0x2000
	s_add_u32 s16, s46, 0x80080
	v_lshl_add_u64 v[142:143], v[152:153], 0, s[34:35]
	s_addc_u32 s17, s47, 0
	s_add_i32 s33, s83, s92
	global_load_lds_dwordx4 v[142:143], off
	v_lshl_add_u64 v[142:143], s[16:17], 0, v[134:135]
	s_mov_b32 m0, s33
	s_nop 0
	global_load_lds_dwordx4 v[142:143], off
	v_lshl_add_u64 v[142:143], s[16:17], 0, v[130:131]
	s_add_i32 m0, s33, 0x2000
	s_nop 0
	global_load_lds_dwordx4 v[142:143], off
	v_lshl_add_u64 v[142:143], v[196:197], 0, s[34:35]
	s_mov_b32 m0, s7
	s_nop 0
	global_load_lds_dwordx4 v[142:143], off
	v_lshl_add_u64 v[142:143], v[234:235], 0, s[34:35]
	s_mov_b32 m0, s8
	s_nop 0
	global_load_lds_dwordx4 v[142:143], off
	s_waitcnt vmcnt(8)
	s_waitcnt lgkmcnt(0)
	s_barrier
	s_waitcnt lgkmcnt(0)
	v_mfma_f32_16x16x32_bf16 v[62:65], v[148:151], v[188:191], v[62:65]
	v_mfma_f32_16x16x32_bf16 v[54:57], v[164:167], v[188:191], v[54:57]
	v_mfma_f32_16x16x32_bf16 v[46:49], v[148:151], v[210:213], v[46:49]
	v_mfma_f32_16x16x32_bf16 v[38:41], v[164:167], v[210:213], v[38:41]
	v_mfma_f32_16x16x32_bf16 v[30:33], v[148:151], v[218:221], v[30:33]
	v_mfma_f32_16x16x32_bf16 v[22:25], v[164:167], v[218:221], v[22:25]
	v_mfma_f32_16x16x32_bf16 v[14:17], v[148:151], v[226:229], v[14:17]
	v_mfma_f32_16x16x32_bf16 v[6:9], v[164:167], v[226:229], v[6:9]
	v_mfma_f32_16x16x32_bf16 v[62:65], v[160:163], v[192:195], v[62:65]
	v_mfma_f32_16x16x32_bf16 v[54:57], v[168:171], v[192:195], v[54:57]
	v_mfma_f32_16x16x32_bf16 v[46:49], v[160:163], v[214:217], v[46:49]
	v_mfma_f32_16x16x32_bf16 v[38:41], v[168:171], v[214:217], v[38:41]
	v_mfma_f32_16x16x32_bf16 v[30:33], v[160:163], v[222:225], v[30:33]
	v_mfma_f32_16x16x32_bf16 v[22:25], v[168:171], v[222:225], v[22:25]
	v_mfma_f32_16x16x32_bf16 v[14:17], v[160:163], v[230:233], v[14:17]
	v_mfma_f32_16x16x32_bf16 v[6:9], v[168:171], v[230:233], v[6:9]
	v_mfma_f32_16x16x32_bf16 v[58:61], v[172:175], v[188:191], v[58:61]
	v_mfma_f32_16x16x32_bf16 v[50:53], v[180:183], v[188:191], v[50:53]
	v_mfma_f32_16x16x32_bf16 v[42:45], v[172:175], v[210:213], v[42:45]
	v_mfma_f32_16x16x32_bf16 v[34:37], v[180:183], v[210:213], v[34:37]
	v_mfma_f32_16x16x32_bf16 v[26:29], v[172:175], v[218:221], v[26:29]
	v_mfma_f32_16x16x32_bf16 v[18:21], v[180:183], v[218:221], v[18:21]
	v_mfma_f32_16x16x32_bf16 v[10:13], v[172:175], v[226:229], v[10:13]
	v_mfma_f32_16x16x32_bf16 v[2:5], v[180:183], v[226:229], v[2:5]
	v_mfma_f32_16x16x32_bf16 v[58:61], v[176:179], v[192:195], v[58:61]
	v_mfma_f32_16x16x32_bf16 v[50:53], v[184:187], v[192:195], v[50:53]
	v_mfma_f32_16x16x32_bf16 v[42:45], v[176:179], v[214:217], v[42:45]
	v_mfma_f32_16x16x32_bf16 v[34:37], v[184:187], v[214:217], v[34:37]
	v_mfma_f32_16x16x32_bf16 v[26:29], v[176:179], v[222:225], v[26:29]
	v_mfma_f32_16x16x32_bf16 v[18:21], v[184:187], v[222:225], v[18:21]
	v_mfma_f32_16x16x32_bf16 v[10:13], v[176:179], v[230:233], v[10:13]
	v_mfma_f32_16x16x32_bf16 v[2:5], v[184:187], v[230:233], v[2:5]
	s_barrier
	s_add_i32 s82, s82, 2
	s_add_u32 s44, s44, 0x100
	s_addc_u32 s45, s45, 0
	s_add_u32 vcc_lo, vcc_lo, 0x100
	s_addc_u32 vcc_hi, vcc_hi, 0
	s_cmp_gt_u32 s82, 29
	s_cbranch_scc0 .LBB0_467

; #define PG8_WAIT_V(n) asm volatile("s_waitcnt vmcnt(" #n ")" ::: "memory")
; #define PG8_BAR __builtin_amdgcn_s_barrier()
; template <class Epi, class Sched = StaticOrder, bool ALIGN_EPI = true>
; __device__ __forceinline__ void gemm_phase(LAS unsigned char* lds, const Gemm g, const Sched& S, const Epi& E) {
;     ...
;     PG8_WAIT_V(0);
;     if constexpr (!ALIGN_EPI) { if (wr == 0) PG8_BAR; }
;     PG8_BAR;
.LBB0_473:
	s_setprio 0
	s_waitcnt vmcnt(0)
	v_readlane_b32 s92, v254, 63
	v_readlane_b32 s16, v254, 43
	v_readlane_b32 s22, v254, 39
	v_readlane_b32 s93, v251, 0
	v_readlane_b32 s33, v254, 40
	v_readlane_b32 s17, v254, 44
	v_readlane_b32 s23, v254, 45
	v_readlane_b32 s77, v254, 46
	s_movk_i32 s79, 0x4000
	s_mov_b32 s70, 0x3a000000
	s_barrier
